# v40 pipeline with dependency-checked accumulator-chain reorder also in the first-iteration loops (140 groups)
# speedup vs baseline: 1.0047x; 1.0012x over previous
.LBB0_379:
	v_add_u32_e32 v14, s56, v140
	v_add_u32_e32 v30, s57, v140
	ds_read_b128 v[2:5], v14
	ds_read_b128 v[6:9], v14 offset:1024
	ds_read_b128 v[10:13], v14 offset:2048
	ds_read_b128 v[14:17], v14 offset:3072
	ds_read_b128 v[18:21], v30
	ds_read_b128 v[22:25], v30 offset:1024
	ds_read_b128 v[26:29], v30 offset:2048
	ds_read_b128 v[30:33], v30 offset:3072
	v_add_u32_e32 v141, 0, v1
	ds_read_b128 v[34:37], v141
	ds_read_b128 v[38:41], v141 offset:1024
	ds_read_b128 v[42:45], v141 offset:2048
	ds_read_b128 v[46:49], v141 offset:3072
	ds_read_b128 v[50:53], v141 offset:4096
	ds_read_b128 v[54:57], v141 offset:5120
	ds_read_b128 v[58:61], v141 offset:6144
	ds_read_b128 v[62:65], v141 offset:7168
	s_waitcnt vmcnt(8)
	s_waitcnt lgkmcnt(0)
	s_barrier
	s_setprio 1
	s_waitcnt lgkmcnt(0)
	v_mfma_f32_16x16x32_bf16 v[66:69], v[2:5], v[34:37], 0
	v_mfma_f32_16x16x32_bf16 v[66:69], v[6:9], v[38:41], v[66:69]
	v_mfma_f32_16x16x32_bf16 v[70:73], v[10:13], v[34:37], 0
	v_mfma_f32_16x16x32_bf16 v[70:73], v[14:17], v[38:41], v[70:73]
	v_mfma_f32_16x16x32_bf16 v[78:81], v[10:13], v[42:45], 0
	v_mfma_f32_16x16x32_bf16 v[78:81], v[14:17], v[46:49], v[78:81]
	v_mfma_f32_16x16x32_bf16 v[74:77], v[2:5], v[42:45], 0
	v_mfma_f32_16x16x32_bf16 v[74:77], v[6:9], v[46:49], v[74:77]
	v_mfma_f32_16x16x32_bf16 v[82:85], v[2:5], v[50:53], 0
	v_mfma_f32_16x16x32_bf16 v[82:85], v[6:9], v[54:57], v[82:85]
	v_mfma_f32_16x16x32_bf16 v[86:89], v[10:13], v[50:53], 0
	v_mfma_f32_16x16x32_bf16 v[86:89], v[14:17], v[54:57], v[86:89]
	v_mfma_f32_16x16x32_bf16 v[94:97], v[10:13], v[58:61], 0
	v_mfma_f32_16x16x32_bf16 v[94:97], v[14:17], v[62:65], v[94:97]
	v_mfma_f32_16x16x32_bf16 v[90:93], v[2:5], v[58:61], 0
	v_mfma_f32_16x16x32_bf16 v[90:93], v[6:9], v[62:65], v[90:93]
	s_setprio 0
	s_setprio 1
	v_mfma_f32_16x16x32_bf16 v[98:101], v[18:21], v[34:37], 0
	v_mfma_f32_16x16x32_bf16 v[98:101], v[22:25], v[38:41], v[98:101]
	v_mfma_f32_16x16x32_bf16 v[34:37], v[26:29], v[34:37], 0
	v_mfma_f32_16x16x32_bf16 v[38:41], v[30:33], v[38:41], v[34:37]
	v_mfma_f32_16x16x32_bf16 v[102:105], v[18:21], v[42:45], 0
	v_mfma_f32_16x16x32_bf16 v[102:105], v[22:25], v[46:49], v[102:105]
	v_mfma_f32_16x16x32_bf16 v[42:45], v[26:29], v[42:45], 0
	v_mfma_f32_16x16x32_bf16 v[46:49], v[30:33], v[46:49], v[42:45]
	v_mfma_f32_16x16x32_bf16 v[106:109], v[18:21], v[50:53], 0
	v_mfma_f32_16x16x32_bf16 v[106:109], v[22:25], v[54:57], v[106:109]
	v_mfma_f32_16x16x32_bf16 v[50:53], v[26:29], v[50:53], 0
	v_mfma_f32_16x16x32_bf16 v[54:57], v[30:33], v[54:57], v[50:53]
	v_mfma_f32_16x16x32_bf16 v[110:113], v[18:21], v[58:61], 0
	v_mfma_f32_16x16x32_bf16 v[110:113], v[22:25], v[62:65], v[110:113]
	s_setprio 2
	s_barrier
	v_mfma_f32_16x16x32_bf16 v[58:61], v[26:29], v[58:61], 0
	v_mfma_f32_16x16x32_bf16 v[62:65], v[30:33], v[62:65], v[58:61]
	s_setprio 0
	v_lshl_add_u64 v[136:137], s[38:39], 0, v[130:131]
	s_add_i32 s60, s56, s21
	v_mov_b32_e32 v135, v131
	v_lshl_add_u64 v[142:143], v[136:137], 0, s[10:11]
	s_mov_b32 m0, s60
	v_lshl_add_u64 v[244:245], s[38:39], 0, v[134:135]
	ds_read_b128 v[34:37], v141 offset:16384
	ds_read_b128 v[42:45], v141 offset:17408
	ds_read_b128 v[50:53], v141 offset:18432
	ds_read_b128 v[58:61], v141 offset:19456
	ds_read_b128 v[114:117], v141 offset:20480
	ds_read_b128 v[118:121], v141 offset:21504
	ds_read_b128 v[122:125], v141 offset:22528
	ds_read_b128 v[126:129], v141 offset:23552
	global_load_lds_dwordx4 v[142:143], off
	v_lshl_add_u64 v[142:143], v[244:245], 0, s[10:11]
	s_add_i32 m0, s60, 0x2000
	s_add_i32 s60, s57, s21
	global_load_lds_dwordx4 v[142:143], off
	s_mov_b32 m0, s60
	v_mov_b32_e32 v139, v131
	global_load_lds_dwordx4 v130, s[40:41]
	s_add_i32 m0, s60, 0x2000
	v_lshl_add_u64 v[246:247], s[36:37], 0, v[138:139]
	v_mov_b32_e32 v133, v131
	global_load_lds_dwordx4 v134, s[40:41]
	v_lshl_add_u64 v[142:143], v[246:247], 0, s[10:11]
	s_mov_b32 m0, s33
	v_lshl_add_u64 v[248:249], s[36:37], 0, v[132:133]
	global_load_lds_dwordx4 v[142:143], off
	v_lshl_add_u64 v[142:143], v[248:249], 0, s[10:11]
	s_mov_b32 m0, s46
	s_nop 0
	global_load_lds_dwordx4 v[142:143], off
	s_waitcnt vmcnt(8)
	s_waitcnt lgkmcnt(0)
	s_barrier
	s_setprio 1
	s_waitcnt lgkmcnt(0)
	v_mfma_f32_16x16x32_bf16 v[142:145], v[2:5], v[34:37], 0
	v_mfma_f32_16x16x32_bf16 v[142:145], v[6:9], v[42:45], v[142:145]
	v_mfma_f32_16x16x32_bf16 v[148:151], v[10:13], v[34:37], 0
	v_mfma_f32_16x16x32_bf16 v[148:151], v[14:17], v[42:45], v[148:151]
	v_mfma_f32_16x16x32_bf16 v[156:159], v[10:13], v[50:53], 0
	v_mfma_f32_16x16x32_bf16 v[156:159], v[14:17], v[58:61], v[156:159]
	v_mfma_f32_16x16x32_bf16 v[152:155], v[2:5], v[50:53], 0
	v_mfma_f32_16x16x32_bf16 v[152:155], v[6:9], v[58:61], v[152:155]
	v_mfma_f32_16x16x32_bf16 v[160:163], v[2:5], v[114:117], 0
	v_mfma_f32_16x16x32_bf16 v[160:163], v[6:9], v[118:121], v[160:163]
	v_mfma_f32_16x16x32_bf16 v[164:167], v[10:13], v[114:117], 0
	v_mfma_f32_16x16x32_bf16 v[164:167], v[14:17], v[118:121], v[164:167]
	v_mfma_f32_16x16x32_bf16 v[10:13], v[10:13], v[122:125], 0
	v_mfma_f32_16x16x32_bf16 v[172:175], v[14:17], v[126:129], v[10:13]
	v_mfma_f32_16x16x32_bf16 v[2:5], v[2:5], v[122:125], 0
	v_mfma_f32_16x16x32_bf16 v[168:171], v[6:9], v[126:129], v[2:5]
	s_setprio 0
	s_setprio 1
	v_mfma_f32_16x16x32_bf16 v[2:5], v[18:21], v[34:37], 0
	v_mfma_f32_16x16x32_bf16 v[6:9], v[26:29], v[34:37], 0
	v_mfma_f32_16x16x32_bf16 v[10:13], v[18:21], v[50:53], 0
	v_mfma_f32_16x16x32_bf16 v[14:17], v[26:29], v[50:53], 0
	v_mfma_f32_16x16x32_bf16 v[34:37], v[18:21], v[114:117], 0
	v_mfma_f32_16x16x32_bf16 v[50:53], v[26:29], v[114:117], 0
	v_mfma_f32_16x16x32_bf16 v[18:21], v[18:21], v[122:125], 0
	v_mfma_f32_16x16x32_bf16 v[26:29], v[26:29], v[122:125], 0
	v_mfma_f32_16x16x32_bf16 v[114:117], v[22:25], v[42:45], v[2:5]
	v_mfma_f32_16x16x32_bf16 v[188:191], v[22:25], v[118:121], v[34:37]
	v_mfma_f32_16x16x32_bf16 v[118:121], v[30:33], v[118:121], v[50:53]
	v_mfma_f32_16x16x32_bf16 v[176:179], v[30:33], v[42:45], v[6:9]
	v_mfma_f32_16x16x32_bf16 v[180:183], v[22:25], v[58:61], v[10:13]
	v_mfma_f32_16x16x32_bf16 v[184:187], v[30:33], v[58:61], v[14:17]
	s_setprio 2
	s_barrier
	v_mfma_f32_16x16x32_bf16 v[192:195], v[22:25], v[126:129], v[18:21]
	v_mfma_f32_16x16x32_bf16 v[196:199], v[30:33], v[126:129], v[26:29]
	s_setprio 0
	s_add_i32 s60, 0, 0x18000
	v_add_u32_e32 v2, s60, v140
	s_add_i32 s61, 0, 0x1c000
	ds_read_b128 v[200:203], v2
	ds_read_b128 v[204:207], v2 offset:1024
	ds_read_b128 v[208:211], v2 offset:2048
	ds_read_b128 v[212:215], v2 offset:3072
	v_add_u32_e32 v2, s61, v140
	ds_read_b128 v[216:219], v2
	ds_read_b128 v[220:223], v2 offset:1024
	ds_read_b128 v[224:227], v2 offset:2048
	ds_read_b128 v[228:231], v2 offset:3072
	s_mov_b32 m0, s47
	ds_read_b128 v[42:45], v141 offset:32768
	ds_read_b128 v[50:53], v141 offset:33792
	ds_read_b128 v[58:61], v141 offset:34816
	ds_read_b128 v[122:125], v141 offset:35840
	ds_read_b128 v[126:129], v141 offset:36864
	ds_read_b128 v[232:235], v141 offset:37888
	ds_read_b128 v[236:239], v141 offset:38912
	ds_read_b128 v[240:243], v141 offset:39936
	global_load_lds_dwordx4 v138, s[42:43]
	s_mov_b32 m0, s48
	s_nop 0
	global_load_lds_dwordx4 v132, s[42:43]
	s_waitcnt vmcnt(8)
	s_waitcnt lgkmcnt(0)
	s_barrier
	s_setprio 1
	s_waitcnt lgkmcnt(0)
	v_mfma_f32_16x16x32_bf16 v[2:5], v[200:203], v[42:45], v[66:69]
	v_mfma_f32_16x16x32_bf16 v[2:5], v[204:207], v[50:53], v[2:5]
	v_mfma_f32_16x16x32_bf16 v[6:9], v[208:211], v[42:45], v[70:73]
	v_mfma_f32_16x16x32_bf16 v[6:9], v[212:215], v[50:53], v[6:9]
	v_mfma_f32_16x16x32_bf16 v[14:17], v[208:211], v[58:61], v[78:81]
	v_mfma_f32_16x16x32_bf16 v[14:17], v[212:215], v[122:125], v[14:17]
	v_mfma_f32_16x16x32_bf16 v[10:13], v[200:203], v[58:61], v[74:77]
	v_mfma_f32_16x16x32_bf16 v[10:13], v[204:207], v[122:125], v[10:13]
	v_mfma_f32_16x16x32_bf16 v[18:21], v[200:203], v[126:129], v[82:85]
	v_mfma_f32_16x16x32_bf16 v[18:21], v[204:207], v[232:235], v[18:21]
	v_mfma_f32_16x16x32_bf16 v[22:25], v[208:211], v[126:129], v[86:89]
	v_mfma_f32_16x16x32_bf16 v[22:25], v[212:215], v[232:235], v[22:25]
	v_mfma_f32_16x16x32_bf16 v[30:33], v[208:211], v[236:239], v[94:97]
	v_mfma_f32_16x16x32_bf16 v[30:33], v[212:215], v[240:243], v[30:33]
	v_mfma_f32_16x16x32_bf16 v[26:29], v[200:203], v[236:239], v[90:93]
	v_mfma_f32_16x16x32_bf16 v[26:29], v[204:207], v[240:243], v[26:29]
	s_setprio 0
	s_setprio 1
	v_mfma_f32_16x16x32_bf16 v[34:37], v[216:219], v[42:45], v[98:101]
	v_mfma_f32_16x16x32_bf16 v[38:41], v[224:227], v[42:45], v[38:41]
	v_mfma_f32_16x16x32_bf16 v[34:37], v[220:223], v[50:53], v[34:37]
	v_mfma_f32_16x16x32_bf16 v[38:41], v[228:231], v[50:53], v[38:41]
	v_mfma_f32_16x16x32_bf16 v[42:45], v[216:219], v[58:61], v[102:105]
	v_mfma_f32_16x16x32_bf16 v[46:49], v[224:227], v[58:61], v[46:49]
	v_mfma_f32_16x16x32_bf16 v[50:53], v[216:219], v[126:129], v[106:109]
	v_mfma_f32_16x16x32_bf16 v[54:57], v[224:227], v[126:129], v[54:57]
	v_mfma_f32_16x16x32_bf16 v[58:61], v[216:219], v[236:239], v[110:113]
	v_mfma_f32_16x16x32_bf16 v[62:65], v[224:227], v[236:239], v[62:65]
	v_mfma_f32_16x16x32_bf16 v[42:45], v[220:223], v[122:125], v[42:45]
	v_mfma_f32_16x16x32_bf16 v[46:49], v[228:231], v[122:125], v[46:49]
	v_mfma_f32_16x16x32_bf16 v[50:53], v[220:223], v[232:235], v[50:53]
	v_mfma_f32_16x16x32_bf16 v[54:57], v[228:231], v[232:235], v[54:57]
	s_setprio 2
	s_barrier
	v_mfma_f32_16x16x32_bf16 v[58:61], v[220:223], v[240:243], v[58:61]
	v_mfma_f32_16x16x32_bf16 v[62:65], v[228:231], v[240:243], v[62:65]
	s_setprio 0
	s_add_i32 s60, s60, s21
	v_lshl_add_u64 v[66:67], v[136:137], 0, s[12:13]
	s_mov_b32 m0, s60
	ds_read_b128 v[94:97], v141 offset:49152
	ds_read_b128 v[98:101], v141 offset:50176
	ds_read_b128 v[102:105], v141 offset:51200
	ds_read_b128 v[106:109], v141 offset:52224
	ds_read_b128 v[110:113], v141 offset:53248
	ds_read_b128 v[232:235], v141 offset:54272
	ds_read_b128 v[236:239], v141 offset:55296
	ds_read_b128 v[240:243], v141 offset:56320
	global_load_lds_dwordx4 v[66:67], off
	v_lshl_add_u64 v[66:67], v[244:245], 0, s[12:13]
	s_add_i32 m0, s60, 0x2000
	s_add_i32 s60, s61, s21
	global_load_lds_dwordx4 v[66:67], off
	s_mov_b32 m0, s60
	v_lshl_add_u64 v[66:67], v[246:247], 0, s[12:13]
	global_load_lds_dwordx4 v130, s[44:45]
	s_add_i32 m0, s60, 0x2000
	s_nop 0
	global_load_lds_dwordx4 v134, s[44:45]
	s_mov_b32 m0, s52
	s_nop 0
	global_load_lds_dwordx4 v[66:67], off
	v_lshl_add_u64 v[66:67], v[248:249], 0, s[12:13]
	s_mov_b32 m0, s53
	s_nop 0
	global_load_lds_dwordx4 v[66:67], off
	s_waitcnt vmcnt(8)
	s_waitcnt lgkmcnt(0)
	s_barrier
	s_setprio 1
	s_waitcnt lgkmcnt(0)
	v_mfma_f32_16x16x32_bf16 v[66:69], v[200:203], v[94:97], v[142:145]
	v_mfma_f32_16x16x32_bf16 v[122:125], v[204:207], v[98:101], v[66:69]
	v_mfma_f32_16x16x32_bf16 v[66:69], v[208:211], v[94:97], v[148:151]
	v_mfma_f32_16x16x32_bf16 v[126:129], v[212:215], v[98:101], v[66:69]
	v_mfma_f32_16x16x32_bf16 v[66:69], v[200:203], v[102:105], v[152:155]
	v_mfma_f32_16x16x32_bf16 v[70:73], v[208:211], v[102:105], v[156:159]
	v_mfma_f32_16x16x32_bf16 v[74:77], v[200:203], v[110:113], v[160:163]
	v_mfma_f32_16x16x32_bf16 v[78:81], v[208:211], v[110:113], v[164:167]
	v_mfma_f32_16x16x32_bf16 v[82:85], v[200:203], v[236:239], v[168:171]
	v_mfma_f32_16x16x32_bf16 v[86:89], v[208:211], v[236:239], v[172:175]
	v_mfma_f32_16x16x32_bf16 v[66:69], v[204:207], v[106:109], v[66:69]
	v_mfma_f32_16x16x32_bf16 v[70:73], v[212:215], v[106:109], v[70:73]
	v_mfma_f32_16x16x32_bf16 v[74:77], v[204:207], v[232:235], v[74:77]
	v_mfma_f32_16x16x32_bf16 v[78:81], v[212:215], v[232:235], v[78:81]
	v_mfma_f32_16x16x32_bf16 v[82:85], v[204:207], v[240:243], v[82:85]
	v_mfma_f32_16x16x32_bf16 v[86:89], v[212:215], v[240:243], v[86:89]
	s_setprio 0
	s_setprio 1
	v_mfma_f32_16x16x32_bf16 v[90:93], v[216:219], v[94:97], v[114:117]
	v_mfma_f32_16x16x32_bf16 v[94:97], v[224:227], v[94:97], v[176:179]
	v_mfma_f32_16x16x32_bf16 v[90:93], v[220:223], v[98:101], v[90:93]
	v_mfma_f32_16x16x32_bf16 v[94:97], v[228:231], v[98:101], v[94:97]
	v_mfma_f32_16x16x32_bf16 v[98:101], v[216:219], v[102:105], v[180:183]
	v_mfma_f32_16x16x32_bf16 v[102:105], v[224:227], v[102:105], v[184:187]
	v_mfma_f32_16x16x32_bf16 v[98:101], v[220:223], v[106:109], v[98:101]
	v_mfma_f32_16x16x32_bf16 v[102:105], v[228:231], v[106:109], v[102:105]
	v_mfma_f32_16x16x32_bf16 v[106:109], v[216:219], v[110:113], v[188:191]
	v_mfma_f32_16x16x32_bf16 v[110:113], v[224:227], v[110:113], v[118:121]
	v_mfma_f32_16x16x32_bf16 v[114:117], v[216:219], v[236:239], v[192:195]
	v_mfma_f32_16x16x32_bf16 v[118:121], v[224:227], v[236:239], v[196:199]
	v_mfma_f32_16x16x32_bf16 v[106:109], v[220:223], v[232:235], v[106:109]
	v_mfma_f32_16x16x32_bf16 v[110:113], v[228:231], v[232:235], v[110:113]
	s_setprio 2
	s_barrier
	v_mfma_f32_16x16x32_bf16 v[114:117], v[220:223], v[240:243], v[114:117]
	v_mfma_f32_16x16x32_bf16 v[118:121], v[228:231], v[240:243], v[118:121]
	s_setprio 0
	s_add_i32 s59, s59, 2
	s_cmp_ge_i32 s59, s15
	s_cbranch_scc0 .LBB0_379
	v_mov_b32_e32 v136, v130
	s_branch .LBB0_382

.LBB0_462:
	v_add_u32_e32 v14, s54, v140
	v_add_u32_e32 v30, s55, v140
	ds_read_b128 v[2:5], v14
	ds_read_b128 v[6:9], v14 offset:1024
	ds_read_b128 v[10:13], v14 offset:2048
	ds_read_b128 v[14:17], v14 offset:3072
	ds_read_b128 v[18:21], v30
	ds_read_b128 v[22:25], v30 offset:1024
	ds_read_b128 v[26:29], v30 offset:2048
	ds_read_b128 v[30:33], v30 offset:3072
	v_add_u32_e32 v141, 0, v1
	ds_read_b128 v[34:37], v141
	ds_read_b128 v[38:41], v141 offset:1024
	ds_read_b128 v[42:45], v141 offset:2048
	ds_read_b128 v[46:49], v141 offset:3072
	ds_read_b128 v[50:53], v141 offset:4096
	ds_read_b128 v[54:57], v141 offset:5120
	ds_read_b128 v[58:61], v141 offset:6144
	ds_read_b128 v[62:65], v141 offset:7168
	s_waitcnt vmcnt(8)
	s_waitcnt lgkmcnt(0)
	s_barrier
	s_setprio 1
	s_waitcnt lgkmcnt(0)
	v_mfma_f32_16x16x32_bf16 v[66:69], v[2:5], v[34:37], 0
	v_mfma_f32_16x16x32_bf16 v[66:69], v[6:9], v[38:41], v[66:69]
	v_mfma_f32_16x16x32_bf16 v[70:73], v[10:13], v[34:37], 0
	v_mfma_f32_16x16x32_bf16 v[70:73], v[14:17], v[38:41], v[70:73]
	v_mfma_f32_16x16x32_bf16 v[78:81], v[10:13], v[42:45], 0
	v_mfma_f32_16x16x32_bf16 v[78:81], v[14:17], v[46:49], v[78:81]
	v_mfma_f32_16x16x32_bf16 v[74:77], v[2:5], v[42:45], 0
	v_mfma_f32_16x16x32_bf16 v[74:77], v[6:9], v[46:49], v[74:77]
	v_mfma_f32_16x16x32_bf16 v[82:85], v[2:5], v[50:53], 0
	v_mfma_f32_16x16x32_bf16 v[82:85], v[6:9], v[54:57], v[82:85]
	v_mfma_f32_16x16x32_bf16 v[86:89], v[10:13], v[50:53], 0
	v_mfma_f32_16x16x32_bf16 v[86:89], v[14:17], v[54:57], v[86:89]
	v_mfma_f32_16x16x32_bf16 v[94:97], v[10:13], v[58:61], 0
	v_mfma_f32_16x16x32_bf16 v[94:97], v[14:17], v[62:65], v[94:97]
	v_mfma_f32_16x16x32_bf16 v[90:93], v[2:5], v[58:61], 0
	v_mfma_f32_16x16x32_bf16 v[90:93], v[6:9], v[62:65], v[90:93]
	s_setprio 0
	s_setprio 1
	v_mfma_f32_16x16x32_bf16 v[98:101], v[18:21], v[34:37], 0
	v_mfma_f32_16x16x32_bf16 v[98:101], v[22:25], v[38:41], v[98:101]
	v_mfma_f32_16x16x32_bf16 v[34:37], v[26:29], v[34:37], 0
	v_mfma_f32_16x16x32_bf16 v[38:41], v[30:33], v[38:41], v[34:37]
	v_mfma_f32_16x16x32_bf16 v[102:105], v[18:21], v[42:45], 0
	v_mfma_f32_16x16x32_bf16 v[102:105], v[22:25], v[46:49], v[102:105]
	v_mfma_f32_16x16x32_bf16 v[42:45], v[26:29], v[42:45], 0
	v_mfma_f32_16x16x32_bf16 v[46:49], v[30:33], v[46:49], v[42:45]
	v_mfma_f32_16x16x32_bf16 v[106:109], v[18:21], v[50:53], 0
	v_mfma_f32_16x16x32_bf16 v[106:109], v[22:25], v[54:57], v[106:109]
	v_mfma_f32_16x16x32_bf16 v[50:53], v[26:29], v[50:53], 0
	v_mfma_f32_16x16x32_bf16 v[54:57], v[30:33], v[54:57], v[50:53]
	v_mfma_f32_16x16x32_bf16 v[110:113], v[18:21], v[58:61], 0
	v_mfma_f32_16x16x32_bf16 v[110:113], v[22:25], v[62:65], v[110:113]
	s_setprio 2
	s_barrier
	v_mfma_f32_16x16x32_bf16 v[58:61], v[26:29], v[58:61], 0
	v_mfma_f32_16x16x32_bf16 v[62:65], v[30:33], v[62:65], v[58:61]
	s_setprio 0
	v_lshl_add_u64 v[136:137], s[36:37], 0, v[130:131]
	s_add_i32 s62, s54, s21
	v_mov_b32_e32 v135, v131
	v_lshl_add_u64 v[142:143], v[136:137], 0, s[12:13]
	s_mov_b32 m0, s62
	v_lshl_add_u64 v[244:245], s[36:37], 0, v[134:135]
	ds_read_b128 v[34:37], v141 offset:16384
	ds_read_b128 v[42:45], v141 offset:17408
	ds_read_b128 v[50:53], v141 offset:18432
	ds_read_b128 v[58:61], v141 offset:19456
	ds_read_b128 v[114:117], v141 offset:20480
	ds_read_b128 v[118:121], v141 offset:21504
	ds_read_b128 v[122:125], v141 offset:22528
	ds_read_b128 v[126:129], v141 offset:23552
	global_load_lds_dwordx4 v[142:143], off
	v_lshl_add_u64 v[142:143], v[244:245], 0, s[12:13]
	s_add_i32 m0, s62, 0x2000
	s_add_i32 s62, s55, s21
	global_load_lds_dwordx4 v[142:143], off
	s_mov_b32 m0, s62
	v_mov_b32_e32 v139, v131
	global_load_lds_dwordx4 v130, s[38:39]
	s_add_i32 m0, s62, 0x2000
	v_lshl_add_u64 v[246:247], s[34:35], 0, v[138:139]
	v_mov_b32_e32 v133, v131
	global_load_lds_dwordx4 v134, s[38:39]
	v_lshl_add_u64 v[142:143], v[246:247], 0, s[12:13]
	s_mov_b32 m0, s33
	v_lshl_add_u64 v[248:249], s[34:35], 0, v[132:133]
	global_load_lds_dwordx4 v[142:143], off
	v_lshl_add_u64 v[142:143], v[248:249], 0, s[12:13]
	s_mov_b32 m0, s44
	s_nop 0
	global_load_lds_dwordx4 v[142:143], off
	s_waitcnt vmcnt(8)
	s_waitcnt lgkmcnt(0)
	s_barrier
	s_setprio 1
	s_waitcnt lgkmcnt(0)
	v_mfma_f32_16x16x32_bf16 v[142:145], v[2:5], v[34:37], 0
	v_mfma_f32_16x16x32_bf16 v[142:145], v[6:9], v[42:45], v[142:145]
	v_mfma_f32_16x16x32_bf16 v[148:151], v[10:13], v[34:37], 0
	v_mfma_f32_16x16x32_bf16 v[148:151], v[14:17], v[42:45], v[148:151]
	v_mfma_f32_16x16x32_bf16 v[156:159], v[10:13], v[50:53], 0
	v_mfma_f32_16x16x32_bf16 v[156:159], v[14:17], v[58:61], v[156:159]
	v_mfma_f32_16x16x32_bf16 v[152:155], v[2:5], v[50:53], 0
	v_mfma_f32_16x16x32_bf16 v[152:155], v[6:9], v[58:61], v[152:155]
	v_mfma_f32_16x16x32_bf16 v[160:163], v[2:5], v[114:117], 0
	v_mfma_f32_16x16x32_bf16 v[160:163], v[6:9], v[118:121], v[160:163]
	v_mfma_f32_16x16x32_bf16 v[164:167], v[10:13], v[114:117], 0
	v_mfma_f32_16x16x32_bf16 v[164:167], v[14:17], v[118:121], v[164:167]
	v_mfma_f32_16x16x32_bf16 v[10:13], v[10:13], v[122:125], 0
	v_mfma_f32_16x16x32_bf16 v[172:175], v[14:17], v[126:129], v[10:13]
	v_mfma_f32_16x16x32_bf16 v[2:5], v[2:5], v[122:125], 0
	v_mfma_f32_16x16x32_bf16 v[168:171], v[6:9], v[126:129], v[2:5]
	s_setprio 0
	s_setprio 1
	v_mfma_f32_16x16x32_bf16 v[2:5], v[18:21], v[34:37], 0
	v_mfma_f32_16x16x32_bf16 v[6:9], v[26:29], v[34:37], 0
	v_mfma_f32_16x16x32_bf16 v[10:13], v[18:21], v[50:53], 0
	v_mfma_f32_16x16x32_bf16 v[14:17], v[26:29], v[50:53], 0
	v_mfma_f32_16x16x32_bf16 v[34:37], v[18:21], v[114:117], 0
	v_mfma_f32_16x16x32_bf16 v[50:53], v[26:29], v[114:117], 0
	v_mfma_f32_16x16x32_bf16 v[18:21], v[18:21], v[122:125], 0
	v_mfma_f32_16x16x32_bf16 v[26:29], v[26:29], v[122:125], 0
	v_mfma_f32_16x16x32_bf16 v[114:117], v[22:25], v[42:45], v[2:5]
	v_mfma_f32_16x16x32_bf16 v[122:125], v[30:33], v[42:45], v[6:9]
	v_mfma_f32_16x16x32_bf16 v[184:187], v[22:25], v[118:121], v[34:37]
	v_mfma_f32_16x16x32_bf16 v[118:121], v[30:33], v[118:121], v[50:53]
	v_mfma_f32_16x16x32_bf16 v[188:191], v[22:25], v[126:129], v[18:21]
	v_mfma_f32_16x16x32_bf16 v[126:129], v[30:33], v[126:129], v[26:29]
	s_setprio 2
	s_barrier
	v_mfma_f32_16x16x32_bf16 v[176:179], v[22:25], v[58:61], v[10:13]
	v_mfma_f32_16x16x32_bf16 v[180:183], v[30:33], v[58:61], v[14:17]
	s_setprio 0
	s_add_i32 s62, 0, 0x18000
	v_add_u32_e32 v2, s62, v140
	s_add_i32 s63, 0, 0x1c000
	ds_read_b128 v[192:195], v2
	ds_read_b128 v[196:199], v2 offset:1024
	ds_read_b128 v[200:203], v2 offset:2048
	ds_read_b128 v[204:207], v2 offset:3072
	v_add_u32_e32 v2, s63, v140
	ds_read_b128 v[208:211], v2
	ds_read_b128 v[212:215], v2 offset:1024
	ds_read_b128 v[216:219], v2 offset:2048
	ds_read_b128 v[220:223], v2 offset:3072
	s_mov_b32 m0, s45
	ds_read_b128 v[42:45], v141 offset:32768
	ds_read_b128 v[50:53], v141 offset:33792
	ds_read_b128 v[58:61], v141 offset:34816
	ds_read_b128 v[224:227], v141 offset:35840
	ds_read_b128 v[228:231], v141 offset:36864
	ds_read_b128 v[232:235], v141 offset:37888
	ds_read_b128 v[236:239], v141 offset:38912
	ds_read_b128 v[240:243], v141 offset:39936
	global_load_lds_dwordx4 v138, s[40:41]
	s_mov_b32 m0, s46
	s_nop 0
	global_load_lds_dwordx4 v132, s[40:41]
	s_waitcnt vmcnt(8)
	s_waitcnt lgkmcnt(0)
	s_barrier
	s_setprio 1
	s_waitcnt lgkmcnt(0)
	v_mfma_f32_16x16x32_bf16 v[2:5], v[192:195], v[42:45], v[66:69]
	v_mfma_f32_16x16x32_bf16 v[2:5], v[196:199], v[50:53], v[2:5]
	v_mfma_f32_16x16x32_bf16 v[6:9], v[200:203], v[42:45], v[70:73]
	v_mfma_f32_16x16x32_bf16 v[6:9], v[204:207], v[50:53], v[6:9]
	v_mfma_f32_16x16x32_bf16 v[14:17], v[200:203], v[58:61], v[78:81]
	v_mfma_f32_16x16x32_bf16 v[14:17], v[204:207], v[224:227], v[14:17]
	v_mfma_f32_16x16x32_bf16 v[10:13], v[192:195], v[58:61], v[74:77]
	v_mfma_f32_16x16x32_bf16 v[10:13], v[196:199], v[224:227], v[10:13]
	v_mfma_f32_16x16x32_bf16 v[18:21], v[192:195], v[228:231], v[82:85]
	v_mfma_f32_16x16x32_bf16 v[18:21], v[196:199], v[232:235], v[18:21]
	v_mfma_f32_16x16x32_bf16 v[22:25], v[200:203], v[228:231], v[86:89]
	v_mfma_f32_16x16x32_bf16 v[22:25], v[204:207], v[232:235], v[22:25]
	v_mfma_f32_16x16x32_bf16 v[30:33], v[200:203], v[236:239], v[94:97]
	v_mfma_f32_16x16x32_bf16 v[30:33], v[204:207], v[240:243], v[30:33]
	v_mfma_f32_16x16x32_bf16 v[26:29], v[192:195], v[236:239], v[90:93]
	v_mfma_f32_16x16x32_bf16 v[26:29], v[196:199], v[240:243], v[26:29]
	s_setprio 0
	s_setprio 1
	v_mfma_f32_16x16x32_bf16 v[34:37], v[208:211], v[42:45], v[98:101]
	v_mfma_f32_16x16x32_bf16 v[38:41], v[216:219], v[42:45], v[38:41]
	v_mfma_f32_16x16x32_bf16 v[34:37], v[212:215], v[50:53], v[34:37]
	v_mfma_f32_16x16x32_bf16 v[38:41], v[220:223], v[50:53], v[38:41]
	v_mfma_f32_16x16x32_bf16 v[42:45], v[208:211], v[58:61], v[102:105]
	v_mfma_f32_16x16x32_bf16 v[46:49], v[216:219], v[58:61], v[46:49]
	v_mfma_f32_16x16x32_bf16 v[50:53], v[208:211], v[228:231], v[106:109]
	v_mfma_f32_16x16x32_bf16 v[54:57], v[216:219], v[228:231], v[54:57]
	v_mfma_f32_16x16x32_bf16 v[58:61], v[208:211], v[236:239], v[110:113]
	v_mfma_f32_16x16x32_bf16 v[62:65], v[216:219], v[236:239], v[62:65]
	v_mfma_f32_16x16x32_bf16 v[42:45], v[212:215], v[224:227], v[42:45]
	v_mfma_f32_16x16x32_bf16 v[46:49], v[220:223], v[224:227], v[46:49]
	v_mfma_f32_16x16x32_bf16 v[50:53], v[212:215], v[232:235], v[50:53]
	v_mfma_f32_16x16x32_bf16 v[54:57], v[220:223], v[232:235], v[54:57]
	s_setprio 2
	s_barrier
	v_mfma_f32_16x16x32_bf16 v[58:61], v[212:215], v[240:243], v[58:61]
	v_mfma_f32_16x16x32_bf16 v[62:65], v[220:223], v[240:243], v[62:65]
	s_setprio 0
	s_add_i32 s62, s62, s21
	v_lshl_add_u64 v[66:67], v[136:137], 0, s[14:15]
	s_mov_b32 m0, s62
	ds_read_b128 v[102:105], v141 offset:49152
	ds_read_b128 v[106:109], v141 offset:50176
	ds_read_b128 v[110:113], v141 offset:51200
	ds_read_b128 v[224:227], v141 offset:52224
	ds_read_b128 v[228:231], v141 offset:53248
	ds_read_b128 v[232:235], v141 offset:54272
	ds_read_b128 v[236:239], v141 offset:55296
	ds_read_b128 v[240:243], v141 offset:56320
	global_load_lds_dwordx4 v[66:67], off
	v_lshl_add_u64 v[66:67], v[244:245], 0, s[14:15]
	s_add_i32 m0, s62, 0x2000
	s_add_i32 s62, s63, s21
	global_load_lds_dwordx4 v[66:67], off
	s_mov_b32 m0, s62
	v_lshl_add_u64 v[66:67], v[246:247], 0, s[14:15]
	global_load_lds_dwordx4 v130, s[42:43]
	s_add_i32 m0, s62, 0x2000
	s_nop 0
	global_load_lds_dwordx4 v134, s[42:43]
	s_mov_b32 m0, s50
	s_nop 0
	global_load_lds_dwordx4 v[66:67], off
	v_lshl_add_u64 v[66:67], v[248:249], 0, s[14:15]
	s_mov_b32 m0, s51
	s_nop 0
	global_load_lds_dwordx4 v[66:67], off
	s_waitcnt vmcnt(8)
	s_waitcnt lgkmcnt(0)
	s_barrier
	s_setprio 1
	s_waitcnt lgkmcnt(0)
	v_mfma_f32_16x16x32_bf16 v[66:69], v[192:195], v[102:105], v[142:145]
	v_mfma_f32_16x16x32_bf16 v[66:69], v[196:199], v[106:109], v[66:69]
	v_mfma_f32_16x16x32_bf16 v[70:73], v[200:203], v[102:105], v[148:151]
	v_mfma_f32_16x16x32_bf16 v[70:73], v[204:207], v[106:109], v[70:73]
	v_mfma_f32_16x16x32_bf16 v[78:81], v[200:203], v[110:113], v[156:159]
	v_mfma_f32_16x16x32_bf16 v[78:81], v[204:207], v[224:227], v[78:81]
	v_mfma_f32_16x16x32_bf16 v[74:77], v[192:195], v[110:113], v[152:155]
	v_mfma_f32_16x16x32_bf16 v[74:77], v[196:199], v[224:227], v[74:77]
	v_mfma_f32_16x16x32_bf16 v[82:85], v[192:195], v[228:231], v[160:163]
	v_mfma_f32_16x16x32_bf16 v[82:85], v[196:199], v[232:235], v[82:85]
	v_mfma_f32_16x16x32_bf16 v[86:89], v[200:203], v[228:231], v[164:167]
	v_mfma_f32_16x16x32_bf16 v[86:89], v[204:207], v[232:235], v[86:89]
	v_mfma_f32_16x16x32_bf16 v[94:97], v[200:203], v[236:239], v[172:175]
	v_mfma_f32_16x16x32_bf16 v[94:97], v[204:207], v[240:243], v[94:97]
	v_mfma_f32_16x16x32_bf16 v[90:93], v[192:195], v[236:239], v[168:171]
	v_mfma_f32_16x16x32_bf16 v[90:93], v[196:199], v[240:243], v[90:93]
	s_setprio 0
	s_setprio 1
	v_mfma_f32_16x16x32_bf16 v[98:101], v[208:211], v[102:105], v[114:117]
	v_mfma_f32_16x16x32_bf16 v[102:105], v[216:219], v[102:105], v[122:125]
	v_mfma_f32_16x16x32_bf16 v[98:101], v[212:215], v[106:109], v[98:101]
	v_mfma_f32_16x16x32_bf16 v[102:105], v[220:223], v[106:109], v[102:105]
	v_mfma_f32_16x16x32_bf16 v[106:109], v[208:211], v[110:113], v[176:179]
	v_mfma_f32_16x16x32_bf16 v[110:113], v[216:219], v[110:113], v[180:183]
	v_mfma_f32_16x16x32_bf16 v[114:117], v[208:211], v[228:231], v[184:187]
	v_mfma_f32_16x16x32_bf16 v[118:121], v[216:219], v[228:231], v[118:121]
	v_mfma_f32_16x16x32_bf16 v[122:125], v[208:211], v[236:239], v[188:191]
	v_mfma_f32_16x16x32_bf16 v[126:129], v[216:219], v[236:239], v[126:129]
	v_mfma_f32_16x16x32_bf16 v[106:109], v[212:215], v[224:227], v[106:109]
	v_mfma_f32_16x16x32_bf16 v[110:113], v[220:223], v[224:227], v[110:113]
	v_mfma_f32_16x16x32_bf16 v[114:117], v[212:215], v[232:235], v[114:117]
	v_mfma_f32_16x16x32_bf16 v[118:121], v[220:223], v[232:235], v[118:121]
	s_setprio 2
	s_barrier
	v_mfma_f32_16x16x32_bf16 v[122:125], v[212:215], v[240:243], v[122:125]
	v_mfma_f32_16x16x32_bf16 v[126:129], v[220:223], v[240:243], v[126:129]
	s_setprio 0
	s_add_i32 s61, s61, 2
	s_cmp_ge_i32 s61, s60
	s_cbranch_scc0 .LBB0_462
	v_mov_b32_e32 v136, v130
	s_branch .LBB0_465

.LBB0_495:
	v_add_u32_e32 v14, s58, v140
	v_add_u32_e32 v30, s59, v140
	ds_read_b128 v[2:5], v14
	ds_read_b128 v[6:9], v14 offset:1024
	ds_read_b128 v[10:13], v14 offset:2048
	ds_read_b128 v[14:17], v14 offset:3072
	ds_read_b128 v[18:21], v30
	ds_read_b128 v[22:25], v30 offset:1024
	ds_read_b128 v[26:29], v30 offset:2048
	ds_read_b128 v[30:33], v30 offset:3072
	v_add_u32_e32 v141, 0, v1
	ds_read_b128 v[34:37], v141
	ds_read_b128 v[38:41], v141 offset:1024
	ds_read_b128 v[42:45], v141 offset:2048
	ds_read_b128 v[46:49], v141 offset:3072
	ds_read_b128 v[50:53], v141 offset:4096
	ds_read_b128 v[54:57], v141 offset:5120
	ds_read_b128 v[58:61], v141 offset:6144
	ds_read_b128 v[62:65], v141 offset:7168
	s_waitcnt vmcnt(8)
	s_waitcnt lgkmcnt(0)
	s_barrier
	s_setprio 1
	s_waitcnt lgkmcnt(0)
	v_mfma_f32_16x16x32_bf16 v[66:69], v[2:5], v[34:37], 0
	v_mfma_f32_16x16x32_bf16 v[66:69], v[6:9], v[38:41], v[66:69]
	v_mfma_f32_16x16x32_bf16 v[70:73], v[10:13], v[34:37], 0
	v_mfma_f32_16x16x32_bf16 v[70:73], v[14:17], v[38:41], v[70:73]
	v_mfma_f32_16x16x32_bf16 v[78:81], v[10:13], v[42:45], 0
	v_mfma_f32_16x16x32_bf16 v[78:81], v[14:17], v[46:49], v[78:81]
	v_mfma_f32_16x16x32_bf16 v[74:77], v[2:5], v[42:45], 0
	v_mfma_f32_16x16x32_bf16 v[74:77], v[6:9], v[46:49], v[74:77]
	v_mfma_f32_16x16x32_bf16 v[82:85], v[2:5], v[50:53], 0
	v_mfma_f32_16x16x32_bf16 v[82:85], v[6:9], v[54:57], v[82:85]
	v_mfma_f32_16x16x32_bf16 v[86:89], v[10:13], v[50:53], 0
	v_mfma_f32_16x16x32_bf16 v[86:89], v[14:17], v[54:57], v[86:89]
	v_mfma_f32_16x16x32_bf16 v[94:97], v[10:13], v[58:61], 0
	v_mfma_f32_16x16x32_bf16 v[94:97], v[14:17], v[62:65], v[94:97]
	v_mfma_f32_16x16x32_bf16 v[90:93], v[2:5], v[58:61], 0
	v_mfma_f32_16x16x32_bf16 v[90:93], v[6:9], v[62:65], v[90:93]
	s_setprio 0
	s_setprio 1
	v_mfma_f32_16x16x32_bf16 v[98:101], v[18:21], v[34:37], 0
	v_mfma_f32_16x16x32_bf16 v[98:101], v[22:25], v[38:41], v[98:101]
	v_mfma_f32_16x16x32_bf16 v[34:37], v[26:29], v[34:37], 0
	v_mfma_f32_16x16x32_bf16 v[38:41], v[30:33], v[38:41], v[34:37]
	v_mfma_f32_16x16x32_bf16 v[102:105], v[18:21], v[42:45], 0
	v_mfma_f32_16x16x32_bf16 v[102:105], v[22:25], v[46:49], v[102:105]
	v_mfma_f32_16x16x32_bf16 v[42:45], v[26:29], v[42:45], 0
	v_mfma_f32_16x16x32_bf16 v[46:49], v[30:33], v[46:49], v[42:45]
	v_mfma_f32_16x16x32_bf16 v[106:109], v[18:21], v[50:53], 0
	v_mfma_f32_16x16x32_bf16 v[106:109], v[22:25], v[54:57], v[106:109]
	v_mfma_f32_16x16x32_bf16 v[50:53], v[26:29], v[50:53], 0
	v_mfma_f32_16x16x32_bf16 v[54:57], v[30:33], v[54:57], v[50:53]
	v_mfma_f32_16x16x32_bf16 v[110:113], v[18:21], v[58:61], 0
	v_mfma_f32_16x16x32_bf16 v[110:113], v[22:25], v[62:65], v[110:113]
	s_setprio 2
	s_barrier
	v_mfma_f32_16x16x32_bf16 v[58:61], v[26:29], v[58:61], 0
	v_mfma_f32_16x16x32_bf16 v[62:65], v[30:33], v[62:65], v[58:61]
	s_setprio 0
	v_lshl_add_u64 v[136:137], s[38:39], 0, v[130:131]
	s_add_i32 s62, s58, s46
	v_mov_b32_e32 v135, v131
	v_lshl_add_u64 v[142:143], v[136:137], 0, s[10:11]
	s_mov_b32 m0, s62
	v_lshl_add_u64 v[244:245], s[38:39], 0, v[134:135]
	ds_read_b128 v[34:37], v141 offset:16384
	ds_read_b128 v[42:45], v141 offset:17408
	ds_read_b128 v[50:53], v141 offset:18432
	ds_read_b128 v[58:61], v141 offset:19456
	ds_read_b128 v[114:117], v141 offset:20480
	ds_read_b128 v[118:121], v141 offset:21504
	ds_read_b128 v[122:125], v141 offset:22528
	ds_read_b128 v[126:129], v141 offset:23552
	global_load_lds_dwordx4 v[142:143], off
	v_lshl_add_u64 v[142:143], v[244:245], 0, s[10:11]
	s_add_i32 m0, s62, 0x2000
	s_add_i32 s62, s59, s46
	global_load_lds_dwordx4 v[142:143], off
	s_mov_b32 m0, s62
	v_mov_b32_e32 v139, v131
	global_load_lds_dwordx4 v130, s[40:41]
	s_add_i32 m0, s62, 0x2000
	v_lshl_add_u64 v[246:247], s[36:37], 0, v[138:139]
	v_mov_b32_e32 v133, v131
	global_load_lds_dwordx4 v134, s[40:41]
	v_lshl_add_u64 v[142:143], v[246:247], 0, s[10:11]
	s_mov_b32 m0, s47
	v_lshl_add_u64 v[248:249], s[36:37], 0, v[132:133]
	global_load_lds_dwordx4 v[142:143], off
	v_lshl_add_u64 v[142:143], v[248:249], 0, s[10:11]
	s_mov_b32 m0, s48
	s_nop 0
	global_load_lds_dwordx4 v[142:143], off
	s_waitcnt vmcnt(8)
	s_waitcnt lgkmcnt(0)
	s_barrier
	s_setprio 1
	s_waitcnt lgkmcnt(0)
	v_mfma_f32_16x16x32_bf16 v[142:145], v[2:5], v[34:37], 0
	v_mfma_f32_16x16x32_bf16 v[142:145], v[6:9], v[42:45], v[142:145]
	v_mfma_f32_16x16x32_bf16 v[148:151], v[10:13], v[34:37], 0
	v_mfma_f32_16x16x32_bf16 v[148:151], v[14:17], v[42:45], v[148:151]
	v_mfma_f32_16x16x32_bf16 v[156:159], v[10:13], v[50:53], 0
	v_mfma_f32_16x16x32_bf16 v[156:159], v[14:17], v[58:61], v[156:159]
	v_mfma_f32_16x16x32_bf16 v[152:155], v[2:5], v[50:53], 0
	v_mfma_f32_16x16x32_bf16 v[152:155], v[6:9], v[58:61], v[152:155]
	v_mfma_f32_16x16x32_bf16 v[160:163], v[2:5], v[114:117], 0
	v_mfma_f32_16x16x32_bf16 v[160:163], v[6:9], v[118:121], v[160:163]
	v_mfma_f32_16x16x32_bf16 v[164:167], v[10:13], v[114:117], 0
	v_mfma_f32_16x16x32_bf16 v[164:167], v[14:17], v[118:121], v[164:167]
	v_mfma_f32_16x16x32_bf16 v[10:13], v[10:13], v[122:125], 0
	v_mfma_f32_16x16x32_bf16 v[172:175], v[14:17], v[126:129], v[10:13]
	v_mfma_f32_16x16x32_bf16 v[2:5], v[2:5], v[122:125], 0
	v_mfma_f32_16x16x32_bf16 v[168:171], v[6:9], v[126:129], v[2:5]
	s_setprio 0
	s_setprio 1
	v_mfma_f32_16x16x32_bf16 v[2:5], v[18:21], v[34:37], 0
	v_mfma_f32_16x16x32_bf16 v[6:9], v[26:29], v[34:37], 0
	v_mfma_f32_16x16x32_bf16 v[10:13], v[18:21], v[50:53], 0
	v_mfma_f32_16x16x32_bf16 v[14:17], v[26:29], v[50:53], 0
	v_mfma_f32_16x16x32_bf16 v[34:37], v[18:21], v[114:117], 0
	v_mfma_f32_16x16x32_bf16 v[50:53], v[26:29], v[114:117], 0
	v_mfma_f32_16x16x32_bf16 v[18:21], v[18:21], v[122:125], 0
	v_mfma_f32_16x16x32_bf16 v[26:29], v[26:29], v[122:125], 0
	v_mfma_f32_16x16x32_bf16 v[114:117], v[22:25], v[42:45], v[2:5]
	v_mfma_f32_16x16x32_bf16 v[122:125], v[30:33], v[42:45], v[6:9]
	v_mfma_f32_16x16x32_bf16 v[184:187], v[22:25], v[118:121], v[34:37]
	v_mfma_f32_16x16x32_bf16 v[118:121], v[30:33], v[118:121], v[50:53]
	v_mfma_f32_16x16x32_bf16 v[188:191], v[22:25], v[126:129], v[18:21]
	v_mfma_f32_16x16x32_bf16 v[126:129], v[30:33], v[126:129], v[26:29]
	s_setprio 2
	s_barrier
	v_mfma_f32_16x16x32_bf16 v[176:179], v[22:25], v[58:61], v[10:13]
	v_mfma_f32_16x16x32_bf16 v[180:183], v[30:33], v[58:61], v[14:17]
	s_setprio 0
	s_add_i32 s62, 0, 0x18000
	v_add_u32_e32 v2, s62, v140
	s_add_i32 s63, 0, 0x1c000
	ds_read_b128 v[192:195], v2
	ds_read_b128 v[196:199], v2 offset:1024
	ds_read_b128 v[200:203], v2 offset:2048
	ds_read_b128 v[204:207], v2 offset:3072
	v_add_u32_e32 v2, s63, v140
	ds_read_b128 v[208:211], v2
	ds_read_b128 v[212:215], v2 offset:1024
	ds_read_b128 v[216:219], v2 offset:2048
	ds_read_b128 v[220:223], v2 offset:3072
	s_mov_b32 m0, s49
	ds_read_b128 v[42:45], v141 offset:32768
	ds_read_b128 v[50:53], v141 offset:33792
	ds_read_b128 v[58:61], v141 offset:34816
	ds_read_b128 v[224:227], v141 offset:35840
	ds_read_b128 v[228:231], v141 offset:36864
	ds_read_b128 v[232:235], v141 offset:37888
	ds_read_b128 v[236:239], v141 offset:38912
	ds_read_b128 v[240:243], v141 offset:39936
	global_load_lds_dwordx4 v138, s[42:43]
	s_mov_b32 m0, s50
	s_nop 0
	global_load_lds_dwordx4 v132, s[42:43]
	s_waitcnt vmcnt(8)
	s_waitcnt lgkmcnt(0)
	s_barrier
	s_setprio 1
	s_waitcnt lgkmcnt(0)
	v_mfma_f32_16x16x32_bf16 v[2:5], v[192:195], v[42:45], v[66:69]
	v_mfma_f32_16x16x32_bf16 v[2:5], v[196:199], v[50:53], v[2:5]
	v_mfma_f32_16x16x32_bf16 v[6:9], v[200:203], v[42:45], v[70:73]
	v_mfma_f32_16x16x32_bf16 v[6:9], v[204:207], v[50:53], v[6:9]
	v_mfma_f32_16x16x32_bf16 v[14:17], v[200:203], v[58:61], v[78:81]
	v_mfma_f32_16x16x32_bf16 v[14:17], v[204:207], v[224:227], v[14:17]
	v_mfma_f32_16x16x32_bf16 v[10:13], v[192:195], v[58:61], v[74:77]
	v_mfma_f32_16x16x32_bf16 v[10:13], v[196:199], v[224:227], v[10:13]
	v_mfma_f32_16x16x32_bf16 v[18:21], v[192:195], v[228:231], v[82:85]
	v_mfma_f32_16x16x32_bf16 v[18:21], v[196:199], v[232:235], v[18:21]
	v_mfma_f32_16x16x32_bf16 v[22:25], v[200:203], v[228:231], v[86:89]
	v_mfma_f32_16x16x32_bf16 v[22:25], v[204:207], v[232:235], v[22:25]
	v_mfma_f32_16x16x32_bf16 v[30:33], v[200:203], v[236:239], v[94:97]
	v_mfma_f32_16x16x32_bf16 v[30:33], v[204:207], v[240:243], v[30:33]
	v_mfma_f32_16x16x32_bf16 v[26:29], v[192:195], v[236:239], v[90:93]
	v_mfma_f32_16x16x32_bf16 v[26:29], v[196:199], v[240:243], v[26:29]
	s_setprio 0
	s_setprio 1
	v_mfma_f32_16x16x32_bf16 v[34:37], v[208:211], v[42:45], v[98:101]
	v_mfma_f32_16x16x32_bf16 v[38:41], v[216:219], v[42:45], v[38:41]
	v_mfma_f32_16x16x32_bf16 v[34:37], v[212:215], v[50:53], v[34:37]
	v_mfma_f32_16x16x32_bf16 v[38:41], v[220:223], v[50:53], v[38:41]
	v_mfma_f32_16x16x32_bf16 v[42:45], v[208:211], v[58:61], v[102:105]
	v_mfma_f32_16x16x32_bf16 v[46:49], v[216:219], v[58:61], v[46:49]
	v_mfma_f32_16x16x32_bf16 v[50:53], v[208:211], v[228:231], v[106:109]
	v_mfma_f32_16x16x32_bf16 v[54:57], v[216:219], v[228:231], v[54:57]
	v_mfma_f32_16x16x32_bf16 v[58:61], v[208:211], v[236:239], v[110:113]
	v_mfma_f32_16x16x32_bf16 v[62:65], v[216:219], v[236:239], v[62:65]
	v_mfma_f32_16x16x32_bf16 v[42:45], v[212:215], v[224:227], v[42:45]
	v_mfma_f32_16x16x32_bf16 v[46:49], v[220:223], v[224:227], v[46:49]
	v_mfma_f32_16x16x32_bf16 v[50:53], v[212:215], v[232:235], v[50:53]
	v_mfma_f32_16x16x32_bf16 v[54:57], v[220:223], v[232:235], v[54:57]
	s_setprio 2
	s_barrier
	v_mfma_f32_16x16x32_bf16 v[58:61], v[212:215], v[240:243], v[58:61]
	v_mfma_f32_16x16x32_bf16 v[62:65], v[220:223], v[240:243], v[62:65]
	s_setprio 0
	s_add_i32 s62, s62, s46
	v_lshl_add_u64 v[66:67], v[136:137], 0, s[12:13]
	s_mov_b32 m0, s62
	ds_read_b128 v[102:105], v141 offset:49152
	ds_read_b128 v[106:109], v141 offset:50176
	ds_read_b128 v[110:113], v141 offset:51200
	ds_read_b128 v[224:227], v141 offset:52224
	ds_read_b128 v[228:231], v141 offset:53248
	ds_read_b128 v[232:235], v141 offset:54272
	ds_read_b128 v[236:239], v141 offset:55296
	ds_read_b128 v[240:243], v141 offset:56320
	global_load_lds_dwordx4 v[66:67], off
	v_lshl_add_u64 v[66:67], v[244:245], 0, s[12:13]
	s_add_i32 m0, s62, 0x2000
	s_add_i32 s62, s63, s46
	global_load_lds_dwordx4 v[66:67], off
	s_mov_b32 m0, s62
	v_lshl_add_u64 v[66:67], v[246:247], 0, s[12:13]
	global_load_lds_dwordx4 v130, s[44:45]
	s_add_i32 m0, s62, 0x2000
	s_nop 0
	global_load_lds_dwordx4 v134, s[44:45]
	s_mov_b32 m0, s54
	s_nop 0
	global_load_lds_dwordx4 v[66:67], off
	v_lshl_add_u64 v[66:67], v[248:249], 0, s[12:13]
	s_mov_b32 m0, s55
	s_nop 0
	global_load_lds_dwordx4 v[66:67], off
	s_waitcnt vmcnt(8)
	s_waitcnt lgkmcnt(0)
	s_barrier
	s_setprio 1
	s_waitcnt lgkmcnt(0)
	v_mfma_f32_16x16x32_bf16 v[66:69], v[192:195], v[102:105], v[142:145]
	v_mfma_f32_16x16x32_bf16 v[66:69], v[196:199], v[106:109], v[66:69]
	v_mfma_f32_16x16x32_bf16 v[70:73], v[200:203], v[102:105], v[148:151]
	v_mfma_f32_16x16x32_bf16 v[70:73], v[204:207], v[106:109], v[70:73]
	v_mfma_f32_16x16x32_bf16 v[78:81], v[200:203], v[110:113], v[156:159]
	v_mfma_f32_16x16x32_bf16 v[78:81], v[204:207], v[224:227], v[78:81]
	v_mfma_f32_16x16x32_bf16 v[74:77], v[192:195], v[110:113], v[152:155]
	v_mfma_f32_16x16x32_bf16 v[74:77], v[196:199], v[224:227], v[74:77]
	v_mfma_f32_16x16x32_bf16 v[82:85], v[192:195], v[228:231], v[160:163]
	v_mfma_f32_16x16x32_bf16 v[82:85], v[196:199], v[232:235], v[82:85]
	v_mfma_f32_16x16x32_bf16 v[86:89], v[200:203], v[228:231], v[164:167]
	v_mfma_f32_16x16x32_bf16 v[86:89], v[204:207], v[232:235], v[86:89]
	v_mfma_f32_16x16x32_bf16 v[94:97], v[200:203], v[236:239], v[172:175]
	v_mfma_f32_16x16x32_bf16 v[94:97], v[204:207], v[240:243], v[94:97]
	v_mfma_f32_16x16x32_bf16 v[90:93], v[192:195], v[236:239], v[168:171]
	v_mfma_f32_16x16x32_bf16 v[90:93], v[196:199], v[240:243], v[90:93]
	s_setprio 0
	s_setprio 1
	v_mfma_f32_16x16x32_bf16 v[98:101], v[208:211], v[102:105], v[114:117]
	v_mfma_f32_16x16x32_bf16 v[102:105], v[216:219], v[102:105], v[122:125]
	v_mfma_f32_16x16x32_bf16 v[98:101], v[212:215], v[106:109], v[98:101]
	v_mfma_f32_16x16x32_bf16 v[102:105], v[220:223], v[106:109], v[102:105]
	v_mfma_f32_16x16x32_bf16 v[106:109], v[208:211], v[110:113], v[176:179]
	v_mfma_f32_16x16x32_bf16 v[110:113], v[216:219], v[110:113], v[180:183]
	v_mfma_f32_16x16x32_bf16 v[114:117], v[208:211], v[228:231], v[184:187]
	v_mfma_f32_16x16x32_bf16 v[118:121], v[216:219], v[228:231], v[118:121]
	v_mfma_f32_16x16x32_bf16 v[122:125], v[208:211], v[236:239], v[188:191]
	v_mfma_f32_16x16x32_bf16 v[126:129], v[216:219], v[236:239], v[126:129]
	v_mfma_f32_16x16x32_bf16 v[106:109], v[212:215], v[224:227], v[106:109]
	v_mfma_f32_16x16x32_bf16 v[110:113], v[220:223], v[224:227], v[110:113]
	v_mfma_f32_16x16x32_bf16 v[114:117], v[212:215], v[232:235], v[114:117]
	v_mfma_f32_16x16x32_bf16 v[118:121], v[220:223], v[232:235], v[118:121]
	s_setprio 2
	s_barrier
	v_mfma_f32_16x16x32_bf16 v[122:125], v[212:215], v[240:243], v[122:125]
	v_mfma_f32_16x16x32_bf16 v[126:129], v[220:223], v[240:243], v[126:129]
	s_setprio 0
	s_add_i32 s27, s27, 2
	s_cmp_ge_i32 s27, s15
	s_cbranch_scc0 .LBB0_495
	v_mov_b32_e32 v136, v130
	s_branch .LBB0_498

.LBB0_528:
	s_add_i32 s53, 0, 0x10000
	s_add_i32 s72, 0, 0x14000
	v_add_u32_e32 v16, s53, v147
	v_add_u32_e32 v32, s72, v147
	ds_read_b128 v[4:7], v16
	ds_read_b128 v[8:11], v16 offset:1024
	ds_read_b128 v[12:15], v16 offset:2048
	ds_read_b128 v[16:19], v16 offset:3072
	ds_read_b128 v[20:23], v32
	ds_read_b128 v[24:27], v32 offset:1024
	ds_read_b128 v[28:31], v32 offset:2048
	ds_read_b128 v[32:35], v32 offset:3072
	v_add_u32_e32 v231, 0, v146
	ds_read_b128 v[36:39], v231
	ds_read_b128 v[40:43], v231 offset:1024
	ds_read_b128 v[44:47], v231 offset:2048
	ds_read_b128 v[48:51], v231 offset:3072
	ds_read_b128 v[52:55], v231 offset:4096
	ds_read_b128 v[56:59], v231 offset:5120
	ds_read_b128 v[60:63], v231 offset:6144
	ds_read_b128 v[64:67], v231 offset:7168
	s_waitcnt vmcnt(8)
	s_waitcnt lgkmcnt(0)
	s_barrier
	s_setprio 1
	s_waitcnt lgkmcnt(0)
	v_mfma_f32_16x16x32_f16 v[68:71], v[4:7], v[36:39], 0
	v_mfma_f32_16x16x32_f16 v[68:71], v[8:11], v[40:43], v[68:71]
	v_mfma_f32_16x16x32_f16 v[72:75], v[12:15], v[36:39], 0
	v_mfma_f32_16x16x32_f16 v[72:75], v[16:19], v[40:43], v[72:75]
	v_mfma_f32_16x16x32_f16 v[80:83], v[12:15], v[44:47], 0
	v_mfma_f32_16x16x32_f16 v[80:83], v[16:19], v[48:51], v[80:83]
	v_mfma_f32_16x16x32_f16 v[76:79], v[4:7], v[44:47], 0
	v_mfma_f32_16x16x32_f16 v[76:79], v[8:11], v[48:51], v[76:79]
	v_mfma_f32_16x16x32_f16 v[84:87], v[4:7], v[52:55], 0
	v_mfma_f32_16x16x32_f16 v[84:87], v[8:11], v[56:59], v[84:87]
	v_mfma_f32_16x16x32_f16 v[88:91], v[12:15], v[52:55], 0
	v_mfma_f32_16x16x32_f16 v[88:91], v[16:19], v[56:59], v[88:91]
	v_mfma_f32_16x16x32_f16 v[96:99], v[12:15], v[60:63], 0
	v_mfma_f32_16x16x32_f16 v[96:99], v[16:19], v[64:67], v[96:99]
	v_mfma_f32_16x16x32_f16 v[92:95], v[4:7], v[60:63], 0
	v_mfma_f32_16x16x32_f16 v[92:95], v[8:11], v[64:67], v[92:95]
	s_setprio 0
	s_setprio 1
	v_mfma_f32_16x16x32_f16 v[100:103], v[20:23], v[36:39], 0
	v_mfma_f32_16x16x32_f16 v[100:103], v[24:27], v[40:43], v[100:103]
	v_mfma_f32_16x16x32_f16 v[36:39], v[28:31], v[36:39], 0
	v_mfma_f32_16x16x32_f16 v[40:43], v[32:35], v[40:43], v[36:39]
	v_mfma_f32_16x16x32_f16 v[104:107], v[20:23], v[44:47], 0
	v_mfma_f32_16x16x32_f16 v[104:107], v[24:27], v[48:51], v[104:107]
	v_mfma_f32_16x16x32_f16 v[44:47], v[28:31], v[44:47], 0
	v_mfma_f32_16x16x32_f16 v[48:51], v[32:35], v[48:51], v[44:47]
	v_mfma_f32_16x16x32_f16 v[108:111], v[20:23], v[52:55], 0
	v_mfma_f32_16x16x32_f16 v[108:111], v[24:27], v[56:59], v[108:111]
	v_mfma_f32_16x16x32_f16 v[52:55], v[28:31], v[52:55], 0
	v_mfma_f32_16x16x32_f16 v[56:59], v[32:35], v[56:59], v[52:55]
	v_mfma_f32_16x16x32_f16 v[112:115], v[20:23], v[60:63], 0
	v_mfma_f32_16x16x32_f16 v[112:115], v[24:27], v[64:67], v[112:115]
	s_setprio 2
	s_barrier
	v_mfma_f32_16x16x32_f16 v[60:63], v[28:31], v[60:63], 0
	v_mfma_f32_16x16x32_f16 v[64:67], v[32:35], v[64:67], v[60:63]
	s_setprio 0
	v_lshl_add_u64 v[136:137], s[6:7], 0, v[2:3]
	s_add_i32 s53, s53, s38
	v_mov_b32_e32 v135, v3
	v_lshl_add_u64 v[140:141], v[136:137], 0, s[74:75]
	s_mov_b32 m0, s53
	v_lshl_add_u64 v[144:145], s[6:7], 0, v[134:135]
	ds_read_b128 v[36:39], v231 offset:16384
	ds_read_b128 v[44:47], v231 offset:17408
	ds_read_b128 v[52:55], v231 offset:18432
	ds_read_b128 v[60:63], v231 offset:19456
	ds_read_b128 v[116:119], v231 offset:20480
	ds_read_b128 v[120:123], v231 offset:21504
	ds_read_b128 v[124:127], v231 offset:22528
	ds_read_b128 v[128:131], v231 offset:23552
	global_load_lds_dwordx4 v[140:141], off
	v_lshl_add_u64 v[140:141], v[144:145], 0, s[74:75]
	s_add_i32 m0, s53, 0x2000
	s_add_i32 s53, s72, s38
	global_load_lds_dwordx4 v[140:141], off
	s_mov_b32 m0, s53
	v_mov_b32_e32 v139, v3
	global_load_lds_dwordx4 v2, s[16:17]
	s_add_i32 m0, s53, 0x2000
	v_lshl_add_u64 v[248:249], s[8:9], 0, v[138:139]
	v_mov_b32_e32 v133, v3
	global_load_lds_dwordx4 v134, s[16:17]
	v_lshl_add_u64 v[140:141], v[248:249], 0, s[74:75]
	s_mov_b32 m0, s58
	v_lshl_add_u64 v[250:251], s[8:9], 0, v[132:133]
	global_load_lds_dwordx4 v[140:141], off
	v_lshl_add_u64 v[140:141], v[250:251], 0, s[74:75]
	s_mov_b32 m0, s59
	s_nop 0
	global_load_lds_dwordx4 v[140:141], off
	s_waitcnt vmcnt(8)
	s_waitcnt lgkmcnt(0)
	s_barrier
	s_setprio 1
	s_waitcnt lgkmcnt(0)
	v_mfma_f32_16x16x32_f16 v[140:143], v[4:7], v[36:39], 0
	v_mfma_f32_16x16x32_f16 v[140:143], v[8:11], v[44:47], v[140:143]
	v_mfma_f32_16x16x32_f16 v[148:151], v[12:15], v[36:39], 0
	v_mfma_f32_16x16x32_f16 v[148:151], v[16:19], v[44:47], v[148:151]
	v_mfma_f32_16x16x32_f16 v[156:159], v[12:15], v[52:55], 0
	v_mfma_f32_16x16x32_f16 v[156:159], v[16:19], v[60:63], v[156:159]
	v_mfma_f32_16x16x32_f16 v[152:155], v[4:7], v[52:55], 0
	v_mfma_f32_16x16x32_f16 v[152:155], v[8:11], v[60:63], v[152:155]
	v_mfma_f32_16x16x32_f16 v[160:163], v[4:7], v[116:119], 0
	v_mfma_f32_16x16x32_f16 v[160:163], v[8:11], v[120:123], v[160:163]
	v_mfma_f32_16x16x32_f16 v[164:167], v[12:15], v[116:119], 0
	v_mfma_f32_16x16x32_f16 v[164:167], v[16:19], v[120:123], v[164:167]
	v_mfma_f32_16x16x32_f16 v[12:15], v[12:15], v[124:127], 0
	v_mfma_f32_16x16x32_f16 v[172:175], v[16:19], v[128:131], v[12:15]
	v_mfma_f32_16x16x32_f16 v[4:7], v[4:7], v[124:127], 0
	v_mfma_f32_16x16x32_f16 v[168:171], v[8:11], v[128:131], v[4:7]
	s_setprio 0
	s_setprio 1
	v_mfma_f32_16x16x32_f16 v[4:7], v[20:23], v[36:39], 0
	v_mfma_f32_16x16x32_f16 v[8:11], v[28:31], v[36:39], 0
	v_mfma_f32_16x16x32_f16 v[12:15], v[20:23], v[52:55], 0
	v_mfma_f32_16x16x32_f16 v[16:19], v[28:31], v[52:55], 0
	v_mfma_f32_16x16x32_f16 v[36:39], v[20:23], v[116:119], 0
	v_mfma_f32_16x16x32_f16 v[52:55], v[28:31], v[116:119], 0
	v_mfma_f32_16x16x32_f16 v[20:23], v[20:23], v[124:127], 0
	v_mfma_f32_16x16x32_f16 v[28:31], v[28:31], v[124:127], 0
	v_mfma_f32_16x16x32_f16 v[116:119], v[24:27], v[44:47], v[4:7]
	v_mfma_f32_16x16x32_f16 v[124:127], v[32:35], v[44:47], v[8:11]
	v_mfma_f32_16x16x32_f16 v[184:187], v[24:27], v[120:123], v[36:39]
	v_mfma_f32_16x16x32_f16 v[120:123], v[32:35], v[120:123], v[52:55]
	v_mfma_f32_16x16x32_f16 v[188:191], v[24:27], v[128:131], v[20:23]
	v_mfma_f32_16x16x32_f16 v[128:131], v[32:35], v[128:131], v[28:31]
	s_setprio 2
	s_barrier
	v_mfma_f32_16x16x32_f16 v[176:179], v[24:27], v[60:63], v[12:15]
	v_mfma_f32_16x16x32_f16 v[180:183], v[32:35], v[60:63], v[16:19]
	s_setprio 0
	s_add_i32 s53, 0, 0x18000
	v_add_u32_e32 v4, s53, v147
	s_add_i32 s72, 0, 0x1c000
	ds_read_b128 v[192:195], v4
	ds_read_b128 v[196:199], v4 offset:1024
	ds_read_b128 v[200:203], v4 offset:2048
	ds_read_b128 v[204:207], v4 offset:3072
	v_add_u32_e32 v4, s72, v147
	ds_read_b128 v[208:211], v4
	ds_read_b128 v[212:215], v4 offset:1024
	ds_read_b128 v[216:219], v4 offset:2048
	ds_read_b128 v[220:223], v4 offset:3072
	s_mov_b32 m0, s60
	ds_read_b128 v[44:47], v231 offset:32768
	ds_read_b128 v[52:55], v231 offset:33792
	ds_read_b128 v[60:63], v231 offset:34816
	ds_read_b128 v[224:227], v231 offset:35840
	ds_read_b128 v[232:235], v231 offset:36864
	ds_read_b128 v[236:239], v231 offset:37888
	ds_read_b128 v[240:243], v231 offset:38912
	ds_read_b128 v[244:247], v231 offset:39936
	global_load_lds_dwordx4 v138, s[26:27]
	s_mov_b32 m0, s61
	s_nop 0
	global_load_lds_dwordx4 v132, s[26:27]
	s_waitcnt vmcnt(8)
	s_waitcnt lgkmcnt(0)
	s_barrier
	s_setprio 1
	s_waitcnt lgkmcnt(0)
	v_mfma_f32_16x16x32_f16 v[4:7], v[192:195], v[44:47], v[68:71]
	v_mfma_f32_16x16x32_f16 v[4:7], v[196:199], v[52:55], v[4:7]
	v_mfma_f32_16x16x32_f16 v[8:11], v[200:203], v[44:47], v[72:75]
	v_mfma_f32_16x16x32_f16 v[8:11], v[204:207], v[52:55], v[8:11]
	v_mfma_f32_16x16x32_f16 v[16:19], v[200:203], v[60:63], v[80:83]
	v_mfma_f32_16x16x32_f16 v[16:19], v[204:207], v[224:227], v[16:19]
	v_mfma_f32_16x16x32_f16 v[12:15], v[192:195], v[60:63], v[76:79]
	v_mfma_f32_16x16x32_f16 v[12:15], v[196:199], v[224:227], v[12:15]
	v_mfma_f32_16x16x32_f16 v[20:23], v[192:195], v[232:235], v[84:87]
	v_mfma_f32_16x16x32_f16 v[20:23], v[196:199], v[236:239], v[20:23]
	v_mfma_f32_16x16x32_f16 v[24:27], v[200:203], v[232:235], v[88:91]
	v_mfma_f32_16x16x32_f16 v[24:27], v[204:207], v[236:239], v[24:27]
	v_mfma_f32_16x16x32_f16 v[32:35], v[200:203], v[240:243], v[96:99]
	v_mfma_f32_16x16x32_f16 v[32:35], v[204:207], v[244:247], v[32:35]
	v_mfma_f32_16x16x32_f16 v[28:31], v[192:195], v[240:243], v[92:95]
	v_mfma_f32_16x16x32_f16 v[28:31], v[196:199], v[244:247], v[28:31]
	s_setprio 0
	s_setprio 1
	v_mfma_f32_16x16x32_f16 v[36:39], v[208:211], v[44:47], v[100:103]
	v_mfma_f32_16x16x32_f16 v[40:43], v[216:219], v[44:47], v[40:43]
	v_mfma_f32_16x16x32_f16 v[36:39], v[212:215], v[52:55], v[36:39]
	v_mfma_f32_16x16x32_f16 v[40:43], v[220:223], v[52:55], v[40:43]
	v_mfma_f32_16x16x32_f16 v[44:47], v[208:211], v[60:63], v[104:107]
	v_mfma_f32_16x16x32_f16 v[48:51], v[216:219], v[60:63], v[48:51]
	v_mfma_f32_16x16x32_f16 v[52:55], v[208:211], v[232:235], v[108:111]
	v_mfma_f32_16x16x32_f16 v[56:59], v[216:219], v[232:235], v[56:59]
	v_mfma_f32_16x16x32_f16 v[60:63], v[208:211], v[240:243], v[112:115]
	v_mfma_f32_16x16x32_f16 v[64:67], v[216:219], v[240:243], v[64:67]
	v_mfma_f32_16x16x32_f16 v[44:47], v[212:215], v[224:227], v[44:47]
	v_mfma_f32_16x16x32_f16 v[48:51], v[220:223], v[224:227], v[48:51]
	v_mfma_f32_16x16x32_f16 v[52:55], v[212:215], v[236:239], v[52:55]
	v_mfma_f32_16x16x32_f16 v[56:59], v[220:223], v[236:239], v[56:59]
	s_setprio 2
	s_barrier
	v_mfma_f32_16x16x32_f16 v[60:63], v[212:215], v[244:247], v[60:63]
	v_mfma_f32_16x16x32_f16 v[64:67], v[220:223], v[244:247], v[64:67]
	s_setprio 0
	s_add_i32 s53, s53, s38
	v_lshl_add_u64 v[68:69], v[136:137], 0, s[24:25]
	s_mov_b32 m0, s53
	ds_read_b128 v[104:107], v231 offset:49152
	ds_read_b128 v[108:111], v231 offset:50176
	ds_read_b128 v[112:115], v231 offset:51200
	ds_read_b128 v[224:227], v231 offset:52224
	ds_read_b128 v[232:235], v231 offset:53248
	ds_read_b128 v[236:239], v231 offset:54272
	ds_read_b128 v[240:243], v231 offset:55296
	ds_read_b128 v[244:247], v231 offset:56320
	global_load_lds_dwordx4 v[68:69], off
	v_lshl_add_u64 v[68:69], v[144:145], 0, s[24:25]
	s_add_i32 m0, s53, 0x2000
	s_add_i32 s53, s72, s38
	global_load_lds_dwordx4 v[68:69], off
	s_mov_b32 m0, s53
	v_lshl_add_u64 v[68:69], v[248:249], 0, s[24:25]
	global_load_lds_dwordx4 v2, s[28:29]
	s_add_i32 m0, s53, 0x2000
	s_nop 0
	global_load_lds_dwordx4 v134, s[28:29]
	s_mov_b32 m0, s64
	s_nop 0
	global_load_lds_dwordx4 v[68:69], off
	v_lshl_add_u64 v[68:69], v[250:251], 0, s[24:25]
	s_mov_b32 m0, s65
	s_nop 0
	global_load_lds_dwordx4 v[68:69], off
	s_waitcnt vmcnt(8)
	s_waitcnt lgkmcnt(0)
	s_barrier
	s_setprio 1
	s_waitcnt lgkmcnt(0)
	v_mfma_f32_16x16x32_f16 v[68:71], v[192:195], v[104:107], v[140:143]
	v_mfma_f32_16x16x32_f16 v[68:71], v[196:199], v[108:111], v[68:71]
	v_mfma_f32_16x16x32_f16 v[72:75], v[200:203], v[104:107], v[148:151]
	v_mfma_f32_16x16x32_f16 v[72:75], v[204:207], v[108:111], v[72:75]
	v_mfma_f32_16x16x32_f16 v[80:83], v[200:203], v[112:115], v[156:159]
	v_mfma_f32_16x16x32_f16 v[80:83], v[204:207], v[224:227], v[80:83]
	v_mfma_f32_16x16x32_f16 v[76:79], v[192:195], v[112:115], v[152:155]
	v_mfma_f32_16x16x32_f16 v[76:79], v[196:199], v[224:227], v[76:79]
	v_mfma_f32_16x16x32_f16 v[84:87], v[192:195], v[232:235], v[160:163]
	v_mfma_f32_16x16x32_f16 v[84:87], v[196:199], v[236:239], v[84:87]
	v_mfma_f32_16x16x32_f16 v[88:91], v[200:203], v[232:235], v[164:167]
	v_mfma_f32_16x16x32_f16 v[88:91], v[204:207], v[236:239], v[88:91]
	v_mfma_f32_16x16x32_f16 v[96:99], v[200:203], v[240:243], v[172:175]
	v_mfma_f32_16x16x32_f16 v[96:99], v[204:207], v[244:247], v[96:99]
	v_mfma_f32_16x16x32_f16 v[92:95], v[192:195], v[240:243], v[168:171]
	v_mfma_f32_16x16x32_f16 v[92:95], v[196:199], v[244:247], v[92:95]
	s_setprio 0
	s_setprio 1
	v_mfma_f32_16x16x32_f16 v[100:103], v[208:211], v[104:107], v[116:119]
	v_mfma_f32_16x16x32_f16 v[104:107], v[216:219], v[104:107], v[124:127]
	v_mfma_f32_16x16x32_f16 v[100:103], v[212:215], v[108:111], v[100:103]
	v_mfma_f32_16x16x32_f16 v[104:107], v[220:223], v[108:111], v[104:107]
	v_mfma_f32_16x16x32_f16 v[108:111], v[208:211], v[112:115], v[176:179]
	v_mfma_f32_16x16x32_f16 v[112:115], v[216:219], v[112:115], v[180:183]
	v_mfma_f32_16x16x32_f16 v[116:119], v[208:211], v[232:235], v[184:187]
	v_mfma_f32_16x16x32_f16 v[120:123], v[216:219], v[232:235], v[120:123]
	v_mfma_f32_16x16x32_f16 v[124:127], v[208:211], v[240:243], v[188:191]
	v_mfma_f32_16x16x32_f16 v[128:131], v[216:219], v[240:243], v[128:131]
	v_mfma_f32_16x16x32_f16 v[108:111], v[212:215], v[224:227], v[108:111]
	v_mfma_f32_16x16x32_f16 v[112:115], v[220:223], v[224:227], v[112:115]
	v_mfma_f32_16x16x32_f16 v[116:119], v[212:215], v[236:239], v[116:119]
	v_mfma_f32_16x16x32_f16 v[120:123], v[220:223], v[236:239], v[120:123]
	s_setprio 2
	s_barrier
	v_mfma_f32_16x16x32_f16 v[124:127], v[212:215], v[244:247], v[124:127]
	v_mfma_f32_16x16x32_f16 v[128:131], v[220:223], v[244:247], v[128:131]
	s_setprio 0
	s_add_i32 s41, s41, 2
	s_cmp_ge_i32 s41, s40
	s_cbranch_scc0 .LBB0_528
	v_mov_b32_e32 v136, v2
	s_branch .LBB0_531

.LBB0_641:
	s_add_i32 s43, 0, 0x10000
	s_add_i32 s71, 0, 0x14000
	v_add_u32_e32 v16, s43, v232
	v_add_u32_e32 v32, s71, v232
	ds_read_b128 v[4:7], v16
	ds_read_b128 v[8:11], v16 offset:1024
	ds_read_b128 v[12:15], v16 offset:2048
	ds_read_b128 v[16:19], v16 offset:3072
	ds_read_b128 v[20:23], v32
	ds_read_b128 v[24:27], v32 offset:1024
	ds_read_b128 v[28:31], v32 offset:2048
	ds_read_b128 v[32:35], v32 offset:3072
	v_add_u32_e32 v233, 0, v231
	ds_read_b128 v[36:39], v233
	ds_read_b128 v[40:43], v233 offset:1024
	ds_read_b128 v[44:47], v233 offset:2048
	ds_read_b128 v[48:51], v233 offset:3072
	ds_read_b128 v[52:55], v233 offset:4096
	ds_read_b128 v[56:59], v233 offset:5120
	ds_read_b128 v[60:63], v233 offset:6144
	ds_read_b128 v[64:67], v233 offset:7168
	s_waitcnt vmcnt(8)
	s_waitcnt lgkmcnt(0)
	s_barrier
	s_setprio 1
	s_waitcnt lgkmcnt(0)
	v_mfma_f32_16x16x32_bf16 v[68:71], v[4:7], v[36:39], 0
	v_mfma_f32_16x16x32_bf16 v[68:71], v[8:11], v[40:43], v[68:71]
	v_mfma_f32_16x16x32_bf16 v[72:75], v[12:15], v[36:39], 0
	v_mfma_f32_16x16x32_bf16 v[72:75], v[16:19], v[40:43], v[72:75]
	v_mfma_f32_16x16x32_bf16 v[80:83], v[12:15], v[44:47], 0
	v_mfma_f32_16x16x32_bf16 v[80:83], v[16:19], v[48:51], v[80:83]
	v_mfma_f32_16x16x32_bf16 v[76:79], v[4:7], v[44:47], 0
	v_mfma_f32_16x16x32_bf16 v[76:79], v[8:11], v[48:51], v[76:79]
	v_mfma_f32_16x16x32_bf16 v[84:87], v[4:7], v[52:55], 0
	v_mfma_f32_16x16x32_bf16 v[84:87], v[8:11], v[56:59], v[84:87]
	v_mfma_f32_16x16x32_bf16 v[88:91], v[12:15], v[52:55], 0
	v_mfma_f32_16x16x32_bf16 v[88:91], v[16:19], v[56:59], v[88:91]
	v_mfma_f32_16x16x32_bf16 v[96:99], v[12:15], v[60:63], 0
	v_mfma_f32_16x16x32_bf16 v[96:99], v[16:19], v[64:67], v[96:99]
	v_mfma_f32_16x16x32_bf16 v[92:95], v[4:7], v[60:63], 0
	v_mfma_f32_16x16x32_bf16 v[92:95], v[8:11], v[64:67], v[92:95]
	s_setprio 0
	s_setprio 1
	v_mfma_f32_16x16x32_bf16 v[100:103], v[20:23], v[36:39], 0
	v_mfma_f32_16x16x32_bf16 v[100:103], v[24:27], v[40:43], v[100:103]
	v_mfma_f32_16x16x32_bf16 v[36:39], v[28:31], v[36:39], 0
	v_mfma_f32_16x16x32_bf16 v[40:43], v[32:35], v[40:43], v[36:39]
	v_mfma_f32_16x16x32_bf16 v[104:107], v[20:23], v[44:47], 0
	v_mfma_f32_16x16x32_bf16 v[104:107], v[24:27], v[48:51], v[104:107]
	v_mfma_f32_16x16x32_bf16 v[44:47], v[28:31], v[44:47], 0
	v_mfma_f32_16x16x32_bf16 v[48:51], v[32:35], v[48:51], v[44:47]
	v_mfma_f32_16x16x32_bf16 v[108:111], v[20:23], v[52:55], 0
	v_mfma_f32_16x16x32_bf16 v[108:111], v[24:27], v[56:59], v[108:111]
	v_mfma_f32_16x16x32_bf16 v[52:55], v[28:31], v[52:55], 0
	v_mfma_f32_16x16x32_bf16 v[56:59], v[32:35], v[56:59], v[52:55]
	v_mfma_f32_16x16x32_bf16 v[112:115], v[20:23], v[60:63], 0
	v_mfma_f32_16x16x32_bf16 v[112:115], v[24:27], v[64:67], v[112:115]
	s_setprio 2
	s_barrier
	v_mfma_f32_16x16x32_bf16 v[60:63], v[28:31], v[60:63], 0
	v_mfma_f32_16x16x32_bf16 v[64:67], v[32:35], v[64:67], v[60:63]
	s_setprio 0
	v_lshl_add_u64 v[186:187], s[8:9], 0, v[2:3]
	s_add_i32 s43, s43, s54
	v_mov_b32_e32 v191, v3
	v_lshl_add_u64 v[134:135], v[186:187], 0, s[80:81]
	s_mov_b32 m0, s43
	v_lshl_add_u64 v[246:247], s[8:9], 0, v[190:191]
	ds_read_b128 v[36:39], v233 offset:16384
	ds_read_b128 v[44:47], v233 offset:17408
	ds_read_b128 v[52:55], v233 offset:18432
	ds_read_b128 v[60:63], v233 offset:19456
	ds_read_b128 v[116:119], v233 offset:20480
	ds_read_b128 v[120:123], v233 offset:21504
	ds_read_b128 v[124:127], v233 offset:22528
	ds_read_b128 v[128:131], v233 offset:23552
	global_load_lds_dwordx4 v[134:135], off
	v_lshl_add_u64 v[134:135], v[246:247], 0, s[80:81]
	s_add_i32 m0, s43, 0x2000
	s_add_i32 s43, s71, s54
	global_load_lds_dwordx4 v[134:135], off
	s_mov_b32 m0, s43
	v_mov_b32_e32 v133, v3
	global_load_lds_dwordx4 v2, s[16:17]
	s_add_i32 m0, s43, 0x2000
	v_lshl_add_u64 v[248:249], s[6:7], 0, v[132:133]
	v_mov_b32_e32 v189, v3
	global_load_lds_dwordx4 v190, s[16:17]
	v_lshl_add_u64 v[134:135], v[248:249], 0, s[80:81]
	s_mov_b32 m0, s55
	v_lshl_add_u64 v[250:251], s[6:7], 0, v[188:189]
	global_load_lds_dwordx4 v[134:135], off
	v_lshl_add_u64 v[134:135], v[250:251], 0, s[80:81]
	s_mov_b32 m0, s56
	s_nop 0
	global_load_lds_dwordx4 v[134:135], off
	s_waitcnt vmcnt(8)
	s_waitcnt lgkmcnt(0)
	s_barrier
	s_setprio 1
	s_waitcnt lgkmcnt(0)
	v_mfma_f32_16x16x32_bf16 v[134:137], v[4:7], v[36:39], 0
	v_mfma_f32_16x16x32_bf16 v[134:137], v[8:11], v[44:47], v[134:137]
	v_mfma_f32_16x16x32_bf16 v[138:141], v[12:15], v[36:39], 0
	v_mfma_f32_16x16x32_bf16 v[138:141], v[16:19], v[44:47], v[138:141]
	v_mfma_f32_16x16x32_bf16 v[146:149], v[12:15], v[52:55], 0
	v_mfma_f32_16x16x32_bf16 v[146:149], v[16:19], v[60:63], v[146:149]
	v_mfma_f32_16x16x32_bf16 v[142:145], v[4:7], v[52:55], 0
	v_mfma_f32_16x16x32_bf16 v[142:145], v[8:11], v[60:63], v[142:145]
	v_mfma_f32_16x16x32_bf16 v[150:153], v[4:7], v[116:119], 0
	v_mfma_f32_16x16x32_bf16 v[150:153], v[8:11], v[120:123], v[150:153]
	v_mfma_f32_16x16x32_bf16 v[154:157], v[12:15], v[116:119], 0
	v_mfma_f32_16x16x32_bf16 v[154:157], v[16:19], v[120:123], v[154:157]
	v_mfma_f32_16x16x32_bf16 v[12:15], v[12:15], v[124:127], 0
	v_mfma_f32_16x16x32_bf16 v[162:165], v[16:19], v[128:131], v[12:15]
	v_mfma_f32_16x16x32_bf16 v[4:7], v[4:7], v[124:127], 0
	v_mfma_f32_16x16x32_bf16 v[158:161], v[8:11], v[128:131], v[4:7]
	s_setprio 0
	s_setprio 1
	v_mfma_f32_16x16x32_bf16 v[4:7], v[20:23], v[36:39], 0
	v_mfma_f32_16x16x32_bf16 v[8:11], v[28:31], v[36:39], 0
	v_mfma_f32_16x16x32_bf16 v[12:15], v[20:23], v[52:55], 0
	v_mfma_f32_16x16x32_bf16 v[16:19], v[28:31], v[52:55], 0
	v_mfma_f32_16x16x32_bf16 v[36:39], v[20:23], v[116:119], 0
	v_mfma_f32_16x16x32_bf16 v[52:55], v[28:31], v[116:119], 0
	v_mfma_f32_16x16x32_bf16 v[20:23], v[20:23], v[124:127], 0
	v_mfma_f32_16x16x32_bf16 v[28:31], v[28:31], v[124:127], 0
	v_mfma_f32_16x16x32_bf16 v[116:119], v[24:27], v[44:47], v[4:7]
	v_mfma_f32_16x16x32_bf16 v[124:127], v[32:35], v[44:47], v[8:11]
	v_mfma_f32_16x16x32_bf16 v[174:177], v[24:27], v[120:123], v[36:39]
	v_mfma_f32_16x16x32_bf16 v[120:123], v[32:35], v[120:123], v[52:55]
	v_mfma_f32_16x16x32_bf16 v[178:181], v[24:27], v[128:131], v[20:23]
	v_mfma_f32_16x16x32_bf16 v[128:131], v[32:35], v[128:131], v[28:31]
	s_setprio 2
	s_barrier
	v_mfma_f32_16x16x32_bf16 v[166:169], v[24:27], v[60:63], v[12:15]
	v_mfma_f32_16x16x32_bf16 v[170:173], v[32:35], v[60:63], v[16:19]
	s_setprio 0
	s_add_i32 s43, 0, 0x18000
	v_add_u32_e32 v4, s43, v232
	s_add_i32 s71, 0, 0x1c000
	ds_read_b128 v[182:185], v4
	ds_read_b128 v[192:195], v4 offset:1024
	ds_read_b128 v[196:199], v4 offset:2048
	ds_read_b128 v[200:203], v4 offset:3072
	v_add_u32_e32 v4, s71, v232
	ds_read_b128 v[204:207], v4
	ds_read_b128 v[208:211], v4 offset:1024
	ds_read_b128 v[212:215], v4 offset:2048
	ds_read_b128 v[216:219], v4 offset:3072
	s_mov_b32 m0, s57
	ds_read_b128 v[44:47], v233 offset:32768
	ds_read_b128 v[52:55], v233 offset:33792
	ds_read_b128 v[60:63], v233 offset:34816
	ds_read_b128 v[220:223], v233 offset:35840
	ds_read_b128 v[224:227], v233 offset:36864
	ds_read_b128 v[234:237], v233 offset:37888
	ds_read_b128 v[238:241], v233 offset:38912
	ds_read_b128 v[242:245], v233 offset:39936
	global_load_lds_dwordx4 v132, s[26:27]
	s_mov_b32 m0, s58
	s_nop 0
	global_load_lds_dwordx4 v188, s[26:27]
	s_waitcnt vmcnt(8)
	s_waitcnt lgkmcnt(0)
	s_barrier
	s_setprio 1
	s_waitcnt lgkmcnt(0)
	v_mfma_f32_16x16x32_bf16 v[4:7], v[182:185], v[44:47], v[68:71]
	v_mfma_f32_16x16x32_bf16 v[4:7], v[192:195], v[52:55], v[4:7]
	v_mfma_f32_16x16x32_bf16 v[8:11], v[196:199], v[44:47], v[72:75]
	v_mfma_f32_16x16x32_bf16 v[8:11], v[200:203], v[52:55], v[8:11]
	v_mfma_f32_16x16x32_bf16 v[16:19], v[196:199], v[60:63], v[80:83]
	v_mfma_f32_16x16x32_bf16 v[16:19], v[200:203], v[220:223], v[16:19]
	v_mfma_f32_16x16x32_bf16 v[12:15], v[182:185], v[60:63], v[76:79]
	v_mfma_f32_16x16x32_bf16 v[12:15], v[192:195], v[220:223], v[12:15]
	v_mfma_f32_16x16x32_bf16 v[20:23], v[182:185], v[224:227], v[84:87]
	v_mfma_f32_16x16x32_bf16 v[20:23], v[192:195], v[234:237], v[20:23]
	v_mfma_f32_16x16x32_bf16 v[24:27], v[196:199], v[224:227], v[88:91]
	v_mfma_f32_16x16x32_bf16 v[24:27], v[200:203], v[234:237], v[24:27]
	v_mfma_f32_16x16x32_bf16 v[32:35], v[196:199], v[238:241], v[96:99]
	v_mfma_f32_16x16x32_bf16 v[32:35], v[200:203], v[242:245], v[32:35]
	v_mfma_f32_16x16x32_bf16 v[28:31], v[182:185], v[238:241], v[92:95]
	v_mfma_f32_16x16x32_bf16 v[28:31], v[192:195], v[242:245], v[28:31]
	s_setprio 0
	s_setprio 1
	v_mfma_f32_16x16x32_bf16 v[36:39], v[204:207], v[44:47], v[100:103]
	v_mfma_f32_16x16x32_bf16 v[40:43], v[212:215], v[44:47], v[40:43]
	v_mfma_f32_16x16x32_bf16 v[36:39], v[208:211], v[52:55], v[36:39]
	v_mfma_f32_16x16x32_bf16 v[40:43], v[216:219], v[52:55], v[40:43]
	v_mfma_f32_16x16x32_bf16 v[44:47], v[204:207], v[60:63], v[104:107]
	v_mfma_f32_16x16x32_bf16 v[48:51], v[212:215], v[60:63], v[48:51]
	v_mfma_f32_16x16x32_bf16 v[52:55], v[204:207], v[224:227], v[108:111]
	v_mfma_f32_16x16x32_bf16 v[56:59], v[212:215], v[224:227], v[56:59]
	v_mfma_f32_16x16x32_bf16 v[60:63], v[204:207], v[238:241], v[112:115]
	v_mfma_f32_16x16x32_bf16 v[64:67], v[212:215], v[238:241], v[64:67]
	v_mfma_f32_16x16x32_bf16 v[44:47], v[208:211], v[220:223], v[44:47]
	v_mfma_f32_16x16x32_bf16 v[48:51], v[216:219], v[220:223], v[48:51]
	v_mfma_f32_16x16x32_bf16 v[52:55], v[208:211], v[234:237], v[52:55]
	v_mfma_f32_16x16x32_bf16 v[56:59], v[216:219], v[234:237], v[56:59]
	s_setprio 2
	s_barrier
	v_mfma_f32_16x16x32_bf16 v[60:63], v[208:211], v[242:245], v[60:63]
	v_mfma_f32_16x16x32_bf16 v[64:67], v[216:219], v[242:245], v[64:67]
	s_setprio 0
	s_add_i32 s43, s43, s54
	v_lshl_add_u64 v[68:69], v[186:187], 0, s[0:1]
	s_mov_b32 m0, s43
	ds_read_b128 v[104:107], v233 offset:49152
	ds_read_b128 v[108:111], v233 offset:50176
	ds_read_b128 v[112:115], v233 offset:51200
	ds_read_b128 v[220:223], v233 offset:52224
	ds_read_b128 v[224:227], v233 offset:53248
	ds_read_b128 v[234:237], v233 offset:54272
	ds_read_b128 v[238:241], v233 offset:55296
	ds_read_b128 v[242:245], v233 offset:56320
	global_load_lds_dwordx4 v[68:69], off
	v_lshl_add_u64 v[68:69], v[246:247], 0, s[0:1]
	s_add_i32 m0, s43, 0x2000
	s_add_i32 s43, s71, s54
	global_load_lds_dwordx4 v[68:69], off
	s_mov_b32 m0, s43
	v_lshl_add_u64 v[68:69], v[248:249], 0, s[0:1]
	global_load_lds_dwordx4 v2, s[28:29]
	s_add_i32 m0, s43, 0x2000
	s_nop 0
	global_load_lds_dwordx4 v190, s[28:29]
	s_mov_b32 m0, s62
	s_nop 0
	global_load_lds_dwordx4 v[68:69], off
	v_lshl_add_u64 v[68:69], v[250:251], 0, s[0:1]
	s_mov_b32 m0, s63
	s_nop 0
	global_load_lds_dwordx4 v[68:69], off
	s_waitcnt vmcnt(8)
	s_waitcnt lgkmcnt(0)
	s_barrier
	s_setprio 1
	s_waitcnt lgkmcnt(0)
	v_mfma_f32_16x16x32_bf16 v[68:71], v[182:185], v[104:107], v[134:137]
	v_mfma_f32_16x16x32_bf16 v[68:71], v[192:195], v[108:111], v[68:71]
	v_mfma_f32_16x16x32_bf16 v[72:75], v[196:199], v[104:107], v[138:141]
	v_mfma_f32_16x16x32_bf16 v[72:75], v[200:203], v[108:111], v[72:75]
	v_mfma_f32_16x16x32_bf16 v[80:83], v[196:199], v[112:115], v[146:149]
	v_mfma_f32_16x16x32_bf16 v[80:83], v[200:203], v[220:223], v[80:83]
	v_mfma_f32_16x16x32_bf16 v[76:79], v[182:185], v[112:115], v[142:145]
	v_mfma_f32_16x16x32_bf16 v[76:79], v[192:195], v[220:223], v[76:79]
	v_mfma_f32_16x16x32_bf16 v[84:87], v[182:185], v[224:227], v[150:153]
	v_mfma_f32_16x16x32_bf16 v[84:87], v[192:195], v[234:237], v[84:87]
	v_mfma_f32_16x16x32_bf16 v[88:91], v[196:199], v[224:227], v[154:157]
	v_mfma_f32_16x16x32_bf16 v[88:91], v[200:203], v[234:237], v[88:91]
	v_mfma_f32_16x16x32_bf16 v[96:99], v[196:199], v[238:241], v[162:165]
	v_mfma_f32_16x16x32_bf16 v[96:99], v[200:203], v[242:245], v[96:99]
	v_mfma_f32_16x16x32_bf16 v[92:95], v[182:185], v[238:241], v[158:161]
	v_mfma_f32_16x16x32_bf16 v[92:95], v[192:195], v[242:245], v[92:95]
	s_setprio 0
	s_setprio 1
	v_mfma_f32_16x16x32_bf16 v[100:103], v[204:207], v[104:107], v[116:119]
	v_mfma_f32_16x16x32_bf16 v[104:107], v[212:215], v[104:107], v[124:127]
	v_mfma_f32_16x16x32_bf16 v[100:103], v[208:211], v[108:111], v[100:103]
	v_mfma_f32_16x16x32_bf16 v[104:107], v[216:219], v[108:111], v[104:107]
	v_mfma_f32_16x16x32_bf16 v[108:111], v[204:207], v[112:115], v[166:169]
	v_mfma_f32_16x16x32_bf16 v[112:115], v[212:215], v[112:115], v[170:173]
	v_mfma_f32_16x16x32_bf16 v[116:119], v[204:207], v[224:227], v[174:177]
	v_mfma_f32_16x16x32_bf16 v[120:123], v[212:215], v[224:227], v[120:123]
	v_mfma_f32_16x16x32_bf16 v[124:127], v[204:207], v[238:241], v[178:181]
	v_mfma_f32_16x16x32_bf16 v[128:131], v[212:215], v[238:241], v[128:131]
	v_mfma_f32_16x16x32_bf16 v[108:111], v[208:211], v[220:223], v[108:111]
	v_mfma_f32_16x16x32_bf16 v[112:115], v[216:219], v[220:223], v[112:115]
	v_mfma_f32_16x16x32_bf16 v[116:119], v[208:211], v[234:237], v[116:119]
	v_mfma_f32_16x16x32_bf16 v[120:123], v[216:219], v[234:237], v[120:123]
	s_setprio 2
	s_barrier
	v_mfma_f32_16x16x32_bf16 v[124:127], v[208:211], v[242:245], v[124:127]
	v_mfma_f32_16x16x32_bf16 v[128:131], v[216:219], v[242:245], v[128:131]
	s_setprio 0
	s_add_i32 s42, s42, 2
	s_cmp_ge_i32 s42, s38
	s_cbranch_scc0 .LBB0_641
	v_mov_b32_e32 v192, v2
	s_branch .LBB0_644

.LBB0_749:
	s_add_i32 s47, 0, 0x10000
	s_add_i32 s49, 0, 0x14000
	v_add_u32_e32 v16, s47, v147
	v_add_u32_e32 v32, s49, v147
	ds_read_b128 v[4:7], v16
	ds_read_b128 v[8:11], v16 offset:1024
	ds_read_b128 v[12:15], v16 offset:2048
	ds_read_b128 v[16:19], v16 offset:3072
	ds_read_b128 v[20:23], v32
	ds_read_b128 v[24:27], v32 offset:1024
	ds_read_b128 v[28:31], v32 offset:2048
	ds_read_b128 v[32:35], v32 offset:3072
	v_add_u32_e32 v231, 0, v146
	ds_read_b128 v[36:39], v231
	ds_read_b128 v[40:43], v231 offset:1024
	ds_read_b128 v[44:47], v231 offset:2048
	ds_read_b128 v[48:51], v231 offset:3072
	ds_read_b128 v[52:55], v231 offset:4096
	ds_read_b128 v[56:59], v231 offset:5120
	ds_read_b128 v[60:63], v231 offset:6144
	ds_read_b128 v[64:67], v231 offset:7168
	s_waitcnt vmcnt(8)
	s_waitcnt lgkmcnt(0)
	s_barrier
	s_setprio 1
	s_waitcnt lgkmcnt(0)
	v_mfma_f32_16x16x32_f16 v[68:71], v[4:7], v[36:39], 0
	v_mfma_f32_16x16x32_f16 v[68:71], v[8:11], v[40:43], v[68:71]
	v_mfma_f32_16x16x32_f16 v[72:75], v[12:15], v[36:39], 0
	v_mfma_f32_16x16x32_f16 v[72:75], v[16:19], v[40:43], v[72:75]
	v_mfma_f32_16x16x32_f16 v[80:83], v[12:15], v[44:47], 0
	v_mfma_f32_16x16x32_f16 v[80:83], v[16:19], v[48:51], v[80:83]
	v_mfma_f32_16x16x32_f16 v[76:79], v[4:7], v[44:47], 0
	v_mfma_f32_16x16x32_f16 v[76:79], v[8:11], v[48:51], v[76:79]
	v_mfma_f32_16x16x32_f16 v[84:87], v[4:7], v[52:55], 0
	v_mfma_f32_16x16x32_f16 v[84:87], v[8:11], v[56:59], v[84:87]
	v_mfma_f32_16x16x32_f16 v[88:91], v[12:15], v[52:55], 0
	v_mfma_f32_16x16x32_f16 v[88:91], v[16:19], v[56:59], v[88:91]
	v_mfma_f32_16x16x32_f16 v[96:99], v[12:15], v[60:63], 0
	v_mfma_f32_16x16x32_f16 v[96:99], v[16:19], v[64:67], v[96:99]
	v_mfma_f32_16x16x32_f16 v[92:95], v[4:7], v[60:63], 0
	v_mfma_f32_16x16x32_f16 v[92:95], v[8:11], v[64:67], v[92:95]
	s_setprio 0
	s_setprio 1
	v_mfma_f32_16x16x32_f16 v[100:103], v[20:23], v[36:39], 0
	v_mfma_f32_16x16x32_f16 v[100:103], v[24:27], v[40:43], v[100:103]
	v_mfma_f32_16x16x32_f16 v[36:39], v[28:31], v[36:39], 0
	v_mfma_f32_16x16x32_f16 v[40:43], v[32:35], v[40:43], v[36:39]
	v_mfma_f32_16x16x32_f16 v[104:107], v[20:23], v[44:47], 0
	v_mfma_f32_16x16x32_f16 v[104:107], v[24:27], v[48:51], v[104:107]
	v_mfma_f32_16x16x32_f16 v[44:47], v[28:31], v[44:47], 0
	v_mfma_f32_16x16x32_f16 v[48:51], v[32:35], v[48:51], v[44:47]
	v_mfma_f32_16x16x32_f16 v[108:111], v[20:23], v[52:55], 0
	v_mfma_f32_16x16x32_f16 v[108:111], v[24:27], v[56:59], v[108:111]
	v_mfma_f32_16x16x32_f16 v[52:55], v[28:31], v[52:55], 0
	v_mfma_f32_16x16x32_f16 v[56:59], v[32:35], v[56:59], v[52:55]
	v_mfma_f32_16x16x32_f16 v[112:115], v[20:23], v[60:63], 0
	v_mfma_f32_16x16x32_f16 v[112:115], v[24:27], v[64:67], v[112:115]
	s_setprio 2
	s_barrier
	v_mfma_f32_16x16x32_f16 v[60:63], v[28:31], v[60:63], 0
	v_mfma_f32_16x16x32_f16 v[64:67], v[32:35], v[64:67], v[60:63]
	s_setprio 0
	v_lshl_add_u64 v[136:137], s[6:7], 0, v[2:3]
	s_add_i32 s47, s47, s62
	v_mov_b32_e32 v135, v3
	v_lshl_add_u64 v[140:141], v[136:137], 0, s[74:75]
	s_mov_b32 m0, s47
	v_lshl_add_u64 v[144:145], s[6:7], 0, v[134:135]
	ds_read_b128 v[36:39], v231 offset:16384
	ds_read_b128 v[44:47], v231 offset:17408
	ds_read_b128 v[52:55], v231 offset:18432
	ds_read_b128 v[60:63], v231 offset:19456
	ds_read_b128 v[116:119], v231 offset:20480
	ds_read_b128 v[120:123], v231 offset:21504
	ds_read_b128 v[124:127], v231 offset:22528
	ds_read_b128 v[128:131], v231 offset:23552
	global_load_lds_dwordx4 v[140:141], off
	v_lshl_add_u64 v[140:141], v[144:145], 0, s[74:75]
	s_add_i32 m0, s47, 0x2000
	s_add_i32 s47, s49, s62
	global_load_lds_dwordx4 v[140:141], off
	s_mov_b32 m0, s47
	v_mov_b32_e32 v139, v3
	global_load_lds_dwordx4 v2, s[16:17]
	s_add_i32 m0, s47, 0x2000
	v_lshl_add_u64 v[248:249], s[8:9], 0, v[138:139]
	v_mov_b32_e32 v133, v3
	global_load_lds_dwordx4 v134, s[16:17]
	v_lshl_add_u64 v[140:141], v[248:249], 0, s[74:75]
	s_mov_b32 m0, s63
	v_lshl_add_u64 v[250:251], s[8:9], 0, v[132:133]
	global_load_lds_dwordx4 v[140:141], off
	v_lshl_add_u64 v[140:141], v[250:251], 0, s[74:75]
	s_mov_b32 m0, s64
	s_nop 0
	global_load_lds_dwordx4 v[140:141], off
	s_waitcnt vmcnt(8)
	s_waitcnt lgkmcnt(0)
	s_barrier
	s_setprio 1
	s_waitcnt lgkmcnt(0)
	v_mfma_f32_16x16x32_f16 v[140:143], v[4:7], v[36:39], 0
	v_mfma_f32_16x16x32_f16 v[140:143], v[8:11], v[44:47], v[140:143]
	v_mfma_f32_16x16x32_f16 v[148:151], v[12:15], v[36:39], 0
	v_mfma_f32_16x16x32_f16 v[148:151], v[16:19], v[44:47], v[148:151]
	v_mfma_f32_16x16x32_f16 v[156:159], v[12:15], v[52:55], 0
	v_mfma_f32_16x16x32_f16 v[156:159], v[16:19], v[60:63], v[156:159]
	v_mfma_f32_16x16x32_f16 v[152:155], v[4:7], v[52:55], 0
	v_mfma_f32_16x16x32_f16 v[152:155], v[8:11], v[60:63], v[152:155]
	v_mfma_f32_16x16x32_f16 v[160:163], v[4:7], v[116:119], 0
	v_mfma_f32_16x16x32_f16 v[160:163], v[8:11], v[120:123], v[160:163]
	v_mfma_f32_16x16x32_f16 v[164:167], v[12:15], v[116:119], 0
	v_mfma_f32_16x16x32_f16 v[164:167], v[16:19], v[120:123], v[164:167]
	v_mfma_f32_16x16x32_f16 v[12:15], v[12:15], v[124:127], 0
	v_mfma_f32_16x16x32_f16 v[172:175], v[16:19], v[128:131], v[12:15]
	v_mfma_f32_16x16x32_f16 v[4:7], v[4:7], v[124:127], 0
	v_mfma_f32_16x16x32_f16 v[168:171], v[8:11], v[128:131], v[4:7]
	s_setprio 0
	s_setprio 1
	v_mfma_f32_16x16x32_f16 v[4:7], v[20:23], v[36:39], 0
	v_mfma_f32_16x16x32_f16 v[8:11], v[28:31], v[36:39], 0
	v_mfma_f32_16x16x32_f16 v[12:15], v[20:23], v[52:55], 0
	v_mfma_f32_16x16x32_f16 v[16:19], v[28:31], v[52:55], 0
	v_mfma_f32_16x16x32_f16 v[36:39], v[20:23], v[116:119], 0
	v_mfma_f32_16x16x32_f16 v[52:55], v[28:31], v[116:119], 0
	v_mfma_f32_16x16x32_f16 v[20:23], v[20:23], v[124:127], 0
	v_mfma_f32_16x16x32_f16 v[28:31], v[28:31], v[124:127], 0
	v_mfma_f32_16x16x32_f16 v[116:119], v[24:27], v[44:47], v[4:7]
	v_mfma_f32_16x16x32_f16 v[124:127], v[32:35], v[44:47], v[8:11]
	v_mfma_f32_16x16x32_f16 v[184:187], v[24:27], v[120:123], v[36:39]
	v_mfma_f32_16x16x32_f16 v[120:123], v[32:35], v[120:123], v[52:55]
	v_mfma_f32_16x16x32_f16 v[188:191], v[24:27], v[128:131], v[20:23]
	v_mfma_f32_16x16x32_f16 v[128:131], v[32:35], v[128:131], v[28:31]
	s_setprio 2
	s_barrier
	v_mfma_f32_16x16x32_f16 v[176:179], v[24:27], v[60:63], v[12:15]
	v_mfma_f32_16x16x32_f16 v[180:183], v[32:35], v[60:63], v[16:19]
	s_setprio 0
	s_add_i32 s47, 0, 0x18000
	v_add_u32_e32 v4, s47, v147
	s_add_i32 s49, 0, 0x1c000
	ds_read_b128 v[192:195], v4
	ds_read_b128 v[196:199], v4 offset:1024
	ds_read_b128 v[200:203], v4 offset:2048
	ds_read_b128 v[204:207], v4 offset:3072
	v_add_u32_e32 v4, s49, v147
	ds_read_b128 v[208:211], v4
	ds_read_b128 v[212:215], v4 offset:1024
	ds_read_b128 v[216:219], v4 offset:2048
	ds_read_b128 v[220:223], v4 offset:3072
	s_mov_b32 m0, s65
	ds_read_b128 v[44:47], v231 offset:32768
	ds_read_b128 v[52:55], v231 offset:33792
	ds_read_b128 v[60:63], v231 offset:34816
	ds_read_b128 v[224:227], v231 offset:35840
	ds_read_b128 v[232:235], v231 offset:36864
	ds_read_b128 v[236:239], v231 offset:37888
	ds_read_b128 v[240:243], v231 offset:38912
	ds_read_b128 v[244:247], v231 offset:39936
	global_load_lds_dwordx4 v138, s[26:27]
	s_mov_b32 m0, s66
	s_nop 0
	global_load_lds_dwordx4 v132, s[26:27]
	s_waitcnt vmcnt(8)
	s_waitcnt lgkmcnt(0)
	s_barrier
	s_setprio 1
	s_waitcnt lgkmcnt(0)
	v_mfma_f32_16x16x32_f16 v[4:7], v[192:195], v[44:47], v[68:71]
	v_mfma_f32_16x16x32_f16 v[4:7], v[196:199], v[52:55], v[4:7]
	v_mfma_f32_16x16x32_f16 v[8:11], v[200:203], v[44:47], v[72:75]
	v_mfma_f32_16x16x32_f16 v[8:11], v[204:207], v[52:55], v[8:11]
	v_mfma_f32_16x16x32_f16 v[16:19], v[200:203], v[60:63], v[80:83]
	v_mfma_f32_16x16x32_f16 v[16:19], v[204:207], v[224:227], v[16:19]
	v_mfma_f32_16x16x32_f16 v[12:15], v[192:195], v[60:63], v[76:79]
	v_mfma_f32_16x16x32_f16 v[12:15], v[196:199], v[224:227], v[12:15]
	v_mfma_f32_16x16x32_f16 v[20:23], v[192:195], v[232:235], v[84:87]
	v_mfma_f32_16x16x32_f16 v[20:23], v[196:199], v[236:239], v[20:23]
	v_mfma_f32_16x16x32_f16 v[24:27], v[200:203], v[232:235], v[88:91]
	v_mfma_f32_16x16x32_f16 v[24:27], v[204:207], v[236:239], v[24:27]
	v_mfma_f32_16x16x32_f16 v[32:35], v[200:203], v[240:243], v[96:99]
	v_mfma_f32_16x16x32_f16 v[32:35], v[204:207], v[244:247], v[32:35]
	v_mfma_f32_16x16x32_f16 v[28:31], v[192:195], v[240:243], v[92:95]
	v_mfma_f32_16x16x32_f16 v[28:31], v[196:199], v[244:247], v[28:31]
	s_setprio 0
	s_setprio 1
	v_mfma_f32_16x16x32_f16 v[36:39], v[208:211], v[44:47], v[100:103]
	v_mfma_f32_16x16x32_f16 v[40:43], v[216:219], v[44:47], v[40:43]
	v_mfma_f32_16x16x32_f16 v[36:39], v[212:215], v[52:55], v[36:39]
	v_mfma_f32_16x16x32_f16 v[40:43], v[220:223], v[52:55], v[40:43]
	v_mfma_f32_16x16x32_f16 v[44:47], v[208:211], v[60:63], v[104:107]
	v_mfma_f32_16x16x32_f16 v[48:51], v[216:219], v[60:63], v[48:51]
	v_mfma_f32_16x16x32_f16 v[52:55], v[208:211], v[232:235], v[108:111]
	v_mfma_f32_16x16x32_f16 v[56:59], v[216:219], v[232:235], v[56:59]
	v_mfma_f32_16x16x32_f16 v[60:63], v[208:211], v[240:243], v[112:115]
	v_mfma_f32_16x16x32_f16 v[64:67], v[216:219], v[240:243], v[64:67]
	v_mfma_f32_16x16x32_f16 v[44:47], v[212:215], v[224:227], v[44:47]
	v_mfma_f32_16x16x32_f16 v[48:51], v[220:223], v[224:227], v[48:51]
	v_mfma_f32_16x16x32_f16 v[52:55], v[212:215], v[236:239], v[52:55]
	v_mfma_f32_16x16x32_f16 v[56:59], v[220:223], v[236:239], v[56:59]
	s_setprio 2
	s_barrier
	v_mfma_f32_16x16x32_f16 v[60:63], v[212:215], v[244:247], v[60:63]
	v_mfma_f32_16x16x32_f16 v[64:67], v[220:223], v[244:247], v[64:67]
	s_setprio 0
	s_add_i32 s47, s47, s62
	v_lshl_add_u64 v[68:69], v[136:137], 0, s[24:25]
	s_mov_b32 m0, s47
	ds_read_b128 v[104:107], v231 offset:49152
	ds_read_b128 v[108:111], v231 offset:50176
	ds_read_b128 v[112:115], v231 offset:51200
	ds_read_b128 v[224:227], v231 offset:52224
	ds_read_b128 v[232:235], v231 offset:53248
	ds_read_b128 v[236:239], v231 offset:54272
	ds_read_b128 v[240:243], v231 offset:55296
	ds_read_b128 v[244:247], v231 offset:56320
	global_load_lds_dwordx4 v[68:69], off
	v_lshl_add_u64 v[68:69], v[144:145], 0, s[24:25]
	s_add_i32 m0, s47, 0x2000
	s_add_i32 s47, s49, s62
	global_load_lds_dwordx4 v[68:69], off
	s_mov_b32 m0, s47
	v_lshl_add_u64 v[68:69], v[248:249], 0, s[24:25]
	global_load_lds_dwordx4 v2, s[28:29]
	s_add_i32 m0, s47, 0x2000
	s_nop 0
	global_load_lds_dwordx4 v134, s[28:29]
	s_mov_b32 m0, s69
	s_nop 0
	global_load_lds_dwordx4 v[68:69], off
	v_lshl_add_u64 v[68:69], v[250:251], 0, s[24:25]
	s_mov_b32 m0, s70
	s_nop 0
	global_load_lds_dwordx4 v[68:69], off
	s_waitcnt vmcnt(8)
	s_waitcnt lgkmcnt(0)
	s_barrier
	s_setprio 1
	s_waitcnt lgkmcnt(0)
	v_mfma_f32_16x16x32_f16 v[68:71], v[192:195], v[104:107], v[140:143]
	v_mfma_f32_16x16x32_f16 v[68:71], v[196:199], v[108:111], v[68:71]
	v_mfma_f32_16x16x32_f16 v[72:75], v[200:203], v[104:107], v[148:151]
	v_mfma_f32_16x16x32_f16 v[72:75], v[204:207], v[108:111], v[72:75]
	v_mfma_f32_16x16x32_f16 v[80:83], v[200:203], v[112:115], v[156:159]
	v_mfma_f32_16x16x32_f16 v[80:83], v[204:207], v[224:227], v[80:83]
	v_mfma_f32_16x16x32_f16 v[76:79], v[192:195], v[112:115], v[152:155]
	v_mfma_f32_16x16x32_f16 v[76:79], v[196:199], v[224:227], v[76:79]
	v_mfma_f32_16x16x32_f16 v[84:87], v[192:195], v[232:235], v[160:163]
	v_mfma_f32_16x16x32_f16 v[84:87], v[196:199], v[236:239], v[84:87]
	v_mfma_f32_16x16x32_f16 v[88:91], v[200:203], v[232:235], v[164:167]
	v_mfma_f32_16x16x32_f16 v[88:91], v[204:207], v[236:239], v[88:91]
	v_mfma_f32_16x16x32_f16 v[96:99], v[200:203], v[240:243], v[172:175]
	v_mfma_f32_16x16x32_f16 v[96:99], v[204:207], v[244:247], v[96:99]
	v_mfma_f32_16x16x32_f16 v[92:95], v[192:195], v[240:243], v[168:171]
	v_mfma_f32_16x16x32_f16 v[92:95], v[196:199], v[244:247], v[92:95]
	s_setprio 0
	s_setprio 1
	v_mfma_f32_16x16x32_f16 v[100:103], v[208:211], v[104:107], v[116:119]
	v_mfma_f32_16x16x32_f16 v[104:107], v[216:219], v[104:107], v[124:127]
	v_mfma_f32_16x16x32_f16 v[100:103], v[212:215], v[108:111], v[100:103]
	v_mfma_f32_16x16x32_f16 v[104:107], v[220:223], v[108:111], v[104:107]
	v_mfma_f32_16x16x32_f16 v[108:111], v[208:211], v[112:115], v[176:179]
	v_mfma_f32_16x16x32_f16 v[112:115], v[216:219], v[112:115], v[180:183]
	v_mfma_f32_16x16x32_f16 v[116:119], v[208:211], v[232:235], v[184:187]
	v_mfma_f32_16x16x32_f16 v[120:123], v[216:219], v[232:235], v[120:123]
	v_mfma_f32_16x16x32_f16 v[124:127], v[208:211], v[240:243], v[188:191]
	v_mfma_f32_16x16x32_f16 v[128:131], v[216:219], v[240:243], v[128:131]
	v_mfma_f32_16x16x32_f16 v[108:111], v[212:215], v[224:227], v[108:111]
	v_mfma_f32_16x16x32_f16 v[112:115], v[220:223], v[224:227], v[112:115]
	v_mfma_f32_16x16x32_f16 v[116:119], v[212:215], v[236:239], v[116:119]
	v_mfma_f32_16x16x32_f16 v[120:123], v[220:223], v[236:239], v[120:123]
	s_setprio 2
	s_barrier
	v_mfma_f32_16x16x32_f16 v[124:127], v[212:215], v[244:247], v[124:127]
	v_mfma_f32_16x16x32_f16 v[128:131], v[220:223], v[244:247], v[128:131]
	s_setprio 0
	s_add_i32 s45, s45, 2
	s_cmp_ge_i32 s45, s44
	s_cbranch_scc0 .LBB0_749
	v_mov_b32_e32 v136, v2
	s_branch .LBB0_752

.LBB0_1175:
	s_add_i32 s61, 0, 0x10000
	s_add_i32 s79, 0, 0x14000
	v_add_u32_e32 v16, s61, v209
	v_add_u32_e32 v32, s79, v209
	ds_read_b128 v[4:7], v16
	ds_read_b128 v[8:11], v16 offset:1024
	ds_read_b128 v[12:15], v16 offset:2048
	ds_read_b128 v[16:19], v16 offset:3072
	ds_read_b128 v[20:23], v32
	ds_read_b128 v[24:27], v32 offset:1024
	ds_read_b128 v[28:31], v32 offset:2048
	ds_read_b128 v[32:35], v32 offset:3072
	v_add_u32_e32 v231, 0, v208
	ds_read_b128 v[36:39], v231
	ds_read_b128 v[40:43], v231 offset:1024
	ds_read_b128 v[44:47], v231 offset:2048
	ds_read_b128 v[48:51], v231 offset:3072
	ds_read_b128 v[52:55], v231 offset:4096
	ds_read_b128 v[56:59], v231 offset:5120
	ds_read_b128 v[60:63], v231 offset:6144
	ds_read_b128 v[64:67], v231 offset:7168
	s_waitcnt vmcnt(8)
	s_waitcnt lgkmcnt(0)
	s_barrier
	s_setprio 1
	s_waitcnt lgkmcnt(0)
	v_mfma_f32_16x16x32_bf16 v[68:71], v[4:7], v[36:39], 0
	v_mfma_f32_16x16x32_bf16 v[68:71], v[8:11], v[40:43], v[68:71]
	v_mfma_f32_16x16x32_bf16 v[72:75], v[12:15], v[36:39], 0
	v_mfma_f32_16x16x32_bf16 v[72:75], v[16:19], v[40:43], v[72:75]
	v_mfma_f32_16x16x32_bf16 v[80:83], v[12:15], v[44:47], 0
	v_mfma_f32_16x16x32_bf16 v[80:83], v[16:19], v[48:51], v[80:83]
	v_mfma_f32_16x16x32_bf16 v[76:79], v[4:7], v[44:47], 0
	v_mfma_f32_16x16x32_bf16 v[76:79], v[8:11], v[48:51], v[76:79]
	v_mfma_f32_16x16x32_bf16 v[84:87], v[4:7], v[52:55], 0
	v_mfma_f32_16x16x32_bf16 v[84:87], v[8:11], v[56:59], v[84:87]
	v_mfma_f32_16x16x32_bf16 v[88:91], v[12:15], v[52:55], 0
	v_mfma_f32_16x16x32_bf16 v[88:91], v[16:19], v[56:59], v[88:91]
	v_mfma_f32_16x16x32_bf16 v[96:99], v[12:15], v[60:63], 0
	v_mfma_f32_16x16x32_bf16 v[96:99], v[16:19], v[64:67], v[96:99]
	v_mfma_f32_16x16x32_bf16 v[92:95], v[4:7], v[60:63], 0
	v_mfma_f32_16x16x32_bf16 v[92:95], v[8:11], v[64:67], v[92:95]
	s_setprio 0
	s_setprio 1
	v_mfma_f32_16x16x32_bf16 v[100:103], v[20:23], v[36:39], 0
	v_mfma_f32_16x16x32_bf16 v[100:103], v[24:27], v[40:43], v[100:103]
	v_mfma_f32_16x16x32_bf16 v[36:39], v[28:31], v[36:39], 0
	v_mfma_f32_16x16x32_bf16 v[40:43], v[32:35], v[40:43], v[36:39]
	v_mfma_f32_16x16x32_bf16 v[104:107], v[20:23], v[44:47], 0
	v_mfma_f32_16x16x32_bf16 v[104:107], v[24:27], v[48:51], v[104:107]
	v_mfma_f32_16x16x32_bf16 v[44:47], v[28:31], v[44:47], 0
	v_mfma_f32_16x16x32_bf16 v[48:51], v[32:35], v[48:51], v[44:47]
	v_mfma_f32_16x16x32_bf16 v[108:111], v[20:23], v[52:55], 0
	v_mfma_f32_16x16x32_bf16 v[108:111], v[24:27], v[56:59], v[108:111]
	v_mfma_f32_16x16x32_bf16 v[52:55], v[28:31], v[52:55], 0
	v_mfma_f32_16x16x32_bf16 v[56:59], v[32:35], v[56:59], v[52:55]
	v_mfma_f32_16x16x32_bf16 v[112:115], v[20:23], v[60:63], 0
	v_mfma_f32_16x16x32_bf16 v[112:115], v[24:27], v[64:67], v[112:115]
	s_setprio 2
	s_barrier
	v_mfma_f32_16x16x32_bf16 v[60:63], v[28:31], v[60:63], 0
	v_mfma_f32_16x16x32_bf16 v[64:67], v[32:35], v[64:67], v[60:63]
	s_setprio 0
	v_lshl_add_u64 v[186:187], s[12:13], 0, v[2:3]
	s_add_i32 s61, s61, s36
	v_mov_b32_e32 v191, v3
	v_lshl_add_u64 v[134:135], v[186:187], 0, s[74:75]
	s_mov_b32 m0, s61
	v_lshl_add_u64 v[226:227], s[12:13], 0, v[190:191]
	ds_read_b128 v[36:39], v231 offset:16384
	ds_read_b128 v[44:47], v231 offset:17408
	ds_read_b128 v[52:55], v231 offset:18432
	ds_read_b128 v[60:63], v231 offset:19456
	ds_read_b128 v[116:119], v231 offset:20480
	ds_read_b128 v[120:123], v231 offset:21504
	ds_read_b128 v[124:127], v231 offset:22528
	ds_read_b128 v[128:131], v231 offset:23552
	global_load_lds_dwordx4 v[134:135], off
	v_lshl_add_u64 v[134:135], v[226:227], 0, s[74:75]
	s_add_i32 m0, s61, 0x2000
	s_add_i32 s61, s79, s36
	global_load_lds_dwordx4 v[134:135], off
	s_mov_b32 m0, s61
	v_mov_b32_e32 v133, v3
	global_load_lds_dwordx4 v2, s[16:17]
	s_add_i32 m0, s61, 0x2000
	v_lshl_add_u64 v[248:249], s[6:7], 0, v[132:133]
	v_mov_b32_e32 v189, v3
	global_load_lds_dwordx4 v190, s[16:17]
	v_lshl_add_u64 v[134:135], v[248:249], 0, s[74:75]
	s_mov_b32 m0, s37
	v_lshl_add_u64 v[250:251], s[6:7], 0, v[188:189]
	global_load_lds_dwordx4 v[134:135], off
	v_lshl_add_u64 v[134:135], v[250:251], 0, s[74:75]
	s_mov_b32 m0, s66
	s_nop 0
	global_load_lds_dwordx4 v[134:135], off
	s_waitcnt vmcnt(8)
	s_waitcnt lgkmcnt(0)
	s_barrier
	s_setprio 1
	s_waitcnt lgkmcnt(0)
	v_mfma_f32_16x16x32_bf16 v[134:137], v[4:7], v[36:39], 0
	v_mfma_f32_16x16x32_bf16 v[134:137], v[8:11], v[44:47], v[134:137]
	v_mfma_f32_16x16x32_bf16 v[138:141], v[12:15], v[36:39], 0
	v_mfma_f32_16x16x32_bf16 v[138:141], v[16:19], v[44:47], v[138:141]
	v_mfma_f32_16x16x32_bf16 v[146:149], v[12:15], v[52:55], 0
	v_mfma_f32_16x16x32_bf16 v[146:149], v[16:19], v[60:63], v[146:149]
	v_mfma_f32_16x16x32_bf16 v[142:145], v[4:7], v[52:55], 0
	v_mfma_f32_16x16x32_bf16 v[142:145], v[8:11], v[60:63], v[142:145]
	v_mfma_f32_16x16x32_bf16 v[150:153], v[4:7], v[116:119], 0
	v_mfma_f32_16x16x32_bf16 v[150:153], v[8:11], v[120:123], v[150:153]
	v_mfma_f32_16x16x32_bf16 v[154:157], v[12:15], v[116:119], 0
	v_mfma_f32_16x16x32_bf16 v[154:157], v[16:19], v[120:123], v[154:157]
	v_mfma_f32_16x16x32_bf16 v[12:15], v[12:15], v[124:127], 0
	v_mfma_f32_16x16x32_bf16 v[162:165], v[16:19], v[128:131], v[12:15]
	v_mfma_f32_16x16x32_bf16 v[4:7], v[4:7], v[124:127], 0
	v_mfma_f32_16x16x32_bf16 v[158:161], v[8:11], v[128:131], v[4:7]
	s_setprio 0
	s_setprio 1
	v_mfma_f32_16x16x32_bf16 v[4:7], v[20:23], v[36:39], 0
	v_mfma_f32_16x16x32_bf16 v[8:11], v[28:31], v[36:39], 0
	v_mfma_f32_16x16x32_bf16 v[12:15], v[20:23], v[52:55], 0
	v_mfma_f32_16x16x32_bf16 v[16:19], v[28:31], v[52:55], 0
	v_mfma_f32_16x16x32_bf16 v[36:39], v[20:23], v[116:119], 0
	v_mfma_f32_16x16x32_bf16 v[52:55], v[28:31], v[116:119], 0
	v_mfma_f32_16x16x32_bf16 v[20:23], v[20:23], v[124:127], 0
	v_mfma_f32_16x16x32_bf16 v[28:31], v[28:31], v[124:127], 0
	v_mfma_f32_16x16x32_bf16 v[116:119], v[24:27], v[44:47], v[4:7]
	v_mfma_f32_16x16x32_bf16 v[124:127], v[32:35], v[44:47], v[8:11]
	v_mfma_f32_16x16x32_bf16 v[174:177], v[24:27], v[120:123], v[36:39]
	v_mfma_f32_16x16x32_bf16 v[120:123], v[32:35], v[120:123], v[52:55]
	v_mfma_f32_16x16x32_bf16 v[178:181], v[24:27], v[128:131], v[20:23]
	v_mfma_f32_16x16x32_bf16 v[128:131], v[32:35], v[128:131], v[28:31]
	s_setprio 2
	s_barrier
	v_mfma_f32_16x16x32_bf16 v[166:169], v[24:27], v[60:63], v[12:15]
	v_mfma_f32_16x16x32_bf16 v[170:173], v[32:35], v[60:63], v[16:19]
	s_setprio 0
	s_add_i32 s61, 0, 0x18000
	v_add_u32_e32 v4, s61, v209
	s_add_i32 s79, 0, 0x1c000
	ds_read_b128 v[182:185], v4
	ds_read_b128 v[192:195], v4 offset:1024
	ds_read_b128 v[196:199], v4 offset:2048
	ds_read_b128 v[200:203], v4 offset:3072
	v_add_u32_e32 v4, s79, v209
	ds_read_b128 v[204:207], v4
	ds_read_b128 v[210:213], v4 offset:1024
	ds_read_b128 v[214:217], v4 offset:2048
	ds_read_b128 v[218:221], v4 offset:3072
	s_mov_b32 m0, s67
	ds_read_b128 v[44:47], v231 offset:32768
	ds_read_b128 v[52:55], v231 offset:33792
	ds_read_b128 v[60:63], v231 offset:34816
	ds_read_b128 v[222:225], v231 offset:35840
	ds_read_b128 v[232:235], v231 offset:36864
	ds_read_b128 v[236:239], v231 offset:37888
	ds_read_b128 v[240:243], v231 offset:38912
	ds_read_b128 v[244:247], v231 offset:39936
	global_load_lds_dwordx4 v132, s[26:27]
	s_mov_b32 m0, s68
	s_nop 0
	global_load_lds_dwordx4 v188, s[26:27]
	s_waitcnt vmcnt(8)
	s_waitcnt lgkmcnt(0)
	s_barrier
	s_setprio 1
	s_waitcnt lgkmcnt(0)
	v_mfma_f32_16x16x32_bf16 v[4:7], v[182:185], v[44:47], v[68:71]
	v_mfma_f32_16x16x32_bf16 v[4:7], v[192:195], v[52:55], v[4:7]
	v_mfma_f32_16x16x32_bf16 v[8:11], v[196:199], v[44:47], v[72:75]
	v_mfma_f32_16x16x32_bf16 v[8:11], v[200:203], v[52:55], v[8:11]
	v_mfma_f32_16x16x32_bf16 v[16:19], v[196:199], v[60:63], v[80:83]
	v_mfma_f32_16x16x32_bf16 v[16:19], v[200:203], v[222:225], v[16:19]
	v_mfma_f32_16x16x32_bf16 v[12:15], v[182:185], v[60:63], v[76:79]
	v_mfma_f32_16x16x32_bf16 v[12:15], v[192:195], v[222:225], v[12:15]
	v_mfma_f32_16x16x32_bf16 v[20:23], v[182:185], v[232:235], v[84:87]
	v_mfma_f32_16x16x32_bf16 v[20:23], v[192:195], v[236:239], v[20:23]
	v_mfma_f32_16x16x32_bf16 v[24:27], v[196:199], v[232:235], v[88:91]
	v_mfma_f32_16x16x32_bf16 v[24:27], v[200:203], v[236:239], v[24:27]
	v_mfma_f32_16x16x32_bf16 v[32:35], v[196:199], v[240:243], v[96:99]
	v_mfma_f32_16x16x32_bf16 v[32:35], v[200:203], v[244:247], v[32:35]
	v_mfma_f32_16x16x32_bf16 v[28:31], v[182:185], v[240:243], v[92:95]
	v_mfma_f32_16x16x32_bf16 v[28:31], v[192:195], v[244:247], v[28:31]
	s_setprio 0
	s_setprio 1
	v_mfma_f32_16x16x32_bf16 v[36:39], v[204:207], v[44:47], v[100:103]
	v_mfma_f32_16x16x32_bf16 v[40:43], v[214:217], v[44:47], v[40:43]
	v_mfma_f32_16x16x32_bf16 v[36:39], v[210:213], v[52:55], v[36:39]
	v_mfma_f32_16x16x32_bf16 v[40:43], v[218:221], v[52:55], v[40:43]
	v_mfma_f32_16x16x32_bf16 v[44:47], v[204:207], v[60:63], v[104:107]
	v_mfma_f32_16x16x32_bf16 v[48:51], v[214:217], v[60:63], v[48:51]
	v_mfma_f32_16x16x32_bf16 v[52:55], v[204:207], v[232:235], v[108:111]
	v_mfma_f32_16x16x32_bf16 v[56:59], v[214:217], v[232:235], v[56:59]
	v_mfma_f32_16x16x32_bf16 v[60:63], v[204:207], v[240:243], v[112:115]
	v_mfma_f32_16x16x32_bf16 v[64:67], v[214:217], v[240:243], v[64:67]
	v_mfma_f32_16x16x32_bf16 v[44:47], v[210:213], v[222:225], v[44:47]
	v_mfma_f32_16x16x32_bf16 v[48:51], v[218:221], v[222:225], v[48:51]
	v_mfma_f32_16x16x32_bf16 v[52:55], v[210:213], v[236:239], v[52:55]
	v_mfma_f32_16x16x32_bf16 v[56:59], v[218:221], v[236:239], v[56:59]
	s_setprio 2
	s_barrier
	v_mfma_f32_16x16x32_bf16 v[60:63], v[210:213], v[244:247], v[60:63]
	v_mfma_f32_16x16x32_bf16 v[64:67], v[218:221], v[244:247], v[64:67]
	s_setprio 0
	s_add_i32 s61, s61, s36
	v_lshl_add_u64 v[68:69], v[186:187], 0, s[24:25]
	s_mov_b32 m0, s61
	ds_read_b128 v[104:107], v231 offset:49152
	ds_read_b128 v[108:111], v231 offset:50176
	ds_read_b128 v[112:115], v231 offset:51200
	ds_read_b128 v[222:225], v231 offset:52224
	ds_read_b128 v[232:235], v231 offset:53248
	ds_read_b128 v[236:239], v231 offset:54272
	ds_read_b128 v[240:243], v231 offset:55296
	ds_read_b128 v[244:247], v231 offset:56320
	global_load_lds_dwordx4 v[68:69], off
	v_lshl_add_u64 v[68:69], v[226:227], 0, s[24:25]
	s_add_i32 m0, s61, 0x2000
	s_add_i32 s61, s79, s36
	global_load_lds_dwordx4 v[68:69], off
	s_mov_b32 m0, s61
	v_lshl_add_u64 v[68:69], v[248:249], 0, s[24:25]
	global_load_lds_dwordx4 v2, s[28:29]
	s_add_i32 m0, s61, 0x2000
	s_nop 0
	global_load_lds_dwordx4 v190, s[28:29]
	s_mov_b32 m0, s71
	s_nop 0
	global_load_lds_dwordx4 v[68:69], off
	v_lshl_add_u64 v[68:69], v[250:251], 0, s[24:25]
	s_mov_b32 m0, s72
	s_nop 0
	global_load_lds_dwordx4 v[68:69], off
	s_waitcnt vmcnt(8)
	s_waitcnt lgkmcnt(0)
	s_barrier
	s_setprio 1
	s_waitcnt lgkmcnt(0)
	v_mfma_f32_16x16x32_bf16 v[68:71], v[182:185], v[104:107], v[134:137]
	v_mfma_f32_16x16x32_bf16 v[68:71], v[192:195], v[108:111], v[68:71]
	v_mfma_f32_16x16x32_bf16 v[72:75], v[196:199], v[104:107], v[138:141]
	v_mfma_f32_16x16x32_bf16 v[72:75], v[200:203], v[108:111], v[72:75]
	v_mfma_f32_16x16x32_bf16 v[80:83], v[196:199], v[112:115], v[146:149]
	v_mfma_f32_16x16x32_bf16 v[80:83], v[200:203], v[222:225], v[80:83]
	v_mfma_f32_16x16x32_bf16 v[76:79], v[182:185], v[112:115], v[142:145]
	v_mfma_f32_16x16x32_bf16 v[76:79], v[192:195], v[222:225], v[76:79]
	v_mfma_f32_16x16x32_bf16 v[84:87], v[182:185], v[232:235], v[150:153]
	v_mfma_f32_16x16x32_bf16 v[84:87], v[192:195], v[236:239], v[84:87]
	v_mfma_f32_16x16x32_bf16 v[88:91], v[196:199], v[232:235], v[154:157]
	v_mfma_f32_16x16x32_bf16 v[88:91], v[200:203], v[236:239], v[88:91]
	v_mfma_f32_16x16x32_bf16 v[96:99], v[196:199], v[240:243], v[162:165]
	v_mfma_f32_16x16x32_bf16 v[96:99], v[200:203], v[244:247], v[96:99]
	v_mfma_f32_16x16x32_bf16 v[92:95], v[182:185], v[240:243], v[158:161]
	v_mfma_f32_16x16x32_bf16 v[92:95], v[192:195], v[244:247], v[92:95]
	s_setprio 0
	s_setprio 1
	v_mfma_f32_16x16x32_bf16 v[100:103], v[204:207], v[104:107], v[116:119]
	v_mfma_f32_16x16x32_bf16 v[104:107], v[214:217], v[104:107], v[124:127]
	v_mfma_f32_16x16x32_bf16 v[100:103], v[210:213], v[108:111], v[100:103]
	v_mfma_f32_16x16x32_bf16 v[104:107], v[218:221], v[108:111], v[104:107]
	v_mfma_f32_16x16x32_bf16 v[108:111], v[204:207], v[112:115], v[166:169]
	v_mfma_f32_16x16x32_bf16 v[112:115], v[214:217], v[112:115], v[170:173]
	v_mfma_f32_16x16x32_bf16 v[116:119], v[204:207], v[232:235], v[174:177]
	v_mfma_f32_16x16x32_bf16 v[120:123], v[214:217], v[232:235], v[120:123]
	v_mfma_f32_16x16x32_bf16 v[124:127], v[204:207], v[240:243], v[178:181]
	v_mfma_f32_16x16x32_bf16 v[128:131], v[214:217], v[240:243], v[128:131]
	v_mfma_f32_16x16x32_bf16 v[108:111], v[210:213], v[222:225], v[108:111]
	v_mfma_f32_16x16x32_bf16 v[112:115], v[218:221], v[222:225], v[112:115]
	v_mfma_f32_16x16x32_bf16 v[116:119], v[210:213], v[236:239], v[116:119]
	v_mfma_f32_16x16x32_bf16 v[120:123], v[218:221], v[236:239], v[120:123]
	s_setprio 2
	s_barrier
	v_mfma_f32_16x16x32_bf16 v[124:127], v[210:213], v[244:247], v[124:127]
	v_mfma_f32_16x16x32_bf16 v[128:131], v[218:221], v[244:247], v[128:131]
	s_setprio 0
	s_add_i32 s43, s43, 2
	s_cmp_ge_i32 s43, s42
	s_cbranch_scc0 .LBB0_1175

.LBB0_1625:
	s_add_i32 s51, 0, 0x10000
	s_add_i32 s72, 0, 0x14000
	v_add_u32_e32 v16, s51, v232
	v_add_u32_e32 v32, s72, v232
	ds_read_b128 v[4:7], v16
	ds_read_b128 v[8:11], v16 offset:1024
	ds_read_b128 v[12:15], v16 offset:2048
	ds_read_b128 v[16:19], v16 offset:3072
	ds_read_b128 v[20:23], v32
	ds_read_b128 v[24:27], v32 offset:1024
	ds_read_b128 v[28:31], v32 offset:2048
	ds_read_b128 v[32:35], v32 offset:3072
	v_add_u32_e32 v233, 0, v231
	ds_read_b128 v[36:39], v233
	ds_read_b128 v[40:43], v233 offset:1024
	ds_read_b128 v[44:47], v233 offset:2048
	ds_read_b128 v[48:51], v233 offset:3072
	ds_read_b128 v[52:55], v233 offset:4096
	ds_read_b128 v[56:59], v233 offset:5120
	ds_read_b128 v[60:63], v233 offset:6144
	ds_read_b128 v[64:67], v233 offset:7168
	s_waitcnt vmcnt(8)
	s_waitcnt lgkmcnt(0)
	s_barrier
	s_setprio 1
	s_waitcnt lgkmcnt(0)
	v_mfma_f32_16x16x32_bf16 v[68:71], v[4:7], v[36:39], 0
	v_mfma_f32_16x16x32_bf16 v[68:71], v[8:11], v[40:43], v[68:71]
	v_mfma_f32_16x16x32_bf16 v[72:75], v[12:15], v[36:39], 0
	v_mfma_f32_16x16x32_bf16 v[72:75], v[16:19], v[40:43], v[72:75]
	v_mfma_f32_16x16x32_bf16 v[80:83], v[12:15], v[44:47], 0
	v_mfma_f32_16x16x32_bf16 v[80:83], v[16:19], v[48:51], v[80:83]
	v_mfma_f32_16x16x32_bf16 v[76:79], v[4:7], v[44:47], 0
	v_mfma_f32_16x16x32_bf16 v[76:79], v[8:11], v[48:51], v[76:79]
	v_mfma_f32_16x16x32_bf16 v[84:87], v[4:7], v[52:55], 0
	v_mfma_f32_16x16x32_bf16 v[84:87], v[8:11], v[56:59], v[84:87]
	v_mfma_f32_16x16x32_bf16 v[88:91], v[12:15], v[52:55], 0
	v_mfma_f32_16x16x32_bf16 v[88:91], v[16:19], v[56:59], v[88:91]
	v_mfma_f32_16x16x32_bf16 v[96:99], v[12:15], v[60:63], 0
	v_mfma_f32_16x16x32_bf16 v[96:99], v[16:19], v[64:67], v[96:99]
	v_mfma_f32_16x16x32_bf16 v[92:95], v[4:7], v[60:63], 0
	v_mfma_f32_16x16x32_bf16 v[92:95], v[8:11], v[64:67], v[92:95]
	s_setprio 0
	s_setprio 1
	v_mfma_f32_16x16x32_bf16 v[100:103], v[20:23], v[36:39], 0
	v_mfma_f32_16x16x32_bf16 v[100:103], v[24:27], v[40:43], v[100:103]
	v_mfma_f32_16x16x32_bf16 v[36:39], v[28:31], v[36:39], 0
	v_mfma_f32_16x16x32_bf16 v[40:43], v[32:35], v[40:43], v[36:39]
	v_mfma_f32_16x16x32_bf16 v[104:107], v[20:23], v[44:47], 0
	v_mfma_f32_16x16x32_bf16 v[104:107], v[24:27], v[48:51], v[104:107]
	v_mfma_f32_16x16x32_bf16 v[44:47], v[28:31], v[44:47], 0
	v_mfma_f32_16x16x32_bf16 v[48:51], v[32:35], v[48:51], v[44:47]
	v_mfma_f32_16x16x32_bf16 v[108:111], v[20:23], v[52:55], 0
	v_mfma_f32_16x16x32_bf16 v[108:111], v[24:27], v[56:59], v[108:111]
	v_mfma_f32_16x16x32_bf16 v[52:55], v[28:31], v[52:55], 0
	v_mfma_f32_16x16x32_bf16 v[56:59], v[32:35], v[56:59], v[52:55]
	v_mfma_f32_16x16x32_bf16 v[112:115], v[20:23], v[60:63], 0
	v_mfma_f32_16x16x32_bf16 v[112:115], v[24:27], v[64:67], v[112:115]
	s_setprio 2
	s_barrier
	v_mfma_f32_16x16x32_bf16 v[60:63], v[28:31], v[60:63], 0
	v_mfma_f32_16x16x32_bf16 v[64:67], v[32:35], v[64:67], v[60:63]
	s_setprio 0
	v_lshl_add_u64 v[186:187], s[12:13], 0, v[2:3]
	s_add_i32 s51, s51, s56
	v_mov_b32_e32 v191, v3
	v_lshl_add_u64 v[134:135], v[186:187], 0, s[74:75]
	s_mov_b32 m0, s51
	v_lshl_add_u64 v[246:247], s[12:13], 0, v[190:191]
	ds_read_b128 v[36:39], v233 offset:16384
	ds_read_b128 v[44:47], v233 offset:17408
	ds_read_b128 v[52:55], v233 offset:18432
	ds_read_b128 v[60:63], v233 offset:19456
	ds_read_b128 v[116:119], v233 offset:20480
	ds_read_b128 v[120:123], v233 offset:21504
	ds_read_b128 v[124:127], v233 offset:22528
	ds_read_b128 v[128:131], v233 offset:23552
	global_load_lds_dwordx4 v[134:135], off
	v_lshl_add_u64 v[134:135], v[246:247], 0, s[74:75]
	s_add_i32 m0, s51, 0x2000
	s_add_i32 s51, s72, s56
	global_load_lds_dwordx4 v[134:135], off
	s_mov_b32 m0, s51
	v_mov_b32_e32 v133, v3
	global_load_lds_dwordx4 v2, s[16:17]
	s_add_i32 m0, s51, 0x2000
	v_lshl_add_u64 v[248:249], s[14:15], 0, v[132:133]
	v_mov_b32_e32 v189, v3
	global_load_lds_dwordx4 v190, s[16:17]
	v_lshl_add_u64 v[134:135], v[248:249], 0, s[74:75]
	s_mov_b32 m0, s57
	v_lshl_add_u64 v[250:251], s[14:15], 0, v[188:189]
	global_load_lds_dwordx4 v[134:135], off
	v_lshl_add_u64 v[134:135], v[250:251], 0, s[74:75]
	s_mov_b32 m0, s58
	s_nop 0
	global_load_lds_dwordx4 v[134:135], off
	s_waitcnt vmcnt(8)
	s_waitcnt lgkmcnt(0)
	s_barrier
	s_setprio 1
	s_waitcnt lgkmcnt(0)
	v_mfma_f32_16x16x32_bf16 v[134:137], v[4:7], v[36:39], 0
	v_mfma_f32_16x16x32_bf16 v[134:137], v[8:11], v[44:47], v[134:137]
	v_mfma_f32_16x16x32_bf16 v[138:141], v[12:15], v[36:39], 0
	v_mfma_f32_16x16x32_bf16 v[138:141], v[16:19], v[44:47], v[138:141]
	v_mfma_f32_16x16x32_bf16 v[146:149], v[12:15], v[52:55], 0
	v_mfma_f32_16x16x32_bf16 v[146:149], v[16:19], v[60:63], v[146:149]
	v_mfma_f32_16x16x32_bf16 v[142:145], v[4:7], v[52:55], 0
	v_mfma_f32_16x16x32_bf16 v[142:145], v[8:11], v[60:63], v[142:145]
	v_mfma_f32_16x16x32_bf16 v[150:153], v[4:7], v[116:119], 0
	v_mfma_f32_16x16x32_bf16 v[150:153], v[8:11], v[120:123], v[150:153]
	v_mfma_f32_16x16x32_bf16 v[154:157], v[12:15], v[116:119], 0
	v_mfma_f32_16x16x32_bf16 v[154:157], v[16:19], v[120:123], v[154:157]
	v_mfma_f32_16x16x32_bf16 v[12:15], v[12:15], v[124:127], 0
	v_mfma_f32_16x16x32_bf16 v[162:165], v[16:19], v[128:131], v[12:15]
	v_mfma_f32_16x16x32_bf16 v[4:7], v[4:7], v[124:127], 0
	v_mfma_f32_16x16x32_bf16 v[158:161], v[8:11], v[128:131], v[4:7]
	s_setprio 0
	s_setprio 1
	v_mfma_f32_16x16x32_bf16 v[4:7], v[20:23], v[36:39], 0
	v_mfma_f32_16x16x32_bf16 v[8:11], v[28:31], v[36:39], 0
	v_mfma_f32_16x16x32_bf16 v[12:15], v[20:23], v[52:55], 0
	v_mfma_f32_16x16x32_bf16 v[16:19], v[28:31], v[52:55], 0
	v_mfma_f32_16x16x32_bf16 v[36:39], v[20:23], v[116:119], 0
	v_mfma_f32_16x16x32_bf16 v[52:55], v[28:31], v[116:119], 0
	v_mfma_f32_16x16x32_bf16 v[20:23], v[20:23], v[124:127], 0
	v_mfma_f32_16x16x32_bf16 v[28:31], v[28:31], v[124:127], 0
	v_mfma_f32_16x16x32_bf16 v[116:119], v[24:27], v[44:47], v[4:7]
	v_mfma_f32_16x16x32_bf16 v[124:127], v[32:35], v[44:47], v[8:11]
	v_mfma_f32_16x16x32_bf16 v[174:177], v[24:27], v[120:123], v[36:39]
	v_mfma_f32_16x16x32_bf16 v[120:123], v[32:35], v[120:123], v[52:55]
	v_mfma_f32_16x16x32_bf16 v[178:181], v[24:27], v[128:131], v[20:23]
	v_mfma_f32_16x16x32_bf16 v[128:131], v[32:35], v[128:131], v[28:31]
	s_setprio 2
	s_barrier
	v_mfma_f32_16x16x32_bf16 v[166:169], v[24:27], v[60:63], v[12:15]
	v_mfma_f32_16x16x32_bf16 v[170:173], v[32:35], v[60:63], v[16:19]
	s_setprio 0
	s_add_i32 s51, 0, 0x18000
	v_add_u32_e32 v4, s51, v232
	s_add_i32 s72, 0, 0x1c000
	ds_read_b128 v[182:185], v4
	ds_read_b128 v[192:195], v4 offset:1024
	ds_read_b128 v[196:199], v4 offset:2048
	ds_read_b128 v[200:203], v4 offset:3072
	v_add_u32_e32 v4, s72, v232
	ds_read_b128 v[204:207], v4
	ds_read_b128 v[208:211], v4 offset:1024
	ds_read_b128 v[212:215], v4 offset:2048
	ds_read_b128 v[216:219], v4 offset:3072
	s_mov_b32 m0, s59
	ds_read_b128 v[44:47], v233 offset:32768
	ds_read_b128 v[52:55], v233 offset:33792
	ds_read_b128 v[60:63], v233 offset:34816
	ds_read_b128 v[220:223], v233 offset:35840
	ds_read_b128 v[224:227], v233 offset:36864
	ds_read_b128 v[234:237], v233 offset:37888
	ds_read_b128 v[238:241], v233 offset:38912
	ds_read_b128 v[242:245], v233 offset:39936
	global_load_lds_dwordx4 v132, s[26:27]
	s_mov_b32 m0, s60
	s_nop 0
	global_load_lds_dwordx4 v188, s[26:27]
	s_waitcnt vmcnt(8)
	s_waitcnt lgkmcnt(0)
	s_barrier
	s_setprio 1
	s_waitcnt lgkmcnt(0)
	v_mfma_f32_16x16x32_bf16 v[4:7], v[182:185], v[44:47], v[68:71]
	v_mfma_f32_16x16x32_bf16 v[4:7], v[192:195], v[52:55], v[4:7]
	v_mfma_f32_16x16x32_bf16 v[8:11], v[196:199], v[44:47], v[72:75]
	v_mfma_f32_16x16x32_bf16 v[8:11], v[200:203], v[52:55], v[8:11]
	v_mfma_f32_16x16x32_bf16 v[16:19], v[196:199], v[60:63], v[80:83]
	v_mfma_f32_16x16x32_bf16 v[16:19], v[200:203], v[220:223], v[16:19]
	v_mfma_f32_16x16x32_bf16 v[12:15], v[182:185], v[60:63], v[76:79]
	v_mfma_f32_16x16x32_bf16 v[12:15], v[192:195], v[220:223], v[12:15]
	v_mfma_f32_16x16x32_bf16 v[20:23], v[182:185], v[224:227], v[84:87]
	v_mfma_f32_16x16x32_bf16 v[20:23], v[192:195], v[234:237], v[20:23]
	v_mfma_f32_16x16x32_bf16 v[24:27], v[196:199], v[224:227], v[88:91]
	v_mfma_f32_16x16x32_bf16 v[24:27], v[200:203], v[234:237], v[24:27]
	v_mfma_f32_16x16x32_bf16 v[32:35], v[196:199], v[238:241], v[96:99]
	v_mfma_f32_16x16x32_bf16 v[32:35], v[200:203], v[242:245], v[32:35]
	v_mfma_f32_16x16x32_bf16 v[28:31], v[182:185], v[238:241], v[92:95]
	v_mfma_f32_16x16x32_bf16 v[28:31], v[192:195], v[242:245], v[28:31]
	s_setprio 0
	s_setprio 1
	v_mfma_f32_16x16x32_bf16 v[36:39], v[204:207], v[44:47], v[100:103]
	v_mfma_f32_16x16x32_bf16 v[40:43], v[212:215], v[44:47], v[40:43]
	v_mfma_f32_16x16x32_bf16 v[36:39], v[208:211], v[52:55], v[36:39]
	v_mfma_f32_16x16x32_bf16 v[40:43], v[216:219], v[52:55], v[40:43]
	v_mfma_f32_16x16x32_bf16 v[44:47], v[204:207], v[60:63], v[104:107]
	v_mfma_f32_16x16x32_bf16 v[48:51], v[212:215], v[60:63], v[48:51]
	v_mfma_f32_16x16x32_bf16 v[52:55], v[204:207], v[224:227], v[108:111]
	v_mfma_f32_16x16x32_bf16 v[56:59], v[212:215], v[224:227], v[56:59]
	v_mfma_f32_16x16x32_bf16 v[60:63], v[204:207], v[238:241], v[112:115]
	v_mfma_f32_16x16x32_bf16 v[64:67], v[212:215], v[238:241], v[64:67]
	v_mfma_f32_16x16x32_bf16 v[44:47], v[208:211], v[220:223], v[44:47]
	v_mfma_f32_16x16x32_bf16 v[48:51], v[216:219], v[220:223], v[48:51]
	v_mfma_f32_16x16x32_bf16 v[52:55], v[208:211], v[234:237], v[52:55]
	v_mfma_f32_16x16x32_bf16 v[56:59], v[216:219], v[234:237], v[56:59]
	s_setprio 2
	s_barrier
	v_mfma_f32_16x16x32_bf16 v[60:63], v[208:211], v[242:245], v[60:63]
	v_mfma_f32_16x16x32_bf16 v[64:67], v[216:219], v[242:245], v[64:67]
	s_setprio 0
	s_add_i32 s51, s51, s56
	v_lshl_add_u64 v[68:69], v[186:187], 0, s[24:25]
	s_mov_b32 m0, s51
	ds_read_b128 v[104:107], v233 offset:49152
	ds_read_b128 v[108:111], v233 offset:50176
	ds_read_b128 v[112:115], v233 offset:51200
	ds_read_b128 v[220:223], v233 offset:52224
	ds_read_b128 v[224:227], v233 offset:53248
	ds_read_b128 v[234:237], v233 offset:54272
	ds_read_b128 v[238:241], v233 offset:55296
	ds_read_b128 v[242:245], v233 offset:56320
	global_load_lds_dwordx4 v[68:69], off
	v_lshl_add_u64 v[68:69], v[246:247], 0, s[24:25]
	s_add_i32 m0, s51, 0x2000
	s_add_i32 s51, s72, s56
	global_load_lds_dwordx4 v[68:69], off
	s_mov_b32 m0, s51
	v_lshl_add_u64 v[68:69], v[248:249], 0, s[24:25]
	global_load_lds_dwordx4 v2, s[28:29]
	s_add_i32 m0, s51, 0x2000
	s_nop 0
	global_load_lds_dwordx4 v190, s[28:29]
	s_mov_b32 m0, s64
	s_nop 0
	global_load_lds_dwordx4 v[68:69], off
	v_lshl_add_u64 v[68:69], v[250:251], 0, s[24:25]
	s_mov_b32 m0, s65
	s_nop 0
	global_load_lds_dwordx4 v[68:69], off
	s_waitcnt vmcnt(8)
	s_waitcnt lgkmcnt(0)
	s_barrier
	s_setprio 1
	s_waitcnt lgkmcnt(0)
	v_mfma_f32_16x16x32_bf16 v[68:71], v[182:185], v[104:107], v[134:137]
	v_mfma_f32_16x16x32_bf16 v[68:71], v[192:195], v[108:111], v[68:71]
	v_mfma_f32_16x16x32_bf16 v[72:75], v[196:199], v[104:107], v[138:141]
	v_mfma_f32_16x16x32_bf16 v[72:75], v[200:203], v[108:111], v[72:75]
	v_mfma_f32_16x16x32_bf16 v[80:83], v[196:199], v[112:115], v[146:149]
	v_mfma_f32_16x16x32_bf16 v[80:83], v[200:203], v[220:223], v[80:83]
	v_mfma_f32_16x16x32_bf16 v[76:79], v[182:185], v[112:115], v[142:145]
	v_mfma_f32_16x16x32_bf16 v[76:79], v[192:195], v[220:223], v[76:79]
	v_mfma_f32_16x16x32_bf16 v[84:87], v[182:185], v[224:227], v[150:153]
	v_mfma_f32_16x16x32_bf16 v[84:87], v[192:195], v[234:237], v[84:87]
	v_mfma_f32_16x16x32_bf16 v[88:91], v[196:199], v[224:227], v[154:157]
	v_mfma_f32_16x16x32_bf16 v[88:91], v[200:203], v[234:237], v[88:91]
	v_mfma_f32_16x16x32_bf16 v[96:99], v[196:199], v[238:241], v[162:165]
	v_mfma_f32_16x16x32_bf16 v[96:99], v[200:203], v[242:245], v[96:99]
	v_mfma_f32_16x16x32_bf16 v[92:95], v[182:185], v[238:241], v[158:161]
	v_mfma_f32_16x16x32_bf16 v[92:95], v[192:195], v[242:245], v[92:95]
	s_setprio 0
	s_setprio 1
	v_mfma_f32_16x16x32_bf16 v[100:103], v[204:207], v[104:107], v[116:119]
	v_mfma_f32_16x16x32_bf16 v[104:107], v[212:215], v[104:107], v[124:127]
	v_mfma_f32_16x16x32_bf16 v[100:103], v[208:211], v[108:111], v[100:103]
	v_mfma_f32_16x16x32_bf16 v[104:107], v[216:219], v[108:111], v[104:107]
	v_mfma_f32_16x16x32_bf16 v[108:111], v[204:207], v[112:115], v[166:169]
	v_mfma_f32_16x16x32_bf16 v[112:115], v[212:215], v[112:115], v[170:173]
	v_mfma_f32_16x16x32_bf16 v[116:119], v[204:207], v[224:227], v[174:177]
	v_mfma_f32_16x16x32_bf16 v[120:123], v[212:215], v[224:227], v[120:123]
	v_mfma_f32_16x16x32_bf16 v[124:127], v[204:207], v[238:241], v[178:181]
	v_mfma_f32_16x16x32_bf16 v[128:131], v[212:215], v[238:241], v[128:131]
	v_mfma_f32_16x16x32_bf16 v[108:111], v[208:211], v[220:223], v[108:111]
	v_mfma_f32_16x16x32_bf16 v[112:115], v[216:219], v[220:223], v[112:115]
	v_mfma_f32_16x16x32_bf16 v[116:119], v[208:211], v[234:237], v[116:119]
	v_mfma_f32_16x16x32_bf16 v[120:123], v[216:219], v[234:237], v[120:123]
	s_setprio 2
	s_barrier
	v_mfma_f32_16x16x32_bf16 v[124:127], v[208:211], v[242:245], v[124:127]
	v_mfma_f32_16x16x32_bf16 v[128:131], v[216:219], v[242:245], v[128:131]
	s_setprio 0
	s_add_i32 s43, s43, 2
	s_cmp_ge_i32 s43, s42
	s_cbranch_scc0 .LBB0_1625
	v_mov_b32_e32 v192, v2
	s_branch .LBB0_1628

.LBB0_2065:
	s_add_i32 s51, 0, 0x10000
	s_add_i32 s71, 0, 0x14000
	v_add_u32_e32 v16, s51, v232
	v_add_u32_e32 v32, s71, v232
	ds_read_b128 v[4:7], v16
	ds_read_b128 v[8:11], v16 offset:1024
	ds_read_b128 v[12:15], v16 offset:2048
	ds_read_b128 v[16:19], v16 offset:3072
	ds_read_b128 v[20:23], v32
	ds_read_b128 v[24:27], v32 offset:1024
	ds_read_b128 v[28:31], v32 offset:2048
	ds_read_b128 v[32:35], v32 offset:3072
	v_add_u32_e32 v233, 0, v231
	ds_read_b128 v[36:39], v233
	ds_read_b128 v[40:43], v233 offset:1024
	ds_read_b128 v[44:47], v233 offset:2048
	ds_read_b128 v[48:51], v233 offset:3072
	ds_read_b128 v[52:55], v233 offset:4096
	ds_read_b128 v[56:59], v233 offset:5120
	ds_read_b128 v[60:63], v233 offset:6144
	ds_read_b128 v[64:67], v233 offset:7168
	s_waitcnt vmcnt(8)
	s_waitcnt lgkmcnt(0)
	s_barrier
	s_setprio 1
	s_waitcnt lgkmcnt(0)
	v_mfma_f32_16x16x32_bf16 v[68:71], v[4:7], v[36:39], 0
	v_mfma_f32_16x16x32_bf16 v[68:71], v[8:11], v[40:43], v[68:71]
	v_mfma_f32_16x16x32_bf16 v[72:75], v[12:15], v[36:39], 0
	v_mfma_f32_16x16x32_bf16 v[72:75], v[16:19], v[40:43], v[72:75]
	v_mfma_f32_16x16x32_bf16 v[80:83], v[12:15], v[44:47], 0
	v_mfma_f32_16x16x32_bf16 v[80:83], v[16:19], v[48:51], v[80:83]
	v_mfma_f32_16x16x32_bf16 v[76:79], v[4:7], v[44:47], 0
	v_mfma_f32_16x16x32_bf16 v[76:79], v[8:11], v[48:51], v[76:79]
	v_mfma_f32_16x16x32_bf16 v[84:87], v[4:7], v[52:55], 0
	v_mfma_f32_16x16x32_bf16 v[84:87], v[8:11], v[56:59], v[84:87]
	v_mfma_f32_16x16x32_bf16 v[88:91], v[12:15], v[52:55], 0
	v_mfma_f32_16x16x32_bf16 v[88:91], v[16:19], v[56:59], v[88:91]
	v_mfma_f32_16x16x32_bf16 v[96:99], v[12:15], v[60:63], 0
	v_mfma_f32_16x16x32_bf16 v[96:99], v[16:19], v[64:67], v[96:99]
	v_mfma_f32_16x16x32_bf16 v[92:95], v[4:7], v[60:63], 0
	v_mfma_f32_16x16x32_bf16 v[92:95], v[8:11], v[64:67], v[92:95]
	s_setprio 0
	s_setprio 1
	v_mfma_f32_16x16x32_bf16 v[100:103], v[20:23], v[36:39], 0
	v_mfma_f32_16x16x32_bf16 v[100:103], v[24:27], v[40:43], v[100:103]
	v_mfma_f32_16x16x32_bf16 v[36:39], v[28:31], v[36:39], 0
	v_mfma_f32_16x16x32_bf16 v[40:43], v[32:35], v[40:43], v[36:39]
	v_mfma_f32_16x16x32_bf16 v[104:107], v[20:23], v[44:47], 0
	v_mfma_f32_16x16x32_bf16 v[104:107], v[24:27], v[48:51], v[104:107]
	v_mfma_f32_16x16x32_bf16 v[44:47], v[28:31], v[44:47], 0
	v_mfma_f32_16x16x32_bf16 v[48:51], v[32:35], v[48:51], v[44:47]
	v_mfma_f32_16x16x32_bf16 v[108:111], v[20:23], v[52:55], 0
	v_mfma_f32_16x16x32_bf16 v[108:111], v[24:27], v[56:59], v[108:111]
	v_mfma_f32_16x16x32_bf16 v[52:55], v[28:31], v[52:55], 0
	v_mfma_f32_16x16x32_bf16 v[56:59], v[32:35], v[56:59], v[52:55]
	v_mfma_f32_16x16x32_bf16 v[112:115], v[20:23], v[60:63], 0
	v_mfma_f32_16x16x32_bf16 v[112:115], v[24:27], v[64:67], v[112:115]
	s_setprio 2
	s_barrier
	v_mfma_f32_16x16x32_bf16 v[60:63], v[28:31], v[60:63], 0
	v_mfma_f32_16x16x32_bf16 v[64:67], v[32:35], v[64:67], v[60:63]
	s_setprio 0
	v_lshl_add_u64 v[186:187], s[12:13], 0, v[2:3]
	s_add_i32 s51, s51, s38
	v_mov_b32_e32 v191, v3
	v_lshl_add_u64 v[134:135], v[186:187], 0, s[74:75]
	s_mov_b32 m0, s51
	v_lshl_add_u64 v[246:247], s[12:13], 0, v[190:191]
	ds_read_b128 v[36:39], v233 offset:16384
	ds_read_b128 v[44:47], v233 offset:17408
	ds_read_b128 v[52:55], v233 offset:18432
	ds_read_b128 v[60:63], v233 offset:19456
	ds_read_b128 v[116:119], v233 offset:20480
	ds_read_b128 v[120:123], v233 offset:21504
	ds_read_b128 v[124:127], v233 offset:22528
	ds_read_b128 v[128:131], v233 offset:23552
	global_load_lds_dwordx4 v[134:135], off
	v_lshl_add_u64 v[134:135], v[246:247], 0, s[74:75]
	s_add_i32 m0, s51, 0x2000
	s_add_i32 s51, s71, s38
	global_load_lds_dwordx4 v[134:135], off
	s_mov_b32 m0, s51
	v_mov_b32_e32 v133, v3
	global_load_lds_dwordx4 v2, s[16:17]
	s_add_i32 m0, s51, 0x2000
	v_lshl_add_u64 v[248:249], s[14:15], 0, v[132:133]
	v_mov_b32_e32 v189, v3
	global_load_lds_dwordx4 v190, s[16:17]
	v_lshl_add_u64 v[134:135], v[248:249], 0, s[74:75]
	s_mov_b32 m0, s56
	v_lshl_add_u64 v[250:251], s[14:15], 0, v[188:189]
	global_load_lds_dwordx4 v[134:135], off
	v_lshl_add_u64 v[134:135], v[250:251], 0, s[74:75]
	s_mov_b32 m0, s57
	s_nop 0
	global_load_lds_dwordx4 v[134:135], off
	s_waitcnt vmcnt(8)
	s_waitcnt lgkmcnt(0)
	s_barrier
	s_setprio 1
	s_waitcnt lgkmcnt(0)
	v_mfma_f32_16x16x32_bf16 v[134:137], v[4:7], v[36:39], 0
	v_mfma_f32_16x16x32_bf16 v[134:137], v[8:11], v[44:47], v[134:137]
	v_mfma_f32_16x16x32_bf16 v[138:141], v[12:15], v[36:39], 0
	v_mfma_f32_16x16x32_bf16 v[138:141], v[16:19], v[44:47], v[138:141]
	v_mfma_f32_16x16x32_bf16 v[146:149], v[12:15], v[52:55], 0
	v_mfma_f32_16x16x32_bf16 v[146:149], v[16:19], v[60:63], v[146:149]
	v_mfma_f32_16x16x32_bf16 v[142:145], v[4:7], v[52:55], 0
	v_mfma_f32_16x16x32_bf16 v[142:145], v[8:11], v[60:63], v[142:145]
	v_mfma_f32_16x16x32_bf16 v[150:153], v[4:7], v[116:119], 0
	v_mfma_f32_16x16x32_bf16 v[150:153], v[8:11], v[120:123], v[150:153]
	v_mfma_f32_16x16x32_bf16 v[154:157], v[12:15], v[116:119], 0
	v_mfma_f32_16x16x32_bf16 v[154:157], v[16:19], v[120:123], v[154:157]
	v_mfma_f32_16x16x32_bf16 v[12:15], v[12:15], v[124:127], 0
	v_mfma_f32_16x16x32_bf16 v[162:165], v[16:19], v[128:131], v[12:15]
	v_mfma_f32_16x16x32_bf16 v[4:7], v[4:7], v[124:127], 0
	v_mfma_f32_16x16x32_bf16 v[158:161], v[8:11], v[128:131], v[4:7]
	s_setprio 0
	s_setprio 1
	v_mfma_f32_16x16x32_bf16 v[4:7], v[20:23], v[36:39], 0
	v_mfma_f32_16x16x32_bf16 v[8:11], v[28:31], v[36:39], 0
	v_mfma_f32_16x16x32_bf16 v[12:15], v[20:23], v[52:55], 0
	v_mfma_f32_16x16x32_bf16 v[16:19], v[28:31], v[52:55], 0
	v_mfma_f32_16x16x32_bf16 v[36:39], v[20:23], v[116:119], 0
	v_mfma_f32_16x16x32_bf16 v[52:55], v[28:31], v[116:119], 0
	v_mfma_f32_16x16x32_bf16 v[20:23], v[20:23], v[124:127], 0
	v_mfma_f32_16x16x32_bf16 v[28:31], v[28:31], v[124:127], 0
	v_mfma_f32_16x16x32_bf16 v[116:119], v[24:27], v[44:47], v[4:7]
	v_mfma_f32_16x16x32_bf16 v[124:127], v[32:35], v[44:47], v[8:11]
	v_mfma_f32_16x16x32_bf16 v[174:177], v[24:27], v[120:123], v[36:39]
	v_mfma_f32_16x16x32_bf16 v[120:123], v[32:35], v[120:123], v[52:55]
	v_mfma_f32_16x16x32_bf16 v[178:181], v[24:27], v[128:131], v[20:23]
	v_mfma_f32_16x16x32_bf16 v[128:131], v[32:35], v[128:131], v[28:31]
	s_setprio 2
	s_barrier
	v_mfma_f32_16x16x32_bf16 v[166:169], v[24:27], v[60:63], v[12:15]
	v_mfma_f32_16x16x32_bf16 v[170:173], v[32:35], v[60:63], v[16:19]
	s_setprio 0
	s_add_i32 s51, 0, 0x18000
	v_add_u32_e32 v4, s51, v232
	s_add_i32 s71, 0, 0x1c000
	ds_read_b128 v[182:185], v4
	ds_read_b128 v[192:195], v4 offset:1024
	ds_read_b128 v[196:199], v4 offset:2048
	ds_read_b128 v[200:203], v4 offset:3072
	v_add_u32_e32 v4, s71, v232
	ds_read_b128 v[204:207], v4
	ds_read_b128 v[208:211], v4 offset:1024
	ds_read_b128 v[212:215], v4 offset:2048
	ds_read_b128 v[216:219], v4 offset:3072
	s_mov_b32 m0, s58
	ds_read_b128 v[44:47], v233 offset:32768
	ds_read_b128 v[52:55], v233 offset:33792
	ds_read_b128 v[60:63], v233 offset:34816
	ds_read_b128 v[220:223], v233 offset:35840
	ds_read_b128 v[224:227], v233 offset:36864
	ds_read_b128 v[234:237], v233 offset:37888
	ds_read_b128 v[238:241], v233 offset:38912
	ds_read_b128 v[242:245], v233 offset:39936
	global_load_lds_dwordx4 v132, s[26:27]
	s_mov_b32 m0, s59
	s_nop 0
	global_load_lds_dwordx4 v188, s[26:27]
	s_waitcnt vmcnt(8)
	s_waitcnt lgkmcnt(0)
	s_barrier
	s_setprio 1
	s_waitcnt lgkmcnt(0)
	v_mfma_f32_16x16x32_bf16 v[4:7], v[182:185], v[44:47], v[68:71]
	v_mfma_f32_16x16x32_bf16 v[4:7], v[192:195], v[52:55], v[4:7]
	v_mfma_f32_16x16x32_bf16 v[8:11], v[196:199], v[44:47], v[72:75]
	v_mfma_f32_16x16x32_bf16 v[8:11], v[200:203], v[52:55], v[8:11]
	v_mfma_f32_16x16x32_bf16 v[16:19], v[196:199], v[60:63], v[80:83]
	v_mfma_f32_16x16x32_bf16 v[16:19], v[200:203], v[220:223], v[16:19]
	v_mfma_f32_16x16x32_bf16 v[12:15], v[182:185], v[60:63], v[76:79]
	v_mfma_f32_16x16x32_bf16 v[12:15], v[192:195], v[220:223], v[12:15]
	v_mfma_f32_16x16x32_bf16 v[20:23], v[182:185], v[224:227], v[84:87]
	v_mfma_f32_16x16x32_bf16 v[20:23], v[192:195], v[234:237], v[20:23]
	v_mfma_f32_16x16x32_bf16 v[24:27], v[196:199], v[224:227], v[88:91]
	v_mfma_f32_16x16x32_bf16 v[24:27], v[200:203], v[234:237], v[24:27]
	v_mfma_f32_16x16x32_bf16 v[32:35], v[196:199], v[238:241], v[96:99]
	v_mfma_f32_16x16x32_bf16 v[32:35], v[200:203], v[242:245], v[32:35]
	v_mfma_f32_16x16x32_bf16 v[28:31], v[182:185], v[238:241], v[92:95]
	v_mfma_f32_16x16x32_bf16 v[28:31], v[192:195], v[242:245], v[28:31]
	s_setprio 0
	s_setprio 1
	v_mfma_f32_16x16x32_bf16 v[36:39], v[204:207], v[44:47], v[100:103]
	v_mfma_f32_16x16x32_bf16 v[40:43], v[212:215], v[44:47], v[40:43]
	v_mfma_f32_16x16x32_bf16 v[36:39], v[208:211], v[52:55], v[36:39]
	v_mfma_f32_16x16x32_bf16 v[40:43], v[216:219], v[52:55], v[40:43]
	v_mfma_f32_16x16x32_bf16 v[44:47], v[204:207], v[60:63], v[104:107]
	v_mfma_f32_16x16x32_bf16 v[48:51], v[212:215], v[60:63], v[48:51]
	v_mfma_f32_16x16x32_bf16 v[52:55], v[204:207], v[224:227], v[108:111]
	v_mfma_f32_16x16x32_bf16 v[56:59], v[212:215], v[224:227], v[56:59]
	v_mfma_f32_16x16x32_bf16 v[60:63], v[204:207], v[238:241], v[112:115]
	v_mfma_f32_16x16x32_bf16 v[64:67], v[212:215], v[238:241], v[64:67]
	v_mfma_f32_16x16x32_bf16 v[44:47], v[208:211], v[220:223], v[44:47]
	v_mfma_f32_16x16x32_bf16 v[48:51], v[216:219], v[220:223], v[48:51]
	v_mfma_f32_16x16x32_bf16 v[52:55], v[208:211], v[234:237], v[52:55]
	v_mfma_f32_16x16x32_bf16 v[56:59], v[216:219], v[234:237], v[56:59]
	s_setprio 2
	s_barrier
	v_mfma_f32_16x16x32_bf16 v[60:63], v[208:211], v[242:245], v[60:63]
	v_mfma_f32_16x16x32_bf16 v[64:67], v[216:219], v[242:245], v[64:67]
	s_setprio 0
	s_add_i32 s51, s51, s38
	v_lshl_add_u64 v[68:69], v[186:187], 0, s[24:25]
	s_mov_b32 m0, s51
	ds_read_b128 v[104:107], v233 offset:49152
	ds_read_b128 v[108:111], v233 offset:50176
	ds_read_b128 v[112:115], v233 offset:51200
	ds_read_b128 v[220:223], v233 offset:52224
	ds_read_b128 v[224:227], v233 offset:53248
	ds_read_b128 v[234:237], v233 offset:54272
	ds_read_b128 v[238:241], v233 offset:55296
	ds_read_b128 v[242:245], v233 offset:56320
	global_load_lds_dwordx4 v[68:69], off
	v_lshl_add_u64 v[68:69], v[246:247], 0, s[24:25]
	s_add_i32 m0, s51, 0x2000
	s_add_i32 s51, s71, s38
	global_load_lds_dwordx4 v[68:69], off
	s_mov_b32 m0, s51
	v_lshl_add_u64 v[68:69], v[248:249], 0, s[24:25]
	global_load_lds_dwordx4 v2, s[28:29]
	s_add_i32 m0, s51, 0x2000
	s_nop 0
	global_load_lds_dwordx4 v190, s[28:29]
	s_mov_b32 m0, s63
	s_nop 0
	global_load_lds_dwordx4 v[68:69], off
	v_lshl_add_u64 v[68:69], v[250:251], 0, s[24:25]
	s_mov_b32 m0, s64
	s_nop 0
	global_load_lds_dwordx4 v[68:69], off
	s_waitcnt vmcnt(8)
	s_waitcnt lgkmcnt(0)
	s_barrier
	s_setprio 1
	s_waitcnt lgkmcnt(0)
	v_mfma_f32_16x16x32_bf16 v[68:71], v[182:185], v[104:107], v[134:137]
	v_mfma_f32_16x16x32_bf16 v[68:71], v[192:195], v[108:111], v[68:71]
	v_mfma_f32_16x16x32_bf16 v[72:75], v[196:199], v[104:107], v[138:141]
	v_mfma_f32_16x16x32_bf16 v[72:75], v[200:203], v[108:111], v[72:75]
	v_mfma_f32_16x16x32_bf16 v[80:83], v[196:199], v[112:115], v[146:149]
	v_mfma_f32_16x16x32_bf16 v[80:83], v[200:203], v[220:223], v[80:83]
	v_mfma_f32_16x16x32_bf16 v[76:79], v[182:185], v[112:115], v[142:145]
	v_mfma_f32_16x16x32_bf16 v[76:79], v[192:195], v[220:223], v[76:79]
	v_mfma_f32_16x16x32_bf16 v[84:87], v[182:185], v[224:227], v[150:153]
	v_mfma_f32_16x16x32_bf16 v[84:87], v[192:195], v[234:237], v[84:87]
	v_mfma_f32_16x16x32_bf16 v[88:91], v[196:199], v[224:227], v[154:157]
	v_mfma_f32_16x16x32_bf16 v[88:91], v[200:203], v[234:237], v[88:91]
	v_mfma_f32_16x16x32_bf16 v[96:99], v[196:199], v[238:241], v[162:165]
	v_mfma_f32_16x16x32_bf16 v[96:99], v[200:203], v[242:245], v[96:99]
	v_mfma_f32_16x16x32_bf16 v[92:95], v[182:185], v[238:241], v[158:161]
	v_mfma_f32_16x16x32_bf16 v[92:95], v[192:195], v[242:245], v[92:95]
	s_setprio 0
	s_setprio 1
	v_mfma_f32_16x16x32_bf16 v[100:103], v[204:207], v[104:107], v[116:119]
	v_mfma_f32_16x16x32_bf16 v[104:107], v[212:215], v[104:107], v[124:127]
	v_mfma_f32_16x16x32_bf16 v[100:103], v[208:211], v[108:111], v[100:103]
	v_mfma_f32_16x16x32_bf16 v[104:107], v[216:219], v[108:111], v[104:107]
	v_mfma_f32_16x16x32_bf16 v[108:111], v[204:207], v[112:115], v[166:169]
	v_mfma_f32_16x16x32_bf16 v[112:115], v[212:215], v[112:115], v[170:173]
	v_mfma_f32_16x16x32_bf16 v[116:119], v[204:207], v[224:227], v[174:177]
	v_mfma_f32_16x16x32_bf16 v[120:123], v[212:215], v[224:227], v[120:123]
	v_mfma_f32_16x16x32_bf16 v[124:127], v[204:207], v[238:241], v[178:181]
	v_mfma_f32_16x16x32_bf16 v[128:131], v[212:215], v[238:241], v[128:131]
	v_mfma_f32_16x16x32_bf16 v[108:111], v[208:211], v[220:223], v[108:111]
	v_mfma_f32_16x16x32_bf16 v[112:115], v[216:219], v[220:223], v[112:115]
	v_mfma_f32_16x16x32_bf16 v[116:119], v[208:211], v[234:237], v[116:119]
	v_mfma_f32_16x16x32_bf16 v[120:123], v[216:219], v[234:237], v[120:123]
	s_setprio 2
	s_barrier
	v_mfma_f32_16x16x32_bf16 v[124:127], v[208:211], v[242:245], v[124:127]
	v_mfma_f32_16x16x32_bf16 v[128:131], v[216:219], v[242:245], v[128:131]
	s_setprio 0
	s_add_i32 s45, s45, 2
	s_cmp_ge_i32 s45, s44
	s_cbranch_scc0 .LBB0_2065
	v_mov_b32_e32 v192, v2
	s_branch .LBB0_2068

.LBB0_2159:
	s_add_i32 s68, 0, 0x10000
	s_add_i32 s69, 0, 0x14000
	v_add_u32_e32 v16, s68, v143
	v_add_u32_e32 v32, s69, v143
	ds_read_b128 v[4:7], v16
	ds_read_b128 v[8:11], v16 offset:1024
	ds_read_b128 v[12:15], v16 offset:2048
	ds_read_b128 v[16:19], v16 offset:3072
	ds_read_b128 v[20:23], v32
	ds_read_b128 v[24:27], v32 offset:1024
	ds_read_b128 v[28:31], v32 offset:2048
	ds_read_b128 v[32:35], v32 offset:3072
	v_add_u32_e32 v231, 0, v142
	ds_read_b128 v[36:39], v231
	ds_read_b128 v[40:43], v231 offset:1024
	ds_read_b128 v[44:47], v231 offset:2048
	ds_read_b128 v[48:51], v231 offset:3072
	ds_read_b128 v[52:55], v231 offset:4096
	ds_read_b128 v[56:59], v231 offset:5120
	ds_read_b128 v[60:63], v231 offset:6144
	ds_read_b128 v[64:67], v231 offset:7168
	s_waitcnt vmcnt(8)
	s_waitcnt lgkmcnt(0)
	s_barrier
	s_setprio 1
	s_waitcnt lgkmcnt(0)
	v_mfma_f32_16x16x32_f16 v[68:71], v[4:7], v[36:39], 0
	v_mfma_f32_16x16x32_f16 v[68:71], v[8:11], v[40:43], v[68:71]
	v_mfma_f32_16x16x32_f16 v[72:75], v[12:15], v[36:39], 0
	v_mfma_f32_16x16x32_f16 v[72:75], v[16:19], v[40:43], v[72:75]
	v_mfma_f32_16x16x32_f16 v[80:83], v[12:15], v[44:47], 0
	v_mfma_f32_16x16x32_f16 v[80:83], v[16:19], v[48:51], v[80:83]
	v_mfma_f32_16x16x32_f16 v[76:79], v[4:7], v[44:47], 0
	v_mfma_f32_16x16x32_f16 v[76:79], v[8:11], v[48:51], v[76:79]
	v_mfma_f32_16x16x32_f16 v[84:87], v[4:7], v[52:55], 0
	v_mfma_f32_16x16x32_f16 v[84:87], v[8:11], v[56:59], v[84:87]
	v_mfma_f32_16x16x32_f16 v[88:91], v[12:15], v[52:55], 0
	v_mfma_f32_16x16x32_f16 v[88:91], v[16:19], v[56:59], v[88:91]
	v_mfma_f32_16x16x32_f16 v[96:99], v[12:15], v[60:63], 0
	v_mfma_f32_16x16x32_f16 v[100:103], v[16:19], v[64:67], v[96:99]
	v_mfma_f32_16x16x32_f16 v[92:95], v[4:7], v[60:63], 0
	v_mfma_f32_16x16x32_f16 v[92:95], v[8:11], v[64:67], v[92:95]
	s_setprio 0
	s_setprio 1
	v_mfma_f32_16x16x32_f16 v[96:99], v[20:23], v[36:39], 0
	v_mfma_f32_16x16x32_f16 v[116:119], v[24:27], v[40:43], v[96:99]
	v_mfma_f32_16x16x32_f16 v[36:39], v[28:31], v[36:39], 0
	v_mfma_f32_16x16x32_f16 v[36:39], v[32:35], v[40:43], v[36:39]
	v_mfma_f32_16x16x32_f16 v[104:107], v[20:23], v[44:47], 0
	v_mfma_f32_16x16x32_f16 v[40:43], v[24:27], v[48:51], v[104:107]
	v_mfma_f32_16x16x32_f16 v[44:47], v[28:31], v[44:47], 0
	v_mfma_f32_16x16x32_f16 v[44:47], v[32:35], v[48:51], v[44:47]
	v_mfma_f32_16x16x32_f16 v[108:111], v[20:23], v[52:55], 0
	v_mfma_f32_16x16x32_f16 v[48:51], v[24:27], v[56:59], v[108:111]
	v_mfma_f32_16x16x32_f16 v[52:55], v[28:31], v[52:55], 0
	v_mfma_f32_16x16x32_f16 v[52:55], v[32:35], v[56:59], v[52:55]
	v_mfma_f32_16x16x32_f16 v[112:115], v[20:23], v[60:63], 0
	v_mfma_f32_16x16x32_f16 v[56:59], v[24:27], v[64:67], v[112:115]
	s_setprio 2
	s_barrier
	v_mfma_f32_16x16x32_f16 v[60:63], v[28:31], v[60:63], 0
	v_mfma_f32_16x16x32_f16 v[60:63], v[32:35], v[64:67], v[60:63]
	s_setprio 0
	v_lshl_add_u64 v[138:139], s[8:9], 0, v[2:3]
	s_add_i32 s68, s68, s53
	v_mov_b32_e32 v135, v3
	v_lshl_add_u64 v[144:145], v[138:139], 0, s[74:75]
	s_mov_b32 m0, s68
	v_lshl_add_u64 v[192:193], s[8:9], 0, v[134:135]
	ds_read_b128 v[64:67], v231 offset:16384
	ds_read_b128 v[96:99], v231 offset:17408
	ds_read_b128 v[104:107], v231 offset:18432
	ds_read_b128 v[108:111], v231 offset:19456
	ds_read_b128 v[112:115], v231 offset:20480
	ds_read_b128 v[120:123], v231 offset:21504
	ds_read_b128 v[124:127], v231 offset:22528
	ds_read_b128 v[128:131], v231 offset:23552
	global_load_lds_dwordx4 v[144:145], off
	v_lshl_add_u64 v[144:145], v[192:193], 0, s[74:75]
	s_add_i32 m0, s68, 0x2000
	s_add_i32 s68, s69, s53
	global_load_lds_dwordx4 v[144:145], off
	s_mov_b32 m0, s68
	v_mov_b32_e32 v137, v3
	global_load_lds_dwordx4 v2, s[40:41]
	s_add_i32 m0, s68, 0x2000
	v_lshl_add_u64 v[248:249], s[6:7], 0, v[136:137]
	v_mov_b32_e32 v133, v3
	global_load_lds_dwordx4 v134, s[40:41]
	v_lshl_add_u64 v[144:145], v[248:249], 0, s[74:75]
	s_mov_b32 m0, s54
	v_lshl_add_u64 v[250:251], s[6:7], 0, v[132:133]
	global_load_lds_dwordx4 v[144:145], off
	v_lshl_add_u64 v[144:145], v[250:251], 0, s[74:75]
	s_mov_b32 m0, s55
	s_nop 0
	global_load_lds_dwordx4 v[144:145], off
	s_waitcnt vmcnt(8)
	s_waitcnt lgkmcnt(0)
	s_barrier
	s_setprio 1
	s_waitcnt lgkmcnt(0)
	v_mfma_f32_16x16x32_f16 v[144:147], v[4:7], v[64:67], 0
	v_mfma_f32_16x16x32_f16 v[148:151], v[12:15], v[64:67], 0
	v_mfma_f32_16x16x32_f16 v[152:155], v[4:7], v[104:107], 0
	v_mfma_f32_16x16x32_f16 v[156:159], v[12:15], v[104:107], 0
	v_mfma_f32_16x16x32_f16 v[160:163], v[4:7], v[112:115], 0
	v_mfma_f32_16x16x32_f16 v[164:167], v[12:15], v[112:115], 0
	v_mfma_f32_16x16x32_f16 v[4:7], v[4:7], v[124:127], 0
	v_mfma_f32_16x16x32_f16 v[12:15], v[12:15], v[124:127], 0
	v_mfma_f32_16x16x32_f16 v[144:147], v[8:11], v[96:99], v[144:147]
	v_mfma_f32_16x16x32_f16 v[152:155], v[8:11], v[108:111], v[152:155]
	v_mfma_f32_16x16x32_f16 v[160:163], v[8:11], v[120:123], v[160:163]
	v_mfma_f32_16x16x32_f16 v[4:7], v[8:11], v[128:131], v[4:7]
	v_mfma_f32_16x16x32_f16 v[8:11], v[16:19], v[128:131], v[12:15]
	v_mfma_f32_16x16x32_f16 v[148:151], v[16:19], v[96:99], v[148:151]
	v_mfma_f32_16x16x32_f16 v[156:159], v[16:19], v[108:111], v[156:159]
	v_mfma_f32_16x16x32_f16 v[164:167], v[16:19], v[120:123], v[164:167]
	s_setprio 0
	s_setprio 1
	v_mfma_f32_16x16x32_f16 v[12:15], v[20:23], v[64:67], 0
	v_mfma_f32_16x16x32_f16 v[12:15], v[24:27], v[96:99], v[12:15]
	v_mfma_f32_16x16x32_f16 v[16:19], v[28:31], v[64:67], 0
	v_mfma_f32_16x16x32_f16 v[172:175], v[32:35], v[96:99], v[16:19]
	v_mfma_f32_16x16x32_f16 v[64:67], v[20:23], v[104:107], 0
	v_mfma_f32_16x16x32_f16 v[176:179], v[24:27], v[108:111], v[64:67]
	v_mfma_f32_16x16x32_f16 v[104:107], v[28:31], v[104:107], 0
	v_mfma_f32_16x16x32_f16 v[180:183], v[32:35], v[108:111], v[104:107]
	v_mfma_f32_16x16x32_f16 v[168:171], v[20:23], v[112:115], 0
	v_mfma_f32_16x16x32_f16 v[168:171], v[24:27], v[120:123], v[168:171]
	v_mfma_f32_16x16x32_f16 v[112:115], v[28:31], v[112:115], 0
	v_mfma_f32_16x16x32_f16 v[184:187], v[32:35], v[120:123], v[112:115]
	v_mfma_f32_16x16x32_f16 v[20:23], v[20:23], v[124:127], 0
	v_mfma_f32_16x16x32_f16 v[188:191], v[24:27], v[128:131], v[20:23]
	s_setprio 2
	s_barrier
	v_mfma_f32_16x16x32_f16 v[28:31], v[28:31], v[124:127], 0
	v_mfma_f32_16x16x32_f16 v[196:199], v[32:35], v[128:131], v[28:31]
	s_setprio 0
	s_add_i32 s68, 0, 0x18000
	v_add_u32_e32 v24, s68, v143
	s_add_i32 s69, 0, 0x1c000
	ds_read_b128 v[16:19], v24
	ds_read_b128 v[20:23], v24 offset:1024
	s_nop 0
	ds_read_b128 v[28:31], v24 offset:2048
	ds_read_b128 v[200:203], v24 offset:3072
	v_add_u32_e32 v24, s69, v143
	ds_read_b128 v[204:207], v24
	ds_read_b128 v[208:211], v24 offset:1024
	ds_read_b128 v[212:215], v24 offset:2048
	ds_read_b128 v[216:219], v24 offset:3072
	s_mov_b32 m0, s56
	ds_read_b128 v[24:27], v231 offset:32768
	ds_read_b128 v[32:35], v231 offset:33792
	ds_read_b128 v[64:67], v231 offset:34816
	ds_read_b128 v[220:223], v231 offset:35840
	ds_read_b128 v[224:227], v231 offset:36864
	ds_read_b128 v[232:235], v231 offset:37888
	ds_read_b128 v[236:239], v231 offset:38912
	ds_read_b128 v[240:243], v231 offset:39936
	global_load_lds_dwordx4 v136, s[42:43]
	s_mov_b32 m0, s57
	s_nop 0
	global_load_lds_dwordx4 v132, s[42:43]
	s_waitcnt vmcnt(8)
	s_waitcnt lgkmcnt(0)
	s_barrier
	s_setprio 1
	s_waitcnt lgkmcnt(0)
	v_mfma_f32_16x16x32_f16 v[68:71], v[16:19], v[24:27], v[68:71]
	v_mfma_f32_16x16x32_f16 v[128:131], v[20:23], v[32:35], v[68:71]
	v_mfma_f32_16x16x32_f16 v[68:71], v[28:31], v[24:27], v[72:75]
	v_mfma_f32_16x16x32_f16 v[120:123], v[200:203], v[32:35], v[68:71]
	v_mfma_f32_16x16x32_f16 v[68:71], v[16:19], v[64:67], v[76:79]
	v_mfma_f32_16x16x32_f16 v[112:115], v[20:23], v[220:223], v[68:71]
	v_mfma_f32_16x16x32_f16 v[68:71], v[28:31], v[64:67], v[80:83]
	v_mfma_f32_16x16x32_f16 v[104:107], v[200:203], v[220:223], v[68:71]
	v_mfma_f32_16x16x32_f16 v[68:71], v[16:19], v[224:227], v[84:87]
	v_mfma_f32_16x16x32_f16 v[96:99], v[20:23], v[232:235], v[68:71]
	v_mfma_f32_16x16x32_f16 v[68:71], v[28:31], v[224:227], v[88:91]
	v_mfma_f32_16x16x32_f16 v[88:91], v[200:203], v[232:235], v[68:71]
	v_mfma_f32_16x16x32_f16 v[68:71], v[16:19], v[236:239], v[92:95]
	v_mfma_f32_16x16x32_f16 v[80:83], v[20:23], v[240:243], v[68:71]
	v_mfma_f32_16x16x32_f16 v[68:71], v[28:31], v[236:239], v[100:103]
	v_mfma_f32_16x16x32_f16 v[72:75], v[200:203], v[240:243], v[68:71]
	s_setprio 0
	s_setprio 1
	v_mfma_f32_16x16x32_f16 v[68:71], v[204:207], v[24:27], v[116:119]
	v_mfma_f32_16x16x32_f16 v[24:27], v[212:215], v[24:27], v[36:39]
	v_mfma_f32_16x16x32_f16 v[116:119], v[216:219], v[32:35], v[24:27]
	v_mfma_f32_16x16x32_f16 v[24:27], v[204:207], v[64:67], v[40:43]
	v_mfma_f32_16x16x32_f16 v[108:111], v[208:211], v[220:223], v[24:27]
	v_mfma_f32_16x16x32_f16 v[24:27], v[212:215], v[64:67], v[44:47]
	v_mfma_f32_16x16x32_f16 v[100:103], v[216:219], v[220:223], v[24:27]
	v_mfma_f32_16x16x32_f16 v[24:27], v[204:207], v[224:227], v[48:51]
	v_mfma_f32_16x16x32_f16 v[92:95], v[208:211], v[232:235], v[24:27]
	v_mfma_f32_16x16x32_f16 v[24:27], v[212:215], v[224:227], v[52:55]
	v_mfma_f32_16x16x32_f16 v[84:87], v[216:219], v[232:235], v[24:27]
	v_mfma_f32_16x16x32_f16 v[24:27], v[204:207], v[236:239], v[56:59]
	v_mfma_f32_16x16x32_f16 v[76:79], v[208:211], v[240:243], v[24:27]
	v_mfma_f32_16x16x32_f16 v[24:27], v[212:215], v[236:239], v[60:63]
	s_setprio 2
	s_barrier
	v_mfma_f32_16x16x32_f16 v[124:127], v[208:211], v[32:35], v[68:71]
	v_mfma_f32_16x16x32_f16 v[68:71], v[216:219], v[240:243], v[24:27]
	s_setprio 0
	s_add_i32 s68, s68, s53
	s_nop 2
	v_lshl_add_u64 v[24:25], v[138:139], 0, s[24:25]
	s_mov_b32 m0, s68
	ds_read_b128 v[36:39], v231 offset:49152
	ds_read_b128 v[44:47], v231 offset:50176
	ds_read_b128 v[220:223], v231 offset:51200
	ds_read_b128 v[224:227], v231 offset:52224
	ds_read_b128 v[232:235], v231 offset:53248
	ds_read_b128 v[236:239], v231 offset:54272
	ds_read_b128 v[240:243], v231 offset:55296
	ds_read_b128 v[244:247], v231 offset:56320
	global_load_lds_dwordx4 v[24:25], off
	v_lshl_add_u64 v[24:25], v[192:193], 0, s[24:25]
	s_add_i32 m0, s68, 0x2000
	s_add_i32 s68, s69, s53
	global_load_lds_dwordx4 v[24:25], off
	s_mov_b32 m0, s68
	v_lshl_add_u64 v[24:25], v[248:249], 0, s[24:25]
	global_load_lds_dwordx4 v2, s[44:45]
	s_add_i32 m0, s68, 0x2000
	s_nop 0
	global_load_lds_dwordx4 v134, s[44:45]
	s_mov_b32 m0, s59
	s_nop 0
	global_load_lds_dwordx4 v[24:25], off
	v_lshl_add_u64 v[24:25], v[250:251], 0, s[24:25]
	s_mov_b32 m0, s60
	s_nop 0
	global_load_lds_dwordx4 v[24:25], off
	s_waitcnt vmcnt(8)
	s_waitcnt lgkmcnt(0)
	s_barrier
	s_setprio 1
	s_waitcnt lgkmcnt(0)
	v_mfma_f32_16x16x32_f16 v[24:27], v[16:19], v[36:39], v[144:147]
	v_mfma_f32_16x16x32_f16 v[64:67], v[20:23], v[44:47], v[24:27]
	v_mfma_f32_16x16x32_f16 v[24:27], v[28:31], v[36:39], v[148:151]
	v_mfma_f32_16x16x32_f16 v[56:59], v[200:203], v[44:47], v[24:27]
	v_mfma_f32_16x16x32_f16 v[24:27], v[16:19], v[220:223], v[152:155]
	v_mfma_f32_16x16x32_f16 v[48:51], v[20:23], v[224:227], v[24:27]
	v_mfma_f32_16x16x32_f16 v[24:27], v[28:31], v[220:223], v[156:159]
	v_mfma_f32_16x16x32_f16 v[40:43], v[200:203], v[224:227], v[24:27]
	v_mfma_f32_16x16x32_f16 v[24:27], v[16:19], v[232:235], v[160:163]
	v_mfma_f32_16x16x32_f16 v[4:7], v[16:19], v[240:243], v[4:7]
	v_mfma_f32_16x16x32_f16 v[32:35], v[20:23], v[236:239], v[24:27]
	v_mfma_f32_16x16x32_f16 v[24:27], v[28:31], v[232:235], v[164:167]
	v_mfma_f32_16x16x32_f16 v[16:19], v[20:23], v[244:247], v[4:7]
	v_mfma_f32_16x16x32_f16 v[4:7], v[28:31], v[240:243], v[8:11]
	v_mfma_f32_16x16x32_f16 v[24:27], v[200:203], v[236:239], v[24:27]
	v_mfma_f32_16x16x32_f16 v[8:11], v[200:203], v[244:247], v[4:7]
	s_setprio 0
	s_setprio 1
	v_mfma_f32_16x16x32_f16 v[4:7], v[204:207], v[36:39], v[12:15]
	v_mfma_f32_16x16x32_f16 v[60:63], v[208:211], v[44:47], v[4:7]
	v_mfma_f32_16x16x32_f16 v[4:7], v[212:215], v[36:39], v[172:175]
	v_mfma_f32_16x16x32_f16 v[52:55], v[216:219], v[44:47], v[4:7]
	v_mfma_f32_16x16x32_f16 v[4:7], v[204:207], v[220:223], v[176:179]
	v_mfma_f32_16x16x32_f16 v[44:47], v[208:211], v[224:227], v[4:7]
	v_mfma_f32_16x16x32_f16 v[4:7], v[212:215], v[220:223], v[180:183]
	v_mfma_f32_16x16x32_f16 v[36:39], v[216:219], v[224:227], v[4:7]
	v_mfma_f32_16x16x32_f16 v[4:7], v[204:207], v[232:235], v[168:171]
	v_mfma_f32_16x16x32_f16 v[28:31], v[208:211], v[236:239], v[4:7]
	v_mfma_f32_16x16x32_f16 v[4:7], v[212:215], v[232:235], v[184:187]
	v_mfma_f32_16x16x32_f16 v[20:23], v[216:219], v[236:239], v[4:7]
	v_mfma_f32_16x16x32_f16 v[4:7], v[204:207], v[240:243], v[188:191]
	v_mfma_f32_16x16x32_f16 v[12:15], v[208:211], v[244:247], v[4:7]
	s_setprio 2
	s_barrier
	v_mfma_f32_16x16x32_f16 v[4:7], v[212:215], v[240:243], v[196:199]
	v_mfma_f32_16x16x32_f16 v[4:7], v[216:219], v[244:247], v[4:7]
	s_setprio 0
	s_add_i32 s67, s67, 2
	s_cmp_ge_i32 s67, s11
	s_cbranch_scc0 .LBB0_2159

.LBB0_2269:
	s_add_i32 s51, 0, 0x10000
	s_add_i32 s71, 0, 0x14000
	v_add_u32_e32 v16, s51, v232
	v_add_u32_e32 v32, s71, v232
	ds_read_b128 v[4:7], v16
	ds_read_b128 v[8:11], v16 offset:1024
	ds_read_b128 v[12:15], v16 offset:2048
	ds_read_b128 v[16:19], v16 offset:3072
	ds_read_b128 v[20:23], v32
	ds_read_b128 v[24:27], v32 offset:1024
	ds_read_b128 v[28:31], v32 offset:2048
	ds_read_b128 v[32:35], v32 offset:3072
	v_add_u32_e32 v233, 0, v231
	ds_read_b128 v[36:39], v233
	ds_read_b128 v[40:43], v233 offset:1024
	ds_read_b128 v[44:47], v233 offset:2048
	ds_read_b128 v[48:51], v233 offset:3072
	ds_read_b128 v[52:55], v233 offset:4096
	ds_read_b128 v[56:59], v233 offset:5120
	ds_read_b128 v[60:63], v233 offset:6144
	ds_read_b128 v[64:67], v233 offset:7168
	s_waitcnt vmcnt(8)
	s_waitcnt lgkmcnt(0)
	s_barrier
	s_setprio 1
	s_waitcnt lgkmcnt(0)
	v_mfma_f32_16x16x32_bf16 v[68:71], v[4:7], v[36:39], 0
	v_mfma_f32_16x16x32_bf16 v[68:71], v[8:11], v[40:43], v[68:71]
	v_mfma_f32_16x16x32_bf16 v[72:75], v[12:15], v[36:39], 0
	v_mfma_f32_16x16x32_bf16 v[72:75], v[16:19], v[40:43], v[72:75]
	v_mfma_f32_16x16x32_bf16 v[80:83], v[12:15], v[44:47], 0
	v_mfma_f32_16x16x32_bf16 v[80:83], v[16:19], v[48:51], v[80:83]
	v_mfma_f32_16x16x32_bf16 v[76:79], v[4:7], v[44:47], 0
	v_mfma_f32_16x16x32_bf16 v[76:79], v[8:11], v[48:51], v[76:79]
	v_mfma_f32_16x16x32_bf16 v[84:87], v[4:7], v[52:55], 0
	v_mfma_f32_16x16x32_bf16 v[84:87], v[8:11], v[56:59], v[84:87]
	v_mfma_f32_16x16x32_bf16 v[88:91], v[12:15], v[52:55], 0
	v_mfma_f32_16x16x32_bf16 v[88:91], v[16:19], v[56:59], v[88:91]
	v_mfma_f32_16x16x32_bf16 v[96:99], v[12:15], v[60:63], 0
	v_mfma_f32_16x16x32_bf16 v[96:99], v[16:19], v[64:67], v[96:99]
	v_mfma_f32_16x16x32_bf16 v[92:95], v[4:7], v[60:63], 0
	v_mfma_f32_16x16x32_bf16 v[92:95], v[8:11], v[64:67], v[92:95]
	s_setprio 0
	s_setprio 1
	v_mfma_f32_16x16x32_bf16 v[100:103], v[20:23], v[36:39], 0
	v_mfma_f32_16x16x32_bf16 v[100:103], v[24:27], v[40:43], v[100:103]
	v_mfma_f32_16x16x32_bf16 v[36:39], v[28:31], v[36:39], 0
	v_mfma_f32_16x16x32_bf16 v[40:43], v[32:35], v[40:43], v[36:39]
	v_mfma_f32_16x16x32_bf16 v[104:107], v[20:23], v[44:47], 0
	v_mfma_f32_16x16x32_bf16 v[104:107], v[24:27], v[48:51], v[104:107]
	v_mfma_f32_16x16x32_bf16 v[44:47], v[28:31], v[44:47], 0
	v_mfma_f32_16x16x32_bf16 v[48:51], v[32:35], v[48:51], v[44:47]
	v_mfma_f32_16x16x32_bf16 v[108:111], v[20:23], v[52:55], 0
	v_mfma_f32_16x16x32_bf16 v[108:111], v[24:27], v[56:59], v[108:111]
	v_mfma_f32_16x16x32_bf16 v[52:55], v[28:31], v[52:55], 0
	v_mfma_f32_16x16x32_bf16 v[56:59], v[32:35], v[56:59], v[52:55]
	v_mfma_f32_16x16x32_bf16 v[112:115], v[20:23], v[60:63], 0
	v_mfma_f32_16x16x32_bf16 v[112:115], v[24:27], v[64:67], v[112:115]
	s_setprio 2
	s_barrier
	v_mfma_f32_16x16x32_bf16 v[60:63], v[28:31], v[60:63], 0
	v_mfma_f32_16x16x32_bf16 v[64:67], v[32:35], v[64:67], v[60:63]
	s_setprio 0
	v_lshl_add_u64 v[186:187], s[12:13], 0, v[2:3]
	s_add_i32 s51, s51, s38
	v_mov_b32_e32 v191, v3
	v_lshl_add_u64 v[134:135], v[186:187], 0, s[74:75]
	s_mov_b32 m0, s51
	v_lshl_add_u64 v[246:247], s[12:13], 0, v[190:191]
	ds_read_b128 v[36:39], v233 offset:16384
	ds_read_b128 v[44:47], v233 offset:17408
	ds_read_b128 v[52:55], v233 offset:18432
	ds_read_b128 v[60:63], v233 offset:19456
	ds_read_b128 v[116:119], v233 offset:20480
	ds_read_b128 v[120:123], v233 offset:21504
	ds_read_b128 v[124:127], v233 offset:22528
	ds_read_b128 v[128:131], v233 offset:23552
	global_load_lds_dwordx4 v[134:135], off
	v_lshl_add_u64 v[134:135], v[246:247], 0, s[74:75]
	s_add_i32 m0, s51, 0x2000
	s_add_i32 s51, s71, s38
	global_load_lds_dwordx4 v[134:135], off
	s_mov_b32 m0, s51
	v_mov_b32_e32 v133, v3
	global_load_lds_dwordx4 v2, s[16:17]
	s_add_i32 m0, s51, 0x2000
	v_lshl_add_u64 v[248:249], s[14:15], 0, v[132:133]
	v_mov_b32_e32 v189, v3
	global_load_lds_dwordx4 v190, s[16:17]
	v_lshl_add_u64 v[134:135], v[248:249], 0, s[74:75]
	s_mov_b32 m0, s56
	v_lshl_add_u64 v[250:251], s[14:15], 0, v[188:189]
	global_load_lds_dwordx4 v[134:135], off
	v_lshl_add_u64 v[134:135], v[250:251], 0, s[74:75]
	s_mov_b32 m0, s57
	s_nop 0
	global_load_lds_dwordx4 v[134:135], off
	s_waitcnt vmcnt(8)
	s_waitcnt lgkmcnt(0)
	s_barrier
	s_setprio 1
	s_waitcnt lgkmcnt(0)
	v_mfma_f32_16x16x32_bf16 v[134:137], v[4:7], v[36:39], 0
	v_mfma_f32_16x16x32_bf16 v[134:137], v[8:11], v[44:47], v[134:137]
	v_mfma_f32_16x16x32_bf16 v[138:141], v[12:15], v[36:39], 0
	v_mfma_f32_16x16x32_bf16 v[138:141], v[16:19], v[44:47], v[138:141]
	v_mfma_f32_16x16x32_bf16 v[146:149], v[12:15], v[52:55], 0
	v_mfma_f32_16x16x32_bf16 v[146:149], v[16:19], v[60:63], v[146:149]
	v_mfma_f32_16x16x32_bf16 v[142:145], v[4:7], v[52:55], 0
	v_mfma_f32_16x16x32_bf16 v[142:145], v[8:11], v[60:63], v[142:145]
	v_mfma_f32_16x16x32_bf16 v[150:153], v[4:7], v[116:119], 0
	v_mfma_f32_16x16x32_bf16 v[150:153], v[8:11], v[120:123], v[150:153]
	v_mfma_f32_16x16x32_bf16 v[154:157], v[12:15], v[116:119], 0
	v_mfma_f32_16x16x32_bf16 v[154:157], v[16:19], v[120:123], v[154:157]
	v_mfma_f32_16x16x32_bf16 v[12:15], v[12:15], v[124:127], 0
	v_mfma_f32_16x16x32_bf16 v[162:165], v[16:19], v[128:131], v[12:15]
	v_mfma_f32_16x16x32_bf16 v[4:7], v[4:7], v[124:127], 0
	v_mfma_f32_16x16x32_bf16 v[158:161], v[8:11], v[128:131], v[4:7]
	s_setprio 0
	s_setprio 1
	v_mfma_f32_16x16x32_bf16 v[4:7], v[20:23], v[36:39], 0
	v_mfma_f32_16x16x32_bf16 v[8:11], v[28:31], v[36:39], 0
	v_mfma_f32_16x16x32_bf16 v[12:15], v[20:23], v[52:55], 0
	v_mfma_f32_16x16x32_bf16 v[16:19], v[28:31], v[52:55], 0
	v_mfma_f32_16x16x32_bf16 v[36:39], v[20:23], v[116:119], 0
	v_mfma_f32_16x16x32_bf16 v[52:55], v[28:31], v[116:119], 0
	v_mfma_f32_16x16x32_bf16 v[20:23], v[20:23], v[124:127], 0
	v_mfma_f32_16x16x32_bf16 v[28:31], v[28:31], v[124:127], 0
	v_mfma_f32_16x16x32_bf16 v[116:119], v[24:27], v[44:47], v[4:7]
	v_mfma_f32_16x16x32_bf16 v[124:127], v[32:35], v[44:47], v[8:11]
	v_mfma_f32_16x16x32_bf16 v[174:177], v[24:27], v[120:123], v[36:39]
	v_mfma_f32_16x16x32_bf16 v[120:123], v[32:35], v[120:123], v[52:55]
	v_mfma_f32_16x16x32_bf16 v[178:181], v[24:27], v[128:131], v[20:23]
	v_mfma_f32_16x16x32_bf16 v[128:131], v[32:35], v[128:131], v[28:31]
	s_setprio 2
	s_barrier
	v_mfma_f32_16x16x32_bf16 v[166:169], v[24:27], v[60:63], v[12:15]
	v_mfma_f32_16x16x32_bf16 v[170:173], v[32:35], v[60:63], v[16:19]
	s_setprio 0
	s_add_i32 s51, 0, 0x18000
	v_add_u32_e32 v4, s51, v232
	s_add_i32 s71, 0, 0x1c000
	ds_read_b128 v[182:185], v4
	ds_read_b128 v[192:195], v4 offset:1024
	ds_read_b128 v[196:199], v4 offset:2048
	ds_read_b128 v[200:203], v4 offset:3072
	v_add_u32_e32 v4, s71, v232
	ds_read_b128 v[204:207], v4
	ds_read_b128 v[208:211], v4 offset:1024
	ds_read_b128 v[212:215], v4 offset:2048
	ds_read_b128 v[216:219], v4 offset:3072
	s_mov_b32 m0, s58
	ds_read_b128 v[44:47], v233 offset:32768
	ds_read_b128 v[52:55], v233 offset:33792
	ds_read_b128 v[60:63], v233 offset:34816
	ds_read_b128 v[220:223], v233 offset:35840
	ds_read_b128 v[224:227], v233 offset:36864
	ds_read_b128 v[234:237], v233 offset:37888
	ds_read_b128 v[238:241], v233 offset:38912
	ds_read_b128 v[242:245], v233 offset:39936
	global_load_lds_dwordx4 v132, s[26:27]
	s_mov_b32 m0, s59
	s_nop 0
	global_load_lds_dwordx4 v188, s[26:27]
	s_waitcnt vmcnt(8)
	s_waitcnt lgkmcnt(0)
	s_barrier
	s_setprio 1
	s_waitcnt lgkmcnt(0)
	v_mfma_f32_16x16x32_bf16 v[4:7], v[182:185], v[44:47], v[68:71]
	v_mfma_f32_16x16x32_bf16 v[4:7], v[192:195], v[52:55], v[4:7]
	v_mfma_f32_16x16x32_bf16 v[8:11], v[196:199], v[44:47], v[72:75]
	v_mfma_f32_16x16x32_bf16 v[8:11], v[200:203], v[52:55], v[8:11]
	v_mfma_f32_16x16x32_bf16 v[16:19], v[196:199], v[60:63], v[80:83]
	v_mfma_f32_16x16x32_bf16 v[16:19], v[200:203], v[220:223], v[16:19]
	v_mfma_f32_16x16x32_bf16 v[12:15], v[182:185], v[60:63], v[76:79]
	v_mfma_f32_16x16x32_bf16 v[12:15], v[192:195], v[220:223], v[12:15]
	v_mfma_f32_16x16x32_bf16 v[20:23], v[182:185], v[224:227], v[84:87]
	v_mfma_f32_16x16x32_bf16 v[20:23], v[192:195], v[234:237], v[20:23]
	v_mfma_f32_16x16x32_bf16 v[24:27], v[196:199], v[224:227], v[88:91]
	v_mfma_f32_16x16x32_bf16 v[24:27], v[200:203], v[234:237], v[24:27]
	v_mfma_f32_16x16x32_bf16 v[32:35], v[196:199], v[238:241], v[96:99]
	v_mfma_f32_16x16x32_bf16 v[32:35], v[200:203], v[242:245], v[32:35]
	v_mfma_f32_16x16x32_bf16 v[28:31], v[182:185], v[238:241], v[92:95]
	v_mfma_f32_16x16x32_bf16 v[28:31], v[192:195], v[242:245], v[28:31]
	s_setprio 0
	s_setprio 1
	v_mfma_f32_16x16x32_bf16 v[36:39], v[204:207], v[44:47], v[100:103]
	v_mfma_f32_16x16x32_bf16 v[40:43], v[212:215], v[44:47], v[40:43]
	v_mfma_f32_16x16x32_bf16 v[36:39], v[208:211], v[52:55], v[36:39]
	v_mfma_f32_16x16x32_bf16 v[40:43], v[216:219], v[52:55], v[40:43]
	v_mfma_f32_16x16x32_bf16 v[44:47], v[204:207], v[60:63], v[104:107]
	v_mfma_f32_16x16x32_bf16 v[48:51], v[212:215], v[60:63], v[48:51]
	v_mfma_f32_16x16x32_bf16 v[52:55], v[204:207], v[224:227], v[108:111]
	v_mfma_f32_16x16x32_bf16 v[56:59], v[212:215], v[224:227], v[56:59]
	v_mfma_f32_16x16x32_bf16 v[60:63], v[204:207], v[238:241], v[112:115]
	v_mfma_f32_16x16x32_bf16 v[64:67], v[212:215], v[238:241], v[64:67]
	v_mfma_f32_16x16x32_bf16 v[44:47], v[208:211], v[220:223], v[44:47]
	v_mfma_f32_16x16x32_bf16 v[48:51], v[216:219], v[220:223], v[48:51]
	v_mfma_f32_16x16x32_bf16 v[52:55], v[208:211], v[234:237], v[52:55]
	v_mfma_f32_16x16x32_bf16 v[56:59], v[216:219], v[234:237], v[56:59]
	s_setprio 2
	s_barrier
	v_mfma_f32_16x16x32_bf16 v[60:63], v[208:211], v[242:245], v[60:63]
	v_mfma_f32_16x16x32_bf16 v[64:67], v[216:219], v[242:245], v[64:67]
	s_setprio 0
	s_add_i32 s51, s51, s38
	v_lshl_add_u64 v[68:69], v[186:187], 0, s[24:25]
	s_mov_b32 m0, s51
	ds_read_b128 v[104:107], v233 offset:49152
	ds_read_b128 v[108:111], v233 offset:50176
	ds_read_b128 v[112:115], v233 offset:51200
	ds_read_b128 v[220:223], v233 offset:52224
	ds_read_b128 v[224:227], v233 offset:53248
	ds_read_b128 v[234:237], v233 offset:54272
	ds_read_b128 v[238:241], v233 offset:55296
	ds_read_b128 v[242:245], v233 offset:56320
	global_load_lds_dwordx4 v[68:69], off
	v_lshl_add_u64 v[68:69], v[246:247], 0, s[24:25]
	s_add_i32 m0, s51, 0x2000
	s_add_i32 s51, s71, s38
	global_load_lds_dwordx4 v[68:69], off
	s_mov_b32 m0, s51
	v_lshl_add_u64 v[68:69], v[248:249], 0, s[24:25]
	global_load_lds_dwordx4 v2, s[28:29]
	s_add_i32 m0, s51, 0x2000
	s_nop 0
	global_load_lds_dwordx4 v190, s[28:29]
	s_mov_b32 m0, s63
	s_nop 0
	global_load_lds_dwordx4 v[68:69], off
	v_lshl_add_u64 v[68:69], v[250:251], 0, s[24:25]
	s_mov_b32 m0, s64
	s_nop 0
	global_load_lds_dwordx4 v[68:69], off
	s_waitcnt vmcnt(8)
	s_waitcnt lgkmcnt(0)
	s_barrier
	s_setprio 1
	s_waitcnt lgkmcnt(0)
	v_mfma_f32_16x16x32_bf16 v[68:71], v[182:185], v[104:107], v[134:137]
	v_mfma_f32_16x16x32_bf16 v[68:71], v[192:195], v[108:111], v[68:71]
	v_mfma_f32_16x16x32_bf16 v[72:75], v[196:199], v[104:107], v[138:141]
	v_mfma_f32_16x16x32_bf16 v[72:75], v[200:203], v[108:111], v[72:75]
	v_mfma_f32_16x16x32_bf16 v[80:83], v[196:199], v[112:115], v[146:149]
	v_mfma_f32_16x16x32_bf16 v[80:83], v[200:203], v[220:223], v[80:83]
	v_mfma_f32_16x16x32_bf16 v[76:79], v[182:185], v[112:115], v[142:145]
	v_mfma_f32_16x16x32_bf16 v[76:79], v[192:195], v[220:223], v[76:79]
	v_mfma_f32_16x16x32_bf16 v[84:87], v[182:185], v[224:227], v[150:153]
	v_mfma_f32_16x16x32_bf16 v[84:87], v[192:195], v[234:237], v[84:87]
	v_mfma_f32_16x16x32_bf16 v[88:91], v[196:199], v[224:227], v[154:157]
	v_mfma_f32_16x16x32_bf16 v[88:91], v[200:203], v[234:237], v[88:91]
	v_mfma_f32_16x16x32_bf16 v[96:99], v[196:199], v[238:241], v[162:165]
	v_mfma_f32_16x16x32_bf16 v[96:99], v[200:203], v[242:245], v[96:99]
	v_mfma_f32_16x16x32_bf16 v[92:95], v[182:185], v[238:241], v[158:161]
	v_mfma_f32_16x16x32_bf16 v[92:95], v[192:195], v[242:245], v[92:95]
	s_setprio 0
	s_setprio 1
	v_mfma_f32_16x16x32_bf16 v[100:103], v[204:207], v[104:107], v[116:119]
	v_mfma_f32_16x16x32_bf16 v[104:107], v[212:215], v[104:107], v[124:127]
	v_mfma_f32_16x16x32_bf16 v[100:103], v[208:211], v[108:111], v[100:103]
	v_mfma_f32_16x16x32_bf16 v[104:107], v[216:219], v[108:111], v[104:107]
	v_mfma_f32_16x16x32_bf16 v[108:111], v[204:207], v[112:115], v[166:169]
	v_mfma_f32_16x16x32_bf16 v[112:115], v[212:215], v[112:115], v[170:173]
	v_mfma_f32_16x16x32_bf16 v[116:119], v[204:207], v[224:227], v[174:177]
	v_mfma_f32_16x16x32_bf16 v[120:123], v[212:215], v[224:227], v[120:123]
	v_mfma_f32_16x16x32_bf16 v[124:127], v[204:207], v[238:241], v[178:181]
	v_mfma_f32_16x16x32_bf16 v[128:131], v[212:215], v[238:241], v[128:131]
	v_mfma_f32_16x16x32_bf16 v[108:111], v[208:211], v[220:223], v[108:111]
	v_mfma_f32_16x16x32_bf16 v[112:115], v[216:219], v[220:223], v[112:115]
	v_mfma_f32_16x16x32_bf16 v[116:119], v[208:211], v[234:237], v[116:119]
	v_mfma_f32_16x16x32_bf16 v[120:123], v[216:219], v[234:237], v[120:123]
	s_setprio 2
	s_barrier
	v_mfma_f32_16x16x32_bf16 v[124:127], v[208:211], v[242:245], v[124:127]
	v_mfma_f32_16x16x32_bf16 v[128:131], v[216:219], v[242:245], v[128:131]
	s_setprio 0
	s_add_i32 s41, s41, 2
	s_cmp_ge_i32 s41, s40
	s_cbranch_scc0 .LBB0_2269
	v_mov_b32_e32 v192, v2
	s_branch .LBB0_2272
